# lever 4: per-segment s_setprio flips in all GEMM K-loops deleted, one static s_setprio 1 for waves 4-7 per GEMM phase (reset to 0 at phase end)
# speedup vs baseline: 1.0021x; 1.0021x over previous
; #define PG8_STAGE(bufoff, gbase, voff) do { _Pragma("unroll") for (int _i = 0; _i < 2; ++_i) \
;         __builtin_amdgcn_global_load_lds((const unsigned*)((const char*)(gbase) + (voff)[_i]), (LAS unsigned*)(lds + (bufoff) + ldsw + _i * 8192), 16, 0, 0); } while (0)
; #define PG8_BAR __builtin_amdgcn_s_barrier()
; template <class Epi, class Sched>
; __device__ __forceinline__ void gemm_phase(LAS unsigned char* lds, const Gemm g, const Sched& S, const Epi& E, const int tid) {
;     const int wid = __builtin_amdgcn_readfirstlane(tid >> 6), lane = tid & 63, wr = wid >> 2, wc = wid & 3, fr = lane & 15, fq = lane >> 4;
;     const int K = g.K, nt = K / BK;
;     unsigned voffA[2], voffB[2];
; #pragma unroll
;     for (int i = 0; i < 2; ++i) { int R, C; stage_rc(tid * 16 + i * 8192, R, C); const int Rb = Epi::PERM ? ((R & ~31) + perm32(R & 31)) : R;
;         voffA[i] = (unsigned)(R * K + C) * 2u; voffB[i] = (unsigned)(Rb * K + C) * 2u; }
;     const size_t kstep = (size_t)(BK * 2);
;     const size_t hstep = (size_t)HALF * K * 2;
;     const size_t tstep = 2 * hstep;
;     const unsigned ldsw = (unsigned)wid * 1024u;
;     const int aoff = lds_byte(wr * 64 + fr, fq * 8), boff = lds_byte(wc * 32 + fr, fq * 8);
;     ...
;     Unit cur, nxt; int ui = 0;
;     if (!S.next(0, cur)) return;
;     f32x4 acc[2][2][4][2];
; #pragma unroll
;     for (int a = 0; a < 2; ++a)
; #pragma unroll
;         for (int b = 0; b < 2; ++b)
; #pragma unroll
;             for (int m = 0; m < 4; ++m)
; #pragma unroll
;                 for (int n = 0; n < 2; ++n) acc[a][b][m][n] = (f32x4){0.f, 0.f, 0.f, 0.f};
;     bf16x8 At[4][2], B0[2][2], B1[2][2];
;     const char* cA = (const char*)g.A + (size_t)cur.pm * tstep; const char* cB = (const char*)g.Bt + (size_t)cur.pn * tstep;
;     PG8_STAGE(PG8_SB(0, 0), cB, voffB); PG8_STAGE(PG8_SB(0, 1), cB + hstep, voffB); PG8_STAGE(PG8_SA(0, 0), cA, voffA); PG8_STAGE(PG8_SA(0, 1), cA + hstep, voffA);
;     if (wr == 1) PG8_BAR;
.LBB0_155:
	s_cmp_eq_u32 s14, 1
	s_cselect_b64 s[10:11], -1, 0
	s_cmp_lg_u32 s14, 1
	s_cselect_b64 s[0:1], -1, 0
	s_cmp_ge_i32 s72, s28
	v_writelane_b32 v255, s0, 15
	s_cselect_b64 s[48:49], -1, 0
	s_cmp_lt_i32 s72, s29
	v_writelane_b32 v255, s1, 16
	s_cselect_b64 s[0:1], -1, 0
	s_and_b64 s[4:5], s[48:49], s[0:1]
	v_cndmask_b32_e64 v0, 0, 1, s[4:5]
	s_mov_b64 s[0:1], -1
	s_and_b64 vcc, exec, s[10:11]
	v_cmp_ne_u32_e64 s[8:9], 1, v0
	s_cbranch_vccnz .LBB0_249
	s_and_b64 vcc, exec, s[8:9]
	s_cbranch_vccnz .LBB0_177
	v_readlane_b32 s0, v252, 56
	s_waitcnt vmcnt(0)
	v_mov_b32_e32 v132, v223
	v_readlane_b32 s1, v252, 57
	s_andn2_b64 vcc, exec, s[0:1]
	v_readfirstlane_b32 s6, v132
	s_cbranch_vccnz .LBB0_177
	s_cmp_lg_u32 s14, 0
	s_cselect_b64 s[4:5], -1, 0
	v_cndmask_b32_e64 v0, 0, 1, s[4:5]
	v_readlane_b32 s1, v254, 51
	v_readfirstlane_b32 s0, v0
	v_lshlrev_b32_e32 v0, 4, v132
	s_waitcnt lgkmcnt(0)
	v_add_u32_e32 v1, 0x2000, v0
	v_ashrrev_i32_e32 v2, 31, v1
	v_lshrrev_b32_e32 v2, 22, v2
	v_add_u32_e32 v2, v1, v2
	s_waitcnt vmcnt(1)
	v_ashrrev_i32_e32 v4, 10, v2
	v_mul_i32_i24_e32 v2, 0x400, v4
	v_sub_u32_e32 v1, v1, v2
	v_lshrrev_b32_e32 v2, 4, v1
	v_bitop3_b32 v1, v2, v1, 32 bitop3:0x6c
	v_ashrrev_i32_e32 v2, 31, v1
	s_or_b32 s0, s1, s0
	v_lshrrev_b32_e32 v2, 26, v2
	s_mul_i32 s12, s0, 0x580000
	v_add_u32_e32 v2, v1, v2
	v_lshlrev_b32_e32 v3, 3, v4
	s_lshl_b64 s[0:1], s[12:13], 1
	v_readlane_b32 s3, v252, 26
	v_ashrrev_i32_e32 v5, 6, v2
	v_and_b32_e32 v3, -16, v3
	s_add_u32 s12, s3, s0
	v_readlane_b32 s0, v252, 27
	v_add_u32_e32 v3, v5, v3
	s_addc_u32 s73, s0, s1
	v_and_b32_e32 v6, 3, v5
	s_mov_b32 s0, 0x1fffe0
	v_lshrrev_b32_e32 v7, 2, v3
	v_lshlrev_b32_e32 v8, 1, v3
	v_and_b32_e32 v2, 0xc0, v2
	v_and_or_b32 v6, v3, s0, v6
	v_and_b32_e32 v7, 4, v7
	v_and_b32_e32 v8, 24, v8
	v_sub_u32_e32 v1, v1, v2
	v_mov_b32_e32 v11, 1
	v_or3_b32 v7, v6, v7, v8
	v_lshlrev_b32_e32 v6, 5, v4
	v_ashrrev_i16_sdwa v1, v11, sext(v1) dst_sel:DWORD dst_unused:UNUSED_PAD src0_sel:DWORD src1_sel:BYTE_0
	v_and_b32_e32 v8, 32, v6
	v_bfe_i32 v6, v1, 0, 16
	v_add_lshl_u32 v1, v8, v6, 1
	v_lshl_add_u32 v134, v7, 11, v1
	v_lshl_add_u32 v136, v3, 11, v1
	v_bfe_i32 v1, v132, 27, 1
	v_lshrrev_b32_e32 v1, 22, v1
	v_add_u32_e32 v1, v0, v1
	v_and_b32_e32 v1, 0xfffffc00, v1
	v_sub_u32_e32 v0, v0, v1
	v_lshrrev_b32_e32 v1, 4, v0
	v_ashrrev_i32_e32 v133, 31, v132
	v_bitop3_b32 v0, v1, v0, 32 bitop3:0x6c
	v_lshrrev_b32_e32 v2, 26, v133
	v_ashrrev_i32_e32 v1, 31, v0
	v_add_u32_e32 v2, v132, v2
	v_lshrrev_b32_e32 v1, 26, v1
	v_ashrrev_i32_e32 v8, 6, v2
	v_add_u32_e32 v1, v0, v1
	v_lshlrev_b32_e32 v2, 3, v8
	v_ashrrev_i32_e32 v7, 6, v1
	v_and_b32_e32 v2, -16, v2
	v_add_u32_e32 v2, v7, v2
	v_and_b32_e32 v3, 3, v7
	v_and_or_b32 v3, v2, s0, v3
	v_readlane_b32 s0, v252, 61
	v_lshrrev_b32_e32 v9, 2, v2
	v_lshlrev_b32_e32 v10, 1, v2
	v_and_b32_e32 v1, 0xc0, v1
	v_readlane_b32 s1, v252, 62
	s_add_u32 s66, s12, s0
	v_and_b32_e32 v9, 4, v9
	v_and_b32_e32 v10, 24, v10
	v_sub_u32_e32 v0, v0, v1
	s_addc_u32 s67, s73, s1
	s_ashr_i32 s22, s6, 6
	v_or3_b32 v3, v3, v9, v10
	v_lshlrev_b32_e32 v9, 5, v8
	v_ashrrev_i16_sdwa v0, v11, sext(v0) dst_sel:DWORD dst_unused:UNUSED_PAD src0_sel:DWORD src1_sel:BYTE_0
	s_ashr_i32 s7, s6, 8
	s_lshl_b32 s74, s22, 10
	v_and_b32_e32 v10, 32, v9
	v_bfe_i32 v9, v0, 0, 16
	s_add_u32 s0, s66, 0x40000
	v_add_lshl_u32 v0, v10, v9, 1
	s_addc_u32 s1, s67, 0
	s_add_i32 s75, s74, 0
	v_lshl_add_u32 v192, v3, 11, v0
	s_add_i32 m0, s75, 0x10000
	v_lshl_add_u32 v138, v2, 11, v0
	global_load_lds_dwordx4 v192, s[66:67]
	s_add_i32 m0, s75, 0x12000
	s_add_i32 s81, s75, 0x2000
	global_load_lds_dwordx4 v134, s[66:67]
	s_add_i32 m0, s75, 0x14000
	s_add_i32 s82, s75, 0x4000
	global_load_lds_dwordx4 v192, s[0:1]
	s_add_i32 m0, s75, 0x16000
	s_add_i32 s83, s75, 0x6000
	global_load_lds_dwordx4 v134, s[0:1]
	v_readlane_b32 s0, v252, 63
	s_mov_b32 m0, s75
	v_readlane_b32 s1, v253, 0
	v_mov_b32_e32 v135, v193
	s_cmp_eq_u32 s7, 1
	v_lshl_add_u64 v[0:1], s[66:67], 0, v[192:193]
	v_lshl_add_u64 v[2:3], s[66:67], 0, v[134:135]
	s_nop 0
	global_load_lds_dwordx4 v138, s[0:1]
	s_mov_b32 m0, s81
	s_nop 0
	global_load_lds_dwordx4 v136, s[0:1]
	v_readlane_b32 s0, v253, 1
	s_mov_b32 m0, s82
	v_readlane_b32 s1, v253, 2
	s_nop 4
	global_load_lds_dwordx4 v138, s[0:1]
	s_mov_b32 m0, s83
	s_nop 0
	global_load_lds_dwordx4 v136, s[0:1]
	s_cselect_b64 s[0:1], -1, 0
	s_cmp_lg_u32 s7, 1
	s_cbranch_scc1 .LBB0_160
	s_barrier
	s_setprio 1

;     __device__ __forceinline__ Pre prefetch(const Unit& u, int tid) const { return prenorm_load(stats, u.pn * BM, sW + (size_t)(u.pn >> 4) * SW_ROWS + u.pm * BM, tid); }
;     __device__ __forceinline__ Pre prefetch(const Unit& u, int tid) const { return prenorm_load(stats, u.pm * BM, sW + (size_t)(u.pm >> 4) * SW_ROWS + u.pn * BM, tid); }
;     __device__ __forceinline__ Pre prefetch(const Unit& u, int tid) const { return prenorm_load(stats, u.pm * BM, sW + (size_t)(u.pm >> 4) * SW_ROWS + u.pn * BM, tid); }
; #define PG8_STAGE(bufoff, gbase, voff) do { _Pragma("unroll") for (int _i = 0; _i < 2; ++_i) \
;         __builtin_amdgcn_global_load_lds((const unsigned*)((const char*)(gbase) + (voff)[_i]), (LAS unsigned*)(lds + (bufoff) + ldsw + _i * 8192), 16, 0, 0); } while (0)
; #define PG8_LDA(dst, b, h) do { _Pragma("unroll") for (int m = 0; m < 4; ++m) _Pragma("unroll") for (int k = 0; k < 2; ++k) dst[m][k] = *(const LAS bf16x8*)(lds + PG8_SA(b, h) + aoff + m * 2048 + k * 1024); } while (0)
; #define PG8_LDB(dst, b, h) do { _Pragma("unroll") for (int n = 0; n < 2; ++n) _Pragma("unroll") for (int k = 0; k < 2; ++k) dst[n][k] = *(const LAS bf16x8*)(lds + PG8_SB(b, h) + boff + n * 2048 + k * 1024); } while (0)
; #define PG8_WAIT_V(n) asm volatile("s_waitcnt vmcnt(" #n ")" ::: "memory")
; template <class Epi, class Sched>
; __device__ __forceinline__ void gemm_phase(LAS unsigned char* lds, const Gemm g, const Sched& S, const Epi& E, const int tid) {
;     ...
;     for (;;) {
;         const bool has_next = S.next(ui + 1, nxt);
;         const char* nA = has_next ? (const char*)g.A + (size_t)nxt.pm * tstep : cA; const char* nB = has_next ? (const char*)g.Bt + (size_t)nxt.pn * tstep : cB;
;         const typename Epi::Pre pre = E.prefetch(cur, tid);
;         for (int t = 0; t < nt; t += 2) {
;             const bool last = (t == nt - 2);
;             const char* a1 = cA + (size_t)(t + 1) * kstep;
;             const char* a2 = last ? nA : cA + (size_t)(t + 2) * kstep; const char* b2 = last ? nB : cB + (size_t)(t + 2) * kstep;
;             const char* a3 = a2 + kstep; const char* b3 = b2 + kstep;
;             PG8_LDB(B0, 0, 0); PG8_LDB(B1, 0, 1); PG8_SCHED; PG8_LDA(At, 0, 0); PG8_STAGE(PG8_SA(1, 1), a1 + hstep, voffA);
;             PG8_WAIT_V(8); PG8_WAIT_L(0); PG8_BAR; PG8_MMA(0, 0, At, B0); PG8_MMA(0, 1, At, B1); PG8_BAR; PG8_SCHED;
.LBB0_167:
	s_or_b64 exec, exec, s[22:23]
	s_ashr_i32 s55, s54, 31
	s_lshl_b64 s[22:23], s[54:55], 19
	s_add_u32 s22, s46, s22
	s_addc_u32 s23, s47, s23
	s_and_b64 s[38:39], s[6:7], exec
	s_cselect_b32 s55, s23, s65
	s_cselect_b32 s56, s22, s64
	s_ashr_i32 s63, s62, 31
	s_lshl_b64 s[38:39], s[62:63], 19
	s_add_u32 s38, s12, s38
	s_addc_u32 s39, s73, s39
	s_and_b64 s[58:59], s[6:7], exec
	s_cselect_b32 s57, s39, s67
	s_cselect_b32 s58, s38, s66
	s_add_u32 s64, s64, 0x40080
	s_addc_u32 s65, s65, 0
	s_add_u32 s59, s66, 0x100
	s_addc_u32 s60, s67, 0
	s_mov_b32 s61, -2
	s_add_u32 s63, s64, 0xfffc0080
	s_addc_u32 s66, s65, -1
	s_add_i32 s78, 0, 0x10000
	s_cmp_eq_u32 s61, 12
	s_cselect_b32 s71, s55, s66
	s_cselect_b32 s70, s56, s63
	v_add_u32_e32 v145, s78, v166
	s_cselect_b32 s67, s57, s60
	s_cselect_b32 s66, s58, s59
	s_add_i32 s63, 0, 0x14000
	ds_read_b128 v[146:149], v145
	ds_read_b128 v[150:153], v145 offset:1024
	ds_read_b128 v[154:157], v145 offset:2048
	ds_read_b128 v[158:161], v145 offset:3072
	v_add_u32_e32 v145, s63, v166
	ds_read_b128 v[172:175], v145
	ds_read_b128 v[176:179], v145 offset:1024
	ds_read_b128 v[180:183], v145 offset:2048
	ds_read_b128 v[184:187], v145 offset:3072
	v_lshl_add_u64 v[162:163], s[64:65], 0, v[140:141]
	s_add_i32 m0, s75, 0xc000
	ds_read_b128 v[188:191], v171
	ds_read_b128 v[198:201], v171 offset:1024
	ds_read_b128 v[202:205], v171 offset:2048
	ds_read_b128 v[206:209], v171 offset:3072
	ds_read_b128 v[210:213], v171 offset:4096
	ds_read_b128 v[214:217], v171 offset:5120
	ds_read_b128 v[218:221], v171 offset:6144
	ds_read_b128 v[230:233], v171 offset:7168
	global_load_lds_dwordx4 v[162:163], off
	v_lshl_add_u64 v[162:163], s[64:65], 0, v[142:143]
	s_add_i32 m0, s75, 0xe000
	s_nop 0
	global_load_lds_dwordx4 v[162:163], off
	s_waitcnt vmcnt(8)
	s_waitcnt lgkmcnt(0)
	s_barrier
	s_waitcnt lgkmcnt(0)
	v_mfma_f32_16x16x32_bf16 v[128:131], v[146:149], v[188:191], 0
	v_mfma_f32_16x16x32_bf16 v[124:127], v[154:157], v[188:191], 0
	v_mfma_f32_16x16x32_bf16 v[108:111], v[146:149], v[202:205], 0
	v_mfma_f32_16x16x32_bf16 v[104:107], v[154:157], v[202:205], 0
	v_mfma_f32_16x16x32_bf16 v[92:95], v[146:149], v[210:213], 0
	v_mfma_f32_16x16x32_bf16 v[88:91], v[154:157], v[210:213], 0
	v_mfma_f32_16x16x32_bf16 v[76:79], v[146:149], v[218:221], 0
	v_mfma_f32_16x16x32_bf16 v[72:75], v[154:157], v[218:221], 0
	v_mfma_f32_16x16x32_bf16 v[128:131], v[150:153], v[198:201], v[128:131]
	v_mfma_f32_16x16x32_bf16 v[124:127], v[158:161], v[198:201], v[124:127]
	v_mfma_f32_16x16x32_bf16 v[108:111], v[150:153], v[206:209], v[108:111]
	v_mfma_f32_16x16x32_bf16 v[104:107], v[158:161], v[206:209], v[104:107]
	v_mfma_f32_16x16x32_bf16 v[92:95], v[150:153], v[214:217], v[92:95]
	v_mfma_f32_16x16x32_bf16 v[88:91], v[158:161], v[214:217], v[88:91]
	v_mfma_f32_16x16x32_bf16 v[76:79], v[150:153], v[230:233], v[76:79]
	v_mfma_f32_16x16x32_bf16 v[72:75], v[158:161], v[230:233], v[72:75]
	v_mfma_f32_16x16x32_bf16 v[120:123], v[172:175], v[188:191], 0
	v_mfma_f32_16x16x32_bf16 v[116:119], v[180:183], v[188:191], 0
	v_mfma_f32_16x16x32_bf16 v[100:103], v[172:175], v[202:205], 0
	v_mfma_f32_16x16x32_bf16 v[96:99], v[180:183], v[202:205], 0
	v_mfma_f32_16x16x32_bf16 v[84:87], v[172:175], v[210:213], 0
	v_mfma_f32_16x16x32_bf16 v[80:83], v[180:183], v[210:213], 0
	v_mfma_f32_16x16x32_bf16 v[68:71], v[172:175], v[218:221], 0
	v_mfma_f32_16x16x32_bf16 v[64:67], v[180:183], v[218:221], 0
	v_mfma_f32_16x16x32_bf16 v[120:123], v[176:179], v[198:201], v[120:123]
	v_mfma_f32_16x16x32_bf16 v[116:119], v[184:187], v[198:201], v[116:119]
	v_mfma_f32_16x16x32_bf16 v[100:103], v[176:179], v[206:209], v[100:103]
	v_mfma_f32_16x16x32_bf16 v[96:99], v[184:187], v[206:209], v[96:99]
	v_mfma_f32_16x16x32_bf16 v[84:87], v[176:179], v[214:217], v[84:87]
	v_mfma_f32_16x16x32_bf16 v[80:83], v[184:187], v[214:217], v[80:83]
	v_mfma_f32_16x16x32_bf16 v[68:71], v[176:179], v[230:233], v[68:71]
	v_mfma_f32_16x16x32_bf16 v[64:67], v[184:187], v[230:233], v[64:67]
	s_barrier
	s_add_i32 s78, s78, s74
	v_lshl_add_u64 v[162:163], s[66:67], 0, v[192:193]
	s_mov_b32 m0, s78
	ds_read_b128 v[188:191], v171 offset:16384
	ds_read_b128 v[198:201], v171 offset:17408
	ds_read_b128 v[202:205], v171 offset:18432
	ds_read_b128 v[206:209], v171 offset:19456
	ds_read_b128 v[210:213], v171 offset:20480
	ds_read_b128 v[214:217], v171 offset:21504
	ds_read_b128 v[218:221], v171 offset:22528
	ds_read_b128 v[230:233], v171 offset:23552
	global_load_lds_dwordx4 v[162:163], off
	s_add_i32 m0, s78, 0x2000
	s_add_u32 s78, s66, 0x40000
	v_lshl_add_u64 v[234:235], s[66:67], 0, v[134:135]
	s_addc_u32 s79, s67, 0
	s_add_i32 s63, s63, s74
	global_load_lds_dwordx4 v[234:235], off
	v_lshl_add_u64 v[236:237], s[78:79], 0, v[192:193]
	s_mov_b32 m0, s63
	v_lshl_add_u64 v[238:239], s[70:71], 0, v[136:137]
	global_load_lds_dwordx4 v[236:237], off
	v_lshl_add_u64 v[236:237], s[78:79], 0, v[134:135]
	s_add_i32 m0, s63, 0x2000
	s_nop 0
	global_load_lds_dwordx4 v[236:237], off
	v_lshl_add_u64 v[236:237], s[70:71], 0, v[138:139]
	s_mov_b32 m0, s75
	s_nop 0
	global_load_lds_dwordx4 v[236:237], off
	s_mov_b32 m0, s81
	s_nop 0
	global_load_lds_dwordx4 v[238:239], off
	s_waitcnt vmcnt(8)
	s_waitcnt lgkmcnt(0)
	s_barrier
; #define PG8_STAGE(bufoff, gbase, voff) do { _Pragma("unroll") for (int _i = 0; _i < 2; ++_i) \
;         __builtin_amdgcn_global_load_lds((const unsigned*)((const char*)(gbase) + (voff)[_i]), (LAS unsigned*)(lds + (bufoff) + ldsw + _i * 8192), 16, 0, 0); } while (0)
; #define PG8_LDA(dst, b, h) do { _Pragma("unroll") for (int m = 0; m < 4; ++m) _Pragma("unroll") for (int k = 0; k < 2; ++k) dst[m][k] = *(const LAS bf16x8*)(lds + PG8_SA(b, h) + aoff + m * 2048 + k * 1024); } while (0)
; #define PG8_LDB(dst, b, h) do { _Pragma("unroll") for (int n = 0; n < 2; ++n) _Pragma("unroll") for (int k = 0; k < 2; ++k) dst[n][k] = *(const LAS bf16x8*)(lds + PG8_SB(b, h) + boff + n * 2048 + k * 1024); } while (0)
; #define PG8_MMA(ai, bj, At, Bt) do { __builtin_amdgcn_s_setprio(1); _Pragma("unroll") for (int m = 0; m < 4; ++m) _Pragma("unroll") for (int n = 0; n < 2; ++n) _Pragma("unroll") for (int k = 0; k < 2; ++k) \
;         acc[ai][bj][m][n] = __builtin_amdgcn_mfma_f32_16x16x32_bf16(Bt[n][k], At[m][k], acc[ai][bj][m][n], 0, 0, 0); __builtin_amdgcn_s_setprio(0); } while (0)
; #define PG8_WAIT_V(n) asm volatile("s_waitcnt vmcnt(" #n ")" ::: "memory")
; #define PG8_WAIT_L(n) asm volatile("s_waitcnt lgkmcnt(" #n ")" ::: "memory")
; #define PG8_BAR __builtin_amdgcn_s_barrier()
; #define PG8_SCHED __builtin_amdgcn_sched_barrier(0)
; template <class Epi, class Sched>
; __device__ __forceinline__ void gemm_phase(LAS unsigned char* lds, const Gemm g, const Sched& S, const Epi& E, const int tid) {
;     ...
;             PG8_WAIT_V(8); PG8_WAIT_L(0); PG8_BAR; PG8_MMA(0, 0, At, B0); PG8_MMA(0, 1, At, B1); PG8_BAR; PG8_SCHED;
;             PG8_LDA(At, 0, 1); PG8_STAGE(PG8_SB(0, 0), b2, voffB); PG8_STAGE(PG8_SB(0, 1), b2 + hstep, voffB); PG8_STAGE(PG8_SA(0, 0), a2, voffA);
;             PG8_WAIT_V(8); PG8_WAIT_L(0); PG8_BAR; PG8_MMA(1, 0, At, B0); PG8_MMA(1, 1, At, B1); PG8_BAR; PG8_SCHED;
;             PG8_LDB(B0, 1, 0); PG8_LDB(B1, 1, 1); PG8_SCHED; PG8_LDA(At, 1, 0); PG8_STAGE(PG8_SA(0, 1), a2 + hstep, voffA);
;             PG8_WAIT_V(8); PG8_WAIT_L(0); PG8_BAR; PG8_MMA(0, 0, At, B0); PG8_MMA(0, 1, At, B1); PG8_BAR; PG8_SCHED;
	s_waitcnt lgkmcnt(0)
	v_mfma_f32_16x16x32_bf16 v[60:63], v[146:149], v[188:191], 0
	v_mfma_f32_16x16x32_bf16 v[56:59], v[154:157], v[188:191], 0
	v_mfma_f32_16x16x32_bf16 v[44:47], v[146:149], v[202:205], 0
	v_mfma_f32_16x16x32_bf16 v[40:43], v[154:157], v[202:205], 0
	v_mfma_f32_16x16x32_bf16 v[28:31], v[146:149], v[210:213], 0
	v_mfma_f32_16x16x32_bf16 v[24:27], v[154:157], v[210:213], 0
	v_mfma_f32_16x16x32_bf16 v[12:15], v[146:149], v[218:221], 0
	v_mfma_f32_16x16x32_bf16 v[8:11], v[154:157], v[218:221], 0
	v_mfma_f32_16x16x32_bf16 v[60:63], v[150:153], v[198:201], v[60:63]
	v_mfma_f32_16x16x32_bf16 v[56:59], v[158:161], v[198:201], v[56:59]
	v_mfma_f32_16x16x32_bf16 v[44:47], v[150:153], v[206:209], v[44:47]
	v_mfma_f32_16x16x32_bf16 v[40:43], v[158:161], v[206:209], v[40:43]
	v_mfma_f32_16x16x32_bf16 v[28:31], v[150:153], v[214:217], v[28:31]
	v_mfma_f32_16x16x32_bf16 v[24:27], v[158:161], v[214:217], v[24:27]
	v_mfma_f32_16x16x32_bf16 v[12:15], v[150:153], v[230:233], v[12:15]
	v_mfma_f32_16x16x32_bf16 v[8:11], v[158:161], v[230:233], v[8:11]
	v_mfma_f32_16x16x32_bf16 v[52:55], v[172:175], v[188:191], 0
	v_mfma_f32_16x16x32_bf16 v[48:51], v[180:183], v[188:191], 0
	v_mfma_f32_16x16x32_bf16 v[36:39], v[172:175], v[202:205], 0
	v_mfma_f32_16x16x32_bf16 v[32:35], v[180:183], v[202:205], 0
	v_mfma_f32_16x16x32_bf16 v[20:23], v[172:175], v[210:213], 0
	v_mfma_f32_16x16x32_bf16 v[16:19], v[180:183], v[210:213], 0
	v_mfma_f32_16x16x32_bf16 v[4:7], v[172:175], v[218:221], 0
	v_mfma_f32_16x16x32_bf16 v[0:3], v[180:183], v[218:221], 0
	v_mfma_f32_16x16x32_bf16 v[52:55], v[176:179], v[198:201], v[52:55]
	v_mfma_f32_16x16x32_bf16 v[48:51], v[184:187], v[198:201], v[48:51]
	v_mfma_f32_16x16x32_bf16 v[36:39], v[176:179], v[206:209], v[36:39]
	v_mfma_f32_16x16x32_bf16 v[32:35], v[184:187], v[206:209], v[32:35]
	v_mfma_f32_16x16x32_bf16 v[20:23], v[176:179], v[214:217], v[20:23]
	v_mfma_f32_16x16x32_bf16 v[16:19], v[184:187], v[214:217], v[16:19]
	v_mfma_f32_16x16x32_bf16 v[4:7], v[176:179], v[230:233], v[4:7]
	v_mfma_f32_16x16x32_bf16 v[0:3], v[184:187], v[230:233], v[0:3]
	s_barrier
	s_add_i32 s63, 0, 0x18000
	v_add_u32_e32 v145, s63, v166
	s_add_i32 s78, 0, 0x1c000
	ds_read_b128 v[146:149], v145
	ds_read_b128 v[150:153], v145 offset:1024
	ds_read_b128 v[154:157], v145 offset:2048
	ds_read_b128 v[158:161], v145 offset:3072
	v_add_u32_e32 v145, s78, v166
	ds_read_b128 v[172:175], v145
	ds_read_b128 v[176:179], v145 offset:1024
	ds_read_b128 v[180:183], v145 offset:2048
	ds_read_b128 v[184:187], v145 offset:3072
	s_add_u32 s70, s70, 0x40000
	s_addc_u32 s71, s71, 0
	s_mov_b32 m0, s82
	v_lshl_add_u64 v[240:241], s[70:71], 0, v[138:139]
	ds_read_b128 v[188:191], v171 offset:32768
	ds_read_b128 v[198:201], v171 offset:33792
	ds_read_b128 v[202:205], v171 offset:34816
	ds_read_b128 v[206:209], v171 offset:35840
	ds_read_b128 v[210:213], v171 offset:36864
	ds_read_b128 v[214:217], v171 offset:37888
	ds_read_b128 v[218:221], v171 offset:38912
	ds_read_b128 v[230:233], v171 offset:39936
	global_load_lds_dwordx4 v[240:241], off
	v_lshl_add_u64 v[240:241], s[70:71], 0, v[136:137]
	s_mov_b32 m0, s83
	s_nop 0
	global_load_lds_dwordx4 v[240:241], off
	s_waitcnt vmcnt(8)
	s_waitcnt lgkmcnt(0)
	s_barrier
	s_waitcnt lgkmcnt(0)
	v_mfma_f32_16x16x32_bf16 v[128:131], v[146:149], v[188:191], v[128:131]
	v_mfma_f32_16x16x32_bf16 v[124:127], v[154:157], v[188:191], v[124:127]
	v_mfma_f32_16x16x32_bf16 v[108:111], v[146:149], v[202:205], v[108:111]
	v_mfma_f32_16x16x32_bf16 v[104:107], v[154:157], v[202:205], v[104:107]
	v_mfma_f32_16x16x32_bf16 v[92:95], v[146:149], v[210:213], v[92:95]
	v_mfma_f32_16x16x32_bf16 v[88:91], v[154:157], v[210:213], v[88:91]
	v_mfma_f32_16x16x32_bf16 v[76:79], v[146:149], v[218:221], v[76:79]
	v_mfma_f32_16x16x32_bf16 v[72:75], v[154:157], v[218:221], v[72:75]
	v_mfma_f32_16x16x32_bf16 v[128:131], v[150:153], v[198:201], v[128:131]
	v_mfma_f32_16x16x32_bf16 v[124:127], v[158:161], v[198:201], v[124:127]
	v_mfma_f32_16x16x32_bf16 v[108:111], v[150:153], v[206:209], v[108:111]
	v_mfma_f32_16x16x32_bf16 v[104:107], v[158:161], v[206:209], v[104:107]
	v_mfma_f32_16x16x32_bf16 v[92:95], v[150:153], v[214:217], v[92:95]
	v_mfma_f32_16x16x32_bf16 v[88:91], v[158:161], v[214:217], v[88:91]
	v_mfma_f32_16x16x32_bf16 v[76:79], v[150:153], v[230:233], v[76:79]
	v_mfma_f32_16x16x32_bf16 v[72:75], v[158:161], v[230:233], v[72:75]
	v_mfma_f32_16x16x32_bf16 v[120:123], v[172:175], v[188:191], v[120:123]
	v_mfma_f32_16x16x32_bf16 v[116:119], v[180:183], v[188:191], v[116:119]
	v_mfma_f32_16x16x32_bf16 v[100:103], v[172:175], v[202:205], v[100:103]
	v_mfma_f32_16x16x32_bf16 v[96:99], v[180:183], v[202:205], v[96:99]
	v_mfma_f32_16x16x32_bf16 v[84:87], v[172:175], v[210:213], v[84:87]
	v_mfma_f32_16x16x32_bf16 v[80:83], v[180:183], v[210:213], v[80:83]
	v_mfma_f32_16x16x32_bf16 v[68:71], v[172:175], v[218:221], v[68:71]
	v_mfma_f32_16x16x32_bf16 v[64:67], v[180:183], v[218:221], v[64:67]
	v_mfma_f32_16x16x32_bf16 v[120:123], v[176:179], v[198:201], v[120:123]
	v_mfma_f32_16x16x32_bf16 v[116:119], v[184:187], v[198:201], v[116:119]
	v_mfma_f32_16x16x32_bf16 v[100:103], v[176:179], v[206:209], v[100:103]
	v_mfma_f32_16x16x32_bf16 v[96:99], v[184:187], v[206:209], v[96:99]
	v_mfma_f32_16x16x32_bf16 v[84:87], v[176:179], v[214:217], v[84:87]
	v_mfma_f32_16x16x32_bf16 v[80:83], v[184:187], v[214:217], v[80:83]
	v_mfma_f32_16x16x32_bf16 v[68:71], v[176:179], v[230:233], v[68:71]
	v_mfma_f32_16x16x32_bf16 v[64:67], v[184:187], v[230:233], v[64:67]
	s_barrier
; #define PG8_STAGE(bufoff, gbase, voff) do { _Pragma("unroll") for (int _i = 0; _i < 2; ++_i) \
;         __builtin_amdgcn_global_load_lds((const unsigned*)((const char*)(gbase) + (voff)[_i]), (LAS unsigned*)(lds + (bufoff) + ldsw + _i * 8192), 16, 0, 0); } while (0)
; #define PG8_LDA(dst, b, h) do { _Pragma("unroll") for (int m = 0; m < 4; ++m) _Pragma("unroll") for (int k = 0; k < 2; ++k) dst[m][k] = *(const LAS bf16x8*)(lds + PG8_SA(b, h) + aoff + m * 2048 + k * 1024); } while (0)
; #define PG8_LDB(dst, b, h) do { _Pragma("unroll") for (int n = 0; n < 2; ++n) _Pragma("unroll") for (int k = 0; k < 2; ++k) dst[n][k] = *(const LAS bf16x8*)(lds + PG8_SB(b, h) + boff + n * 2048 + k * 1024); } while (0)
; #define PG8_WAIT_V(n) asm volatile("s_waitcnt vmcnt(" #n ")" ::: "memory")
; #define PG8_BAR __builtin_amdgcn_s_barrier()
; template <class Epi, class Sched>
; __device__ __forceinline__ void gemm_phase(LAS unsigned char* lds, const Gemm g, const Sched& S, const Epi& E, const int tid) {
;     ...
;         for (int t = 0; t < nt; t += 2) {
;             const bool last = (t == nt - 2);
;             const char* a1 = cA + (size_t)(t + 1) * kstep;
;             const char* a2 = last ? nA : cA + (size_t)(t + 2) * kstep; const char* b2 = last ? nB : cB + (size_t)(t + 2) * kstep;
;             const char* a3 = a2 + kstep; const char* b3 = b2 + kstep;
;             PG8_LDB(B0, 0, 0); PG8_LDB(B1, 0, 1); PG8_SCHED; PG8_LDA(At, 0, 0); PG8_STAGE(PG8_SA(1, 1), a1 + hstep, voffA);
;             PG8_WAIT_V(8); PG8_WAIT_L(0); PG8_BAR; PG8_MMA(0, 0, At, B0); PG8_MMA(0, 1, At, B1); PG8_BAR; PG8_SCHED;
;             PG8_LDA(At, 0, 1); PG8_STAGE(PG8_SB(0, 0), b2, voffB); PG8_STAGE(PG8_SB(0, 1), b2 + hstep, voffB); PG8_STAGE(PG8_SA(0, 0), a2, voffA);
;             PG8_WAIT_V(8); PG8_WAIT_L(0); PG8_BAR; PG8_MMA(1, 0, At, B0); PG8_MMA(1, 1, At, B1); PG8_BAR; PG8_SCHED;
;             PG8_LDB(B0, 1, 0); PG8_LDB(B1, 1, 1); PG8_SCHED; PG8_LDA(At, 1, 0); PG8_STAGE(PG8_SA(0, 1), a2 + hstep, voffA);
;             PG8_WAIT_V(8); PG8_WAIT_L(0); PG8_BAR; PG8_MMA(0, 0, At, B0); PG8_MMA(0, 1, At, B1); PG8_BAR; PG8_SCHED;
;             PG8_LDA(At, 1, 1); PG8_STAGE(PG8_SB(1, 0), b3, voffB); PG8_STAGE(PG8_SB(1, 1), b3 + hstep, voffB); PG8_STAGE(PG8_SA(1, 0), a3, voffA);
;             PG8_WAIT_V(8); PG8_WAIT_L(0); PG8_BAR; PG8_MMA(1, 0, At, B0); PG8_MMA(1, 1, At, B1); PG8_BAR; PG8_SCHED;
;         }
	s_add_i32 s63, s63, s74
	v_lshl_add_u64 v[162:163], v[162:163], 0, s[68:69]
	s_mov_b32 m0, s63
	ds_read_b128 v[188:191], v171 offset:49152
	ds_read_b128 v[198:201], v171 offset:50176
	ds_read_b128 v[202:205], v171 offset:51200
	ds_read_b128 v[206:209], v171 offset:52224
	ds_read_b128 v[210:213], v171 offset:53248
	ds_read_b128 v[214:217], v171 offset:54272
	ds_read_b128 v[218:221], v171 offset:55296
	ds_read_b128 v[230:233], v171 offset:56320
	global_load_lds_dwordx4 v[162:163], off
	s_add_i32 m0, s63, 0x2000
	s_add_u32 s66, s66, 0x40080
	v_lshl_add_u64 v[162:163], v[234:235], 0, s[68:69]
	s_addc_u32 s67, s67, 0
	s_add_i32 s63, s78, s74
	global_load_lds_dwordx4 v[162:163], off
	v_lshl_add_u64 v[162:163], s[66:67], 0, v[192:193]
	s_mov_b32 m0, s63
	s_nop 0
	global_load_lds_dwordx4 v[162:163], off
	v_lshl_add_u64 v[162:163], s[66:67], 0, v[134:135]
	s_add_i32 m0, s63, 0x2000
	s_nop 0
	global_load_lds_dwordx4 v[162:163], off
	v_lshl_add_u64 v[162:163], v[236:237], 0, s[68:69]
	s_mov_b32 m0, s93
	s_nop 0
	global_load_lds_dwordx4 v[162:163], off
	v_lshl_add_u64 v[162:163], v[238:239], 0, s[68:69]
	s_mov_b32 m0, s94
	s_nop 0
	global_load_lds_dwordx4 v[162:163], off
	s_waitcnt vmcnt(8)
	s_waitcnt lgkmcnt(0)
	s_barrier
	s_waitcnt lgkmcnt(0)
	v_mfma_f32_16x16x32_bf16 v[60:63], v[146:149], v[188:191], v[60:63]
	v_mfma_f32_16x16x32_bf16 v[56:59], v[154:157], v[188:191], v[56:59]
	v_mfma_f32_16x16x32_bf16 v[44:47], v[146:149], v[202:205], v[44:47]
	v_mfma_f32_16x16x32_bf16 v[40:43], v[154:157], v[202:205], v[40:43]
	v_mfma_f32_16x16x32_bf16 v[28:31], v[146:149], v[210:213], v[28:31]
	v_mfma_f32_16x16x32_bf16 v[24:27], v[154:157], v[210:213], v[24:27]
	v_mfma_f32_16x16x32_bf16 v[12:15], v[146:149], v[218:221], v[12:15]
	v_mfma_f32_16x16x32_bf16 v[8:11], v[154:157], v[218:221], v[8:11]
	v_mfma_f32_16x16x32_bf16 v[60:63], v[150:153], v[198:201], v[60:63]
	v_mfma_f32_16x16x32_bf16 v[56:59], v[158:161], v[198:201], v[56:59]
	v_mfma_f32_16x16x32_bf16 v[44:47], v[150:153], v[206:209], v[44:47]
	v_mfma_f32_16x16x32_bf16 v[40:43], v[158:161], v[206:209], v[40:43]
	v_mfma_f32_16x16x32_bf16 v[28:31], v[150:153], v[214:217], v[28:31]
	v_mfma_f32_16x16x32_bf16 v[24:27], v[158:161], v[214:217], v[24:27]
	v_mfma_f32_16x16x32_bf16 v[12:15], v[150:153], v[230:233], v[12:15]
	v_mfma_f32_16x16x32_bf16 v[8:11], v[158:161], v[230:233], v[8:11]
	v_mfma_f32_16x16x32_bf16 v[52:55], v[172:175], v[188:191], v[52:55]
	v_mfma_f32_16x16x32_bf16 v[48:51], v[180:183], v[188:191], v[48:51]
	v_mfma_f32_16x16x32_bf16 v[36:39], v[172:175], v[202:205], v[36:39]
	v_mfma_f32_16x16x32_bf16 v[32:35], v[180:183], v[202:205], v[32:35]
	v_mfma_f32_16x16x32_bf16 v[20:23], v[172:175], v[210:213], v[20:23]
	v_mfma_f32_16x16x32_bf16 v[16:19], v[180:183], v[210:213], v[16:19]
	v_mfma_f32_16x16x32_bf16 v[4:7], v[172:175], v[218:221], v[4:7]
	v_mfma_f32_16x16x32_bf16 v[0:3], v[180:183], v[218:221], v[0:3]
	v_mfma_f32_16x16x32_bf16 v[52:55], v[176:179], v[198:201], v[52:55]
	v_mfma_f32_16x16x32_bf16 v[48:51], v[184:187], v[198:201], v[48:51]
	v_mfma_f32_16x16x32_bf16 v[36:39], v[176:179], v[206:209], v[36:39]
	v_mfma_f32_16x16x32_bf16 v[32:35], v[184:187], v[206:209], v[32:35]
	v_mfma_f32_16x16x32_bf16 v[20:23], v[176:179], v[214:217], v[20:23]
	v_mfma_f32_16x16x32_bf16 v[16:19], v[184:187], v[214:217], v[16:19]
	v_mfma_f32_16x16x32_bf16 v[4:7], v[176:179], v[230:233], v[4:7]
	v_mfma_f32_16x16x32_bf16 v[0:3], v[184:187], v[230:233], v[0:3]
	s_barrier
	s_add_i32 s61, s61, 2
	s_add_u32 s64, s64, 0x100
	s_addc_u32 s65, s65, 0
	s_add_u32 s59, s59, 0x100
	s_addc_u32 s60, s60, 0
	s_cmp_gt_u32 s61, 13
.LBB0_168:
	s_add_u32 s63, s64, 0xfffc0080
	s_addc_u32 s66, s65, -1
	s_add_i32 s78, 0, 0x10000
	s_cmp_eq_u32 s61, 12
	s_cselect_b32 s71, s55, s66
	s_cselect_b32 s70, s56, s63
	v_add_u32_e32 v145, s78, v166
	s_cselect_b32 s67, s57, s60
	s_cselect_b32 s66, s58, s59
	s_add_i32 s63, 0, 0x14000
	ds_read_b128 v[146:149], v145
	ds_read_b128 v[150:153], v145 offset:1024
	ds_read_b128 v[154:157], v145 offset:2048
	ds_read_b128 v[158:161], v145 offset:3072
	v_add_u32_e32 v145, s63, v166
	ds_read_b128 v[172:175], v145
	ds_read_b128 v[176:179], v145 offset:1024
	ds_read_b128 v[180:183], v145 offset:2048
	ds_read_b128 v[184:187], v145 offset:3072
	v_lshl_add_u64 v[162:163], s[64:65], 0, v[140:141]
	s_add_i32 m0, s75, 0xc000
	ds_read_b128 v[188:191], v171
	ds_read_b128 v[198:201], v171 offset:1024
	ds_read_b128 v[202:205], v171 offset:2048
	ds_read_b128 v[206:209], v171 offset:3072
	ds_read_b128 v[210:213], v171 offset:4096
	ds_read_b128 v[214:217], v171 offset:5120
	ds_read_b128 v[218:221], v171 offset:6144
	ds_read_b128 v[230:233], v171 offset:7168
	global_load_lds_dwordx4 v[162:163], off
	v_lshl_add_u64 v[162:163], s[64:65], 0, v[142:143]
	s_add_i32 m0, s75, 0xe000
	s_nop 0
	global_load_lds_dwordx4 v[162:163], off
	s_waitcnt vmcnt(8)
	s_waitcnt lgkmcnt(0)
	s_barrier
; #define PG8_STAGE(bufoff, gbase, voff) do { _Pragma("unroll") for (int _i = 0; _i < 2; ++_i) \
;         __builtin_amdgcn_global_load_lds((const unsigned*)((const char*)(gbase) + (voff)[_i]), (LAS unsigned*)(lds + (bufoff) + ldsw + _i * 8192), 16, 0, 0); } while (0)
; #define PG8_LDA(dst, b, h) do { _Pragma("unroll") for (int m = 0; m < 4; ++m) _Pragma("unroll") for (int k = 0; k < 2; ++k) dst[m][k] = *(const LAS bf16x8*)(lds + PG8_SA(b, h) + aoff + m * 2048 + k * 1024); } while (0)
; #define PG8_LDB(dst, b, h) do { _Pragma("unroll") for (int n = 0; n < 2; ++n) _Pragma("unroll") for (int k = 0; k < 2; ++k) dst[n][k] = *(const LAS bf16x8*)(lds + PG8_SB(b, h) + boff + n * 2048 + k * 1024); } while (0)
; #define PG8_MMA(ai, bj, At, Bt) do { __builtin_amdgcn_s_setprio(1); _Pragma("unroll") for (int m = 0; m < 4; ++m) _Pragma("unroll") for (int n = 0; n < 2; ++n) _Pragma("unroll") for (int k = 0; k < 2; ++k) \
;         acc[ai][bj][m][n] = __builtin_amdgcn_mfma_f32_16x16x32_bf16(Bt[n][k], At[m][k], acc[ai][bj][m][n], 0, 0, 0); __builtin_amdgcn_s_setprio(0); } while (0)
; #define PG8_WAIT_V(n) asm volatile("s_waitcnt vmcnt(" #n ")" ::: "memory")
; #define PG8_WAIT_L(n) asm volatile("s_waitcnt lgkmcnt(" #n ")" ::: "memory")
; #define PG8_BAR __builtin_amdgcn_s_barrier()
; #define PG8_SCHED __builtin_amdgcn_sched_barrier(0)
; template <class Epi, class Sched>
; __device__ __forceinline__ void gemm_phase(LAS unsigned char* lds, const Gemm g, const Sched& S, const Epi& E, const int tid) {
;     ...
;             PG8_WAIT_V(8); PG8_WAIT_L(0); PG8_BAR; PG8_MMA(0, 0, At, B0); PG8_MMA(0, 1, At, B1); PG8_BAR; PG8_SCHED;
;             PG8_LDA(At, 0, 1); PG8_STAGE(PG8_SB(0, 0), b2, voffB); PG8_STAGE(PG8_SB(0, 1), b2 + hstep, voffB); PG8_STAGE(PG8_SA(0, 0), a2, voffA);
;             PG8_WAIT_V(8); PG8_WAIT_L(0); PG8_BAR; PG8_MMA(1, 0, At, B0); PG8_MMA(1, 1, At, B1); PG8_BAR; PG8_SCHED;
;             PG8_LDB(B0, 1, 0); PG8_LDB(B1, 1, 1); PG8_SCHED; PG8_LDA(At, 1, 0); PG8_STAGE(PG8_SA(0, 1), a2 + hstep, voffA);
;             PG8_WAIT_V(8); PG8_WAIT_L(0); PG8_BAR; PG8_MMA(0, 0, At, B0); PG8_MMA(0, 1, At, B1); PG8_BAR; PG8_SCHED;
	s_waitcnt lgkmcnt(0)
	v_mfma_f32_16x16x32_bf16 v[128:131], v[146:149], v[188:191], v[128:131]
	v_mfma_f32_16x16x32_bf16 v[124:127], v[154:157], v[188:191], v[124:127]
	v_mfma_f32_16x16x32_bf16 v[108:111], v[146:149], v[202:205], v[108:111]
	v_mfma_f32_16x16x32_bf16 v[104:107], v[154:157], v[202:205], v[104:107]
	v_mfma_f32_16x16x32_bf16 v[92:95], v[146:149], v[210:213], v[92:95]
	v_mfma_f32_16x16x32_bf16 v[88:91], v[154:157], v[210:213], v[88:91]
	v_mfma_f32_16x16x32_bf16 v[76:79], v[146:149], v[218:221], v[76:79]
	v_mfma_f32_16x16x32_bf16 v[72:75], v[154:157], v[218:221], v[72:75]
	v_mfma_f32_16x16x32_bf16 v[128:131], v[150:153], v[198:201], v[128:131]
	v_mfma_f32_16x16x32_bf16 v[124:127], v[158:161], v[198:201], v[124:127]
	v_mfma_f32_16x16x32_bf16 v[108:111], v[150:153], v[206:209], v[108:111]
	v_mfma_f32_16x16x32_bf16 v[104:107], v[158:161], v[206:209], v[104:107]
	v_mfma_f32_16x16x32_bf16 v[92:95], v[150:153], v[214:217], v[92:95]
	v_mfma_f32_16x16x32_bf16 v[88:91], v[158:161], v[214:217], v[88:91]
	v_mfma_f32_16x16x32_bf16 v[76:79], v[150:153], v[230:233], v[76:79]
	v_mfma_f32_16x16x32_bf16 v[72:75], v[158:161], v[230:233], v[72:75]
	v_mfma_f32_16x16x32_bf16 v[120:123], v[172:175], v[188:191], v[120:123]
	v_mfma_f32_16x16x32_bf16 v[116:119], v[180:183], v[188:191], v[116:119]
	v_mfma_f32_16x16x32_bf16 v[100:103], v[172:175], v[202:205], v[100:103]
	v_mfma_f32_16x16x32_bf16 v[96:99], v[180:183], v[202:205], v[96:99]
	v_mfma_f32_16x16x32_bf16 v[84:87], v[172:175], v[210:213], v[84:87]
	v_mfma_f32_16x16x32_bf16 v[80:83], v[180:183], v[210:213], v[80:83]
	v_mfma_f32_16x16x32_bf16 v[68:71], v[172:175], v[218:221], v[68:71]
	v_mfma_f32_16x16x32_bf16 v[64:67], v[180:183], v[218:221], v[64:67]
	v_mfma_f32_16x16x32_bf16 v[120:123], v[176:179], v[198:201], v[120:123]
	v_mfma_f32_16x16x32_bf16 v[116:119], v[184:187], v[198:201], v[116:119]
	v_mfma_f32_16x16x32_bf16 v[100:103], v[176:179], v[206:209], v[100:103]
	v_mfma_f32_16x16x32_bf16 v[96:99], v[184:187], v[206:209], v[96:99]
	v_mfma_f32_16x16x32_bf16 v[84:87], v[176:179], v[214:217], v[84:87]
	v_mfma_f32_16x16x32_bf16 v[80:83], v[184:187], v[214:217], v[80:83]
	v_mfma_f32_16x16x32_bf16 v[68:71], v[176:179], v[230:233], v[68:71]
	v_mfma_f32_16x16x32_bf16 v[64:67], v[184:187], v[230:233], v[64:67]
	s_barrier
	s_add_i32 s78, s78, s74
	v_lshl_add_u64 v[162:163], s[66:67], 0, v[192:193]
	s_mov_b32 m0, s78
	ds_read_b128 v[188:191], v171 offset:16384
	ds_read_b128 v[198:201], v171 offset:17408
	ds_read_b128 v[202:205], v171 offset:18432
	ds_read_b128 v[206:209], v171 offset:19456
	ds_read_b128 v[210:213], v171 offset:20480
	ds_read_b128 v[214:217], v171 offset:21504
	ds_read_b128 v[218:221], v171 offset:22528
	ds_read_b128 v[230:233], v171 offset:23552
	global_load_lds_dwordx4 v[162:163], off
	s_add_i32 m0, s78, 0x2000
	s_add_u32 s78, s66, 0x40000
	v_lshl_add_u64 v[234:235], s[66:67], 0, v[134:135]
	s_addc_u32 s79, s67, 0
	s_add_i32 s63, s63, s74
	global_load_lds_dwordx4 v[234:235], off
	v_lshl_add_u64 v[236:237], s[78:79], 0, v[192:193]
	s_mov_b32 m0, s63
	v_lshl_add_u64 v[238:239], s[70:71], 0, v[136:137]
	global_load_lds_dwordx4 v[236:237], off
	v_lshl_add_u64 v[236:237], s[78:79], 0, v[134:135]
	s_add_i32 m0, s63, 0x2000
	s_nop 0
	global_load_lds_dwordx4 v[236:237], off
	v_lshl_add_u64 v[236:237], s[70:71], 0, v[138:139]
	s_mov_b32 m0, s75
	s_nop 0
	global_load_lds_dwordx4 v[236:237], off
	s_mov_b32 m0, s81
	s_nop 0
	global_load_lds_dwordx4 v[238:239], off
	s_waitcnt vmcnt(8)
	s_waitcnt lgkmcnt(0)
	s_barrier
	s_waitcnt lgkmcnt(0)
	v_mfma_f32_16x16x32_bf16 v[60:63], v[146:149], v[188:191], v[60:63]
	v_mfma_f32_16x16x32_bf16 v[56:59], v[154:157], v[188:191], v[56:59]
	v_mfma_f32_16x16x32_bf16 v[44:47], v[146:149], v[202:205], v[44:47]
	v_mfma_f32_16x16x32_bf16 v[40:43], v[154:157], v[202:205], v[40:43]
	v_mfma_f32_16x16x32_bf16 v[28:31], v[146:149], v[210:213], v[28:31]
	v_mfma_f32_16x16x32_bf16 v[24:27], v[154:157], v[210:213], v[24:27]
	v_mfma_f32_16x16x32_bf16 v[12:15], v[146:149], v[218:221], v[12:15]
	v_mfma_f32_16x16x32_bf16 v[8:11], v[154:157], v[218:221], v[8:11]
	v_mfma_f32_16x16x32_bf16 v[60:63], v[150:153], v[198:201], v[60:63]
	v_mfma_f32_16x16x32_bf16 v[56:59], v[158:161], v[198:201], v[56:59]
	v_mfma_f32_16x16x32_bf16 v[44:47], v[150:153], v[206:209], v[44:47]
	v_mfma_f32_16x16x32_bf16 v[40:43], v[158:161], v[206:209], v[40:43]
	v_mfma_f32_16x16x32_bf16 v[28:31], v[150:153], v[214:217], v[28:31]
	v_mfma_f32_16x16x32_bf16 v[24:27], v[158:161], v[214:217], v[24:27]
	v_mfma_f32_16x16x32_bf16 v[12:15], v[150:153], v[230:233], v[12:15]
	v_mfma_f32_16x16x32_bf16 v[8:11], v[158:161], v[230:233], v[8:11]
	v_mfma_f32_16x16x32_bf16 v[52:55], v[172:175], v[188:191], v[52:55]
	v_mfma_f32_16x16x32_bf16 v[48:51], v[180:183], v[188:191], v[48:51]
	v_mfma_f32_16x16x32_bf16 v[36:39], v[172:175], v[202:205], v[36:39]
	v_mfma_f32_16x16x32_bf16 v[32:35], v[180:183], v[202:205], v[32:35]
	v_mfma_f32_16x16x32_bf16 v[20:23], v[172:175], v[210:213], v[20:23]
	v_mfma_f32_16x16x32_bf16 v[16:19], v[180:183], v[210:213], v[16:19]
	v_mfma_f32_16x16x32_bf16 v[4:7], v[172:175], v[218:221], v[4:7]
	v_mfma_f32_16x16x32_bf16 v[0:3], v[180:183], v[218:221], v[0:3]
	v_mfma_f32_16x16x32_bf16 v[52:55], v[176:179], v[198:201], v[52:55]
	v_mfma_f32_16x16x32_bf16 v[48:51], v[184:187], v[198:201], v[48:51]
	v_mfma_f32_16x16x32_bf16 v[36:39], v[176:179], v[206:209], v[36:39]
	v_mfma_f32_16x16x32_bf16 v[32:35], v[184:187], v[206:209], v[32:35]
	v_mfma_f32_16x16x32_bf16 v[20:23], v[176:179], v[214:217], v[20:23]
	v_mfma_f32_16x16x32_bf16 v[16:19], v[184:187], v[214:217], v[16:19]
	v_mfma_f32_16x16x32_bf16 v[4:7], v[176:179], v[230:233], v[4:7]
	v_mfma_f32_16x16x32_bf16 v[0:3], v[184:187], v[230:233], v[0:3]
	s_barrier
; #define PG8_STAGE(bufoff, gbase, voff) do { _Pragma("unroll") for (int _i = 0; _i < 2; ++_i) \
;         __builtin_amdgcn_global_load_lds((const unsigned*)((const char*)(gbase) + (voff)[_i]), (LAS unsigned*)(lds + (bufoff) + ldsw + _i * 8192), 16, 0, 0); } while (0)
; #define PG8_LDA(dst, b, h) do { _Pragma("unroll") for (int m = 0; m < 4; ++m) _Pragma("unroll") for (int k = 0; k < 2; ++k) dst[m][k] = *(const LAS bf16x8*)(lds + PG8_SA(b, h) + aoff + m * 2048 + k * 1024); } while (0)
; #define PG8_LDB(dst, b, h) do { _Pragma("unroll") for (int n = 0; n < 2; ++n) _Pragma("unroll") for (int k = 0; k < 2; ++k) dst[n][k] = *(const LAS bf16x8*)(lds + PG8_SB(b, h) + boff + n * 2048 + k * 1024); } while (0)
; #define PG8_MMA(ai, bj, At, Bt) do { __builtin_amdgcn_s_setprio(1); _Pragma("unroll") for (int m = 0; m < 4; ++m) _Pragma("unroll") for (int n = 0; n < 2; ++n) _Pragma("unroll") for (int k = 0; k < 2; ++k) \
;         acc[ai][bj][m][n] = __builtin_amdgcn_mfma_f32_16x16x32_bf16(Bt[n][k], At[m][k], acc[ai][bj][m][n], 0, 0, 0); __builtin_amdgcn_s_setprio(0); } while (0)
; #define PG8_WAIT_V(n) asm volatile("s_waitcnt vmcnt(" #n ")" ::: "memory")
; #define PG8_WAIT_L(n) asm volatile("s_waitcnt lgkmcnt(" #n ")" ::: "memory")
; #define PG8_BAR __builtin_amdgcn_s_barrier()
; #define PG8_SCHED __builtin_amdgcn_sched_barrier(0)
; template <class Epi, class Sched>
; __device__ __forceinline__ void gemm_phase(LAS unsigned char* lds, const Gemm g, const Sched& S, const Epi& E, const int tid) {
;     ...
;             PG8_LDB(B0, 1, 0); PG8_LDB(B1, 1, 1); PG8_SCHED; PG8_LDA(At, 1, 0); PG8_STAGE(PG8_SA(0, 1), a2 + hstep, voffA);
;             PG8_WAIT_V(8); PG8_WAIT_L(0); PG8_BAR; PG8_MMA(0, 0, At, B0); PG8_MMA(0, 1, At, B1); PG8_BAR; PG8_SCHED;
	s_add_i32 s63, 0, 0x18000
	v_add_u32_e32 v145, s63, v166
	s_add_i32 s78, 0, 0x1c000
	ds_read_b128 v[146:149], v145
	ds_read_b128 v[150:153], v145 offset:1024
	ds_read_b128 v[154:157], v145 offset:2048
	ds_read_b128 v[158:161], v145 offset:3072
	v_add_u32_e32 v145, s78, v166
	ds_read_b128 v[172:175], v145
	ds_read_b128 v[176:179], v145 offset:1024
	ds_read_b128 v[180:183], v145 offset:2048
	ds_read_b128 v[184:187], v145 offset:3072
	s_add_u32 s70, s70, 0x40000
	s_addc_u32 s71, s71, 0
	s_mov_b32 m0, s82
	v_lshl_add_u64 v[240:241], s[70:71], 0, v[138:139]
	ds_read_b128 v[188:191], v171 offset:32768
	ds_read_b128 v[198:201], v171 offset:33792
	ds_read_b128 v[202:205], v171 offset:34816
	ds_read_b128 v[206:209], v171 offset:35840
	ds_read_b128 v[210:213], v171 offset:36864
	ds_read_b128 v[214:217], v171 offset:37888
	ds_read_b128 v[218:221], v171 offset:38912
	ds_read_b128 v[230:233], v171 offset:39936
	global_load_lds_dwordx4 v[240:241], off
	v_lshl_add_u64 v[240:241], s[70:71], 0, v[136:137]
	s_mov_b32 m0, s83
	s_nop 0
	global_load_lds_dwordx4 v[240:241], off
	s_waitcnt vmcnt(8)
	s_waitcnt lgkmcnt(0)
	s_barrier
	s_waitcnt lgkmcnt(0)
	v_mfma_f32_16x16x32_bf16 v[128:131], v[146:149], v[188:191], v[128:131]
	v_mfma_f32_16x16x32_bf16 v[124:127], v[154:157], v[188:191], v[124:127]
	v_mfma_f32_16x16x32_bf16 v[108:111], v[146:149], v[202:205], v[108:111]
	v_mfma_f32_16x16x32_bf16 v[104:107], v[154:157], v[202:205], v[104:107]
	v_mfma_f32_16x16x32_bf16 v[92:95], v[146:149], v[210:213], v[92:95]
	v_mfma_f32_16x16x32_bf16 v[88:91], v[154:157], v[210:213], v[88:91]
	v_mfma_f32_16x16x32_bf16 v[76:79], v[146:149], v[218:221], v[76:79]
	v_mfma_f32_16x16x32_bf16 v[72:75], v[154:157], v[218:221], v[72:75]
	v_mfma_f32_16x16x32_bf16 v[128:131], v[150:153], v[198:201], v[128:131]
	v_mfma_f32_16x16x32_bf16 v[124:127], v[158:161], v[198:201], v[124:127]
	v_mfma_f32_16x16x32_bf16 v[108:111], v[150:153], v[206:209], v[108:111]
	v_mfma_f32_16x16x32_bf16 v[104:107], v[158:161], v[206:209], v[104:107]
	v_mfma_f32_16x16x32_bf16 v[92:95], v[150:153], v[214:217], v[92:95]
	v_mfma_f32_16x16x32_bf16 v[88:91], v[158:161], v[214:217], v[88:91]
	v_mfma_f32_16x16x32_bf16 v[76:79], v[150:153], v[230:233], v[76:79]
	v_mfma_f32_16x16x32_bf16 v[72:75], v[158:161], v[230:233], v[72:75]
	v_mfma_f32_16x16x32_bf16 v[120:123], v[172:175], v[188:191], v[120:123]
	v_mfma_f32_16x16x32_bf16 v[116:119], v[180:183], v[188:191], v[116:119]
	v_mfma_f32_16x16x32_bf16 v[100:103], v[172:175], v[202:205], v[100:103]
	v_mfma_f32_16x16x32_bf16 v[96:99], v[180:183], v[202:205], v[96:99]
	v_mfma_f32_16x16x32_bf16 v[84:87], v[172:175], v[210:213], v[84:87]
	v_mfma_f32_16x16x32_bf16 v[80:83], v[180:183], v[210:213], v[80:83]
	v_mfma_f32_16x16x32_bf16 v[68:71], v[172:175], v[218:221], v[68:71]
	v_mfma_f32_16x16x32_bf16 v[64:67], v[180:183], v[218:221], v[64:67]
	v_mfma_f32_16x16x32_bf16 v[120:123], v[176:179], v[198:201], v[120:123]
	v_mfma_f32_16x16x32_bf16 v[116:119], v[184:187], v[198:201], v[116:119]
	v_mfma_f32_16x16x32_bf16 v[100:103], v[176:179], v[206:209], v[100:103]
	v_mfma_f32_16x16x32_bf16 v[96:99], v[184:187], v[206:209], v[96:99]
	v_mfma_f32_16x16x32_bf16 v[84:87], v[176:179], v[214:217], v[84:87]
	v_mfma_f32_16x16x32_bf16 v[80:83], v[184:187], v[214:217], v[80:83]
	v_mfma_f32_16x16x32_bf16 v[68:71], v[176:179], v[230:233], v[68:71]
	v_mfma_f32_16x16x32_bf16 v[64:67], v[184:187], v[230:233], v[64:67]
	s_barrier
; #define PG8_STAGE(bufoff, gbase, voff) do { _Pragma("unroll") for (int _i = 0; _i < 2; ++_i) \
;         __builtin_amdgcn_global_load_lds((const unsigned*)((const char*)(gbase) + (voff)[_i]), (LAS unsigned*)(lds + (bufoff) + ldsw + _i * 8192), 16, 0, 0); } while (0)
; #define PG8_LDA(dst, b, h) do { _Pragma("unroll") for (int m = 0; m < 4; ++m) _Pragma("unroll") for (int k = 0; k < 2; ++k) dst[m][k] = *(const LAS bf16x8*)(lds + PG8_SA(b, h) + aoff + m * 2048 + k * 1024); } while (0)
; #define PG8_MMA(ai, bj, At, Bt) do { __builtin_amdgcn_s_setprio(1); _Pragma("unroll") for (int m = 0; m < 4; ++m) _Pragma("unroll") for (int n = 0; n < 2; ++n) _Pragma("unroll") for (int k = 0; k < 2; ++k) \
;         acc[ai][bj][m][n] = __builtin_amdgcn_mfma_f32_16x16x32_bf16(Bt[n][k], At[m][k], acc[ai][bj][m][n], 0, 0, 0); __builtin_amdgcn_s_setprio(0); } while (0)
; #define PG8_WAIT_V(n) asm volatile("s_waitcnt vmcnt(" #n ")" ::: "memory")
; #define PG8_WAIT_L(n) asm volatile("s_waitcnt lgkmcnt(" #n ")" ::: "memory")
; #define PG8_BAR __builtin_amdgcn_s_barrier()
; #define PG8_SCHED __builtin_amdgcn_sched_barrier(0)
; template <class Epi, class Sched>
; __device__ __forceinline__ void gemm_phase(LAS unsigned char* lds, const Gemm g, const Sched& S, const Epi& E, const int tid) {
;     ...
;             PG8_LDA(At, 1, 1); PG8_STAGE(PG8_SB(1, 0), b3, voffB); PG8_STAGE(PG8_SB(1, 1), b3 + hstep, voffB); PG8_STAGE(PG8_SA(1, 0), a3, voffA);
;             PG8_WAIT_V(8); PG8_WAIT_L(0); PG8_BAR; PG8_MMA(1, 0, At, B0); PG8_MMA(1, 1, At, B1); PG8_BAR; PG8_SCHED;
;         }
;         if (wr == 0) PG8_BAR;
	s_add_i32 s63, s63, s74
	v_lshl_add_u64 v[162:163], v[162:163], 0, s[68:69]
	s_mov_b32 m0, s63
	ds_read_b128 v[188:191], v171 offset:49152
	ds_read_b128 v[198:201], v171 offset:50176
	ds_read_b128 v[202:205], v171 offset:51200
	ds_read_b128 v[206:209], v171 offset:52224
	ds_read_b128 v[210:213], v171 offset:53248
	ds_read_b128 v[214:217], v171 offset:54272
	ds_read_b128 v[218:221], v171 offset:55296
	ds_read_b128 v[230:233], v171 offset:56320
	global_load_lds_dwordx4 v[162:163], off
	s_add_i32 m0, s63, 0x2000
	s_add_u32 s66, s66, 0x40080
	v_lshl_add_u64 v[162:163], v[234:235], 0, s[68:69]
	s_addc_u32 s67, s67, 0
	s_add_i32 s63, s78, s74
	global_load_lds_dwordx4 v[162:163], off
	v_lshl_add_u64 v[162:163], s[66:67], 0, v[192:193]
	s_mov_b32 m0, s63
	s_nop 0
	global_load_lds_dwordx4 v[162:163], off
	v_lshl_add_u64 v[162:163], s[66:67], 0, v[134:135]
	s_add_i32 m0, s63, 0x2000
	s_nop 0
	global_load_lds_dwordx4 v[162:163], off
	v_lshl_add_u64 v[162:163], v[236:237], 0, s[68:69]
	s_mov_b32 m0, s93
	s_nop 0
	global_load_lds_dwordx4 v[162:163], off
	v_lshl_add_u64 v[162:163], v[238:239], 0, s[68:69]
	s_mov_b32 m0, s94
	s_nop 0
	global_load_lds_dwordx4 v[162:163], off
	s_waitcnt vmcnt(8)
	s_waitcnt lgkmcnt(0)
	s_barrier
	s_waitcnt lgkmcnt(0)
	v_mfma_f32_16x16x32_bf16 v[60:63], v[146:149], v[188:191], v[60:63]
	v_mfma_f32_16x16x32_bf16 v[56:59], v[154:157], v[188:191], v[56:59]
	v_mfma_f32_16x16x32_bf16 v[44:47], v[146:149], v[202:205], v[44:47]
	v_mfma_f32_16x16x32_bf16 v[40:43], v[154:157], v[202:205], v[40:43]
	v_mfma_f32_16x16x32_bf16 v[28:31], v[146:149], v[210:213], v[28:31]
	v_mfma_f32_16x16x32_bf16 v[24:27], v[154:157], v[210:213], v[24:27]
	v_mfma_f32_16x16x32_bf16 v[12:15], v[146:149], v[218:221], v[12:15]
	v_mfma_f32_16x16x32_bf16 v[8:11], v[154:157], v[218:221], v[8:11]
	v_mfma_f32_16x16x32_bf16 v[60:63], v[150:153], v[198:201], v[60:63]
	v_mfma_f32_16x16x32_bf16 v[56:59], v[158:161], v[198:201], v[56:59]
	v_mfma_f32_16x16x32_bf16 v[44:47], v[150:153], v[206:209], v[44:47]
	v_mfma_f32_16x16x32_bf16 v[40:43], v[158:161], v[206:209], v[40:43]
	v_mfma_f32_16x16x32_bf16 v[28:31], v[150:153], v[214:217], v[28:31]
	v_mfma_f32_16x16x32_bf16 v[24:27], v[158:161], v[214:217], v[24:27]
	v_mfma_f32_16x16x32_bf16 v[12:15], v[150:153], v[230:233], v[12:15]
	v_mfma_f32_16x16x32_bf16 v[8:11], v[158:161], v[230:233], v[8:11]
	v_mfma_f32_16x16x32_bf16 v[52:55], v[172:175], v[188:191], v[52:55]
	v_mfma_f32_16x16x32_bf16 v[48:51], v[180:183], v[188:191], v[48:51]
	v_mfma_f32_16x16x32_bf16 v[36:39], v[172:175], v[202:205], v[36:39]
	v_mfma_f32_16x16x32_bf16 v[32:35], v[180:183], v[202:205], v[32:35]
	v_mfma_f32_16x16x32_bf16 v[20:23], v[172:175], v[210:213], v[20:23]
	v_mfma_f32_16x16x32_bf16 v[16:19], v[180:183], v[210:213], v[16:19]
	v_mfma_f32_16x16x32_bf16 v[4:7], v[172:175], v[218:221], v[4:7]
	v_mfma_f32_16x16x32_bf16 v[0:3], v[180:183], v[218:221], v[0:3]
	v_mfma_f32_16x16x32_bf16 v[52:55], v[176:179], v[198:201], v[52:55]
	v_mfma_f32_16x16x32_bf16 v[48:51], v[184:187], v[198:201], v[48:51]
	v_mfma_f32_16x16x32_bf16 v[36:39], v[176:179], v[206:209], v[36:39]
	v_mfma_f32_16x16x32_bf16 v[32:35], v[184:187], v[206:209], v[32:35]
	v_mfma_f32_16x16x32_bf16 v[20:23], v[176:179], v[214:217], v[20:23]
	v_mfma_f32_16x16x32_bf16 v[16:19], v[184:187], v[214:217], v[16:19]
	v_mfma_f32_16x16x32_bf16 v[4:7], v[176:179], v[230:233], v[4:7]
	v_mfma_f32_16x16x32_bf16 v[0:3], v[184:187], v[230:233], v[0:3]
	s_barrier
	s_add_i32 s61, s61, 2
	s_add_u32 s64, s64, 0x100
	s_addc_u32 s65, s65, 0
	s_add_u32 s59, s59, 0x100
	s_addc_u32 s60, s60, 0
	s_cmp_gt_u32 s61, 13
	s_cbranch_scc0 .LBB0_168
	s_and_b64 vcc, exec, s[50:51]
	s_cbranch_vccz .LBB0_171
	s_barrier

; #define PG8_WAIT_V(n) asm volatile("s_waitcnt vmcnt(" #n ")" ::: "memory")
; #define PG8_BAR __builtin_amdgcn_s_barrier()
; template <class Epi, class Sched>
; __device__ __forceinline__ void gemm_phase(LAS unsigned char* lds, const Gemm g, const Sched& S, const Epi& E, const int tid) {
;     ...
;     PG8_WAIT_V(0);
;     PG8_BAR;
.LBB0_176:
	s_setprio 0
	s_waitcnt vmcnt(0)
	v_readlane_b32 s64, v254, 46
	v_readlane_b32 s65, v254, 47
	s_barrier
	v_readlane_b32 s12, v254, 48

; #define PG8_STAGE(bufoff, gbase, voff) do { _Pragma("unroll") for (int _i = 0; _i < 2; ++_i) \
;         __builtin_amdgcn_global_load_lds((const unsigned*)((const char*)(gbase) + (voff)[_i]), (LAS unsigned*)(lds + (bufoff) + ldsw + _i * 8192), 16, 0, 0); } while (0)
; #define PG8_BAR __builtin_amdgcn_s_barrier()
; template <class Epi, class Sched>
; __device__ __forceinline__ void gemm_phase(LAS unsigned char* lds, const Gemm g, const Sched& S, const Epi& E, const int tid) {
;     const int wid = __builtin_amdgcn_readfirstlane(tid >> 6), lane = tid & 63, wr = wid >> 2, wc = wid & 3, fr = lane & 15, fq = lane >> 4;
;     const int K = g.K, nt = K / BK;
;     unsigned voffA[2], voffB[2];
; #pragma unroll
;     for (int i = 0; i < 2; ++i) { int R, C; stage_rc(tid * 16 + i * 8192, R, C); const int Rb = Epi::PERM ? ((R & ~31) + perm32(R & 31)) : R;
;         voffA[i] = (unsigned)(R * K + C) * 2u; voffB[i] = (unsigned)(Rb * K + C) * 2u; }
;     const size_t kstep = (size_t)(BK * 2);
;     const size_t hstep = (size_t)HALF * K * 2;
;     const size_t tstep = 2 * hstep;
;     const unsigned ldsw = (unsigned)wid * 1024u;
;     const int aoff = lds_byte(wr * 64 + fr, fq * 8), boff = lds_byte(wc * 32 + fr, fq * 8);
;     ...
;     Unit cur, nxt; int ui = 0;
;     if (!S.next(0, cur)) return;
;     f32x4 acc[2][2][4][2];
; #pragma unroll
;     for (int a = 0; a < 2; ++a)
; #pragma unroll
;         for (int b = 0; b < 2; ++b)
; #pragma unroll
;             for (int m = 0; m < 4; ++m)
; #pragma unroll
;                 for (int n = 0; n < 2; ++n) acc[a][b][m][n] = (f32x4){0.f, 0.f, 0.f, 0.f};
;     bf16x8 At[4][2], B0[2][2], B1[2][2];
;     const char* cA = (const char*)g.A + (size_t)cur.pm * tstep; const char* cB = (const char*)g.Bt + (size_t)cur.pn * tstep;
;     PG8_STAGE(PG8_SB(0, 0), cB, voffB); PG8_STAGE(PG8_SB(0, 1), cB + hstep, voffB); PG8_STAGE(PG8_SA(0, 0), cA, voffA); PG8_STAGE(PG8_SA(0, 1), cA + hstep, voffA);
;     if (wr == 1) PG8_BAR;
.LBB0_249:
	s_and_b64 vcc, exec, s[0:1]
	s_cbranch_vccz .LBB0_542
	s_and_b64 vcc, exec, s[8:9]
	s_cbranch_vccnz .LBB0_335
	v_mov_b32_e32 v160, v223
	s_waitcnt vmcnt(0)
	v_mov_b32_e32 v6, 1
	s_waitcnt lgkmcnt(5)
	v_ashrrev_i32_e32 v161, 31, v160
	s_waitcnt lgkmcnt(0)
	v_lshrrev_b32_e32 v1, 26, v161
	v_add_u32_e32 v1, v160, v1
	s_waitcnt lgkmcnt(0)
	v_ashrrev_i32_e32 v171, 6, v1
	v_bfe_i32 v1, v160, 27, 1
	v_lshlrev_b32_e32 v0, 4, v160
	v_lshrrev_b32_e32 v1, 22, v1
	v_add_u32_e32 v1, v0, v1
	v_and_b32_e32 v1, 0xfffffc00, v1
	v_sub_u32_e32 v1, v0, v1
	v_lshrrev_b32_e32 v2, 4, v1
	v_bitop3_b32 v1, v2, v1, 32 bitop3:0x6c
	v_ashrrev_i32_e32 v3, 31, v1
	v_lshrrev_b32_e32 v3, 26, v3
	v_add_u32_e32 v3, v1, v3
	v_lshlrev_b32_e32 v2, 3, v171
	v_ashrrev_i32_e32 v173, 6, v3
	v_and_b32_e32 v3, 0xc0, v3
	v_and_b32_e32 v2, -16, v2
	v_sub_u32_e32 v1, v1, v3
	v_add_u32_e32 v2, v173, v2
	v_ashrrev_i16_sdwa v1, v6, sext(v1) dst_sel:DWORD dst_unused:UNUSED_PAD src0_sel:DWORD src1_sel:BYTE_0
	v_lshlrev_b32_e32 v4, 5, v171
	v_bfe_i32 v210, v1, 0, 16
	v_lshlrev_b32_e32 v1, 1, v2
	v_lshrrev_b32_e32 v3, 2, v2
	v_and_b32_e32 v5, 3, v173
	s_mov_b32 s0, 0x1fffe0
	v_and_b32_e32 v4, 32, v4
	v_and_b32_e32 v1, 24, v1
	v_and_b32_e32 v3, 4, v3
	v_and_or_b32 v5, v2, s0, v5
	v_or3_b32 v1, v5, v3, v1
	v_add_lshl_u32 v3, v4, v210, 1
	v_add_u32_e32 v0, 0x2000, v0
	v_lshl_add_u32 v164, v1, 11, v3
	v_ashrrev_i32_e32 v1, 31, v0
	v_lshrrev_b32_e32 v1, 22, v1
	v_add_u32_e32 v1, v0, v1
	v_ashrrev_i32_e32 v211, 10, v1
	v_mul_i32_i24_e32 v1, 0x400, v211
	v_sub_u32_e32 v0, v0, v1
	v_lshrrev_b32_e32 v1, 4, v0
	v_bitop3_b32 v0, v1, v0, 32 bitop3:0x6c
	v_lshl_add_u32 v162, v2, 11, v3
	v_ashrrev_i32_e32 v2, 31, v0
	v_lshrrev_b32_e32 v2, 26, v2
	v_add_u32_e32 v2, v0, v2
	v_lshlrev_b32_e32 v1, 3, v211
	v_ashrrev_i32_e32 v212, 6, v2
	v_and_b32_e32 v2, 0xc0, v2
	v_and_b32_e32 v1, -16, v1
	v_sub_u32_e32 v0, v0, v2
	v_add_u32_e32 v1, v212, v1
	v_ashrrev_i16_sdwa v0, v6, sext(v0) dst_sel:DWORD dst_unused:UNUSED_PAD src0_sel:DWORD src1_sel:BYTE_0
	v_lshlrev_b32_e32 v3, 5, v211
	v_bfe_i32 v213, v0, 0, 16
	v_lshlrev_b32_e32 v0, 1, v1
	v_lshrrev_b32_e32 v2, 2, v1
	v_and_b32_e32 v4, 3, v212
	v_and_b32_e32 v3, 32, v3
	v_and_b32_e32 v0, 24, v0
	v_and_b32_e32 v2, 4, v2
	v_and_or_b32 v4, v1, s0, v4
	v_or3_b32 v0, v4, v2, v0
	v_add_lshl_u32 v2, v3, v213, 1
	v_readlane_b32 s0, v253, 46
	v_lshl_add_u32 v168, v0, 11, v2
	v_and_b32_e32 v214, 15, v160
	v_lshlrev_b32_e32 v0, 2, v160
	v_readlane_b32 s1, v253, 47
	v_readfirstlane_b32 s4, v160
	v_lshl_add_u32 v166, v1, 11, v2
	v_lshlrev_b32_e32 v170, 6, v214
	s_andn2_b64 vcc, exec, s[0:1]
	v_and_b32_e32 v215, 32, v0
	s_cbranch_vccnz .LBB0_311
	s_ashr_i32 s5, s4, 6
	s_lshl_b32 s12, s5, 10
	s_add_i32 s73, s12, 0
	v_readlane_b32 s0, v255, 5
	s_add_i32 m0, s73, 0x10000
	v_readlane_b32 s1, v255, 6
	s_add_i32 s74, s73, 0x2000
	s_add_i32 s75, s73, 0x4000
	s_add_i32 s81, s73, 0x6000
	s_ashr_i32 s6, s4, 8
	s_nop 0
	global_load_lds_dwordx4 v164, s[0:1]
	s_add_i32 m0, s73, 0x12000
	s_nop 0
	global_load_lds_dwordx4 v168, s[0:1]
	v_readlane_b32 s0, v255, 3
	s_add_i32 m0, s73, 0x14000
	v_readlane_b32 s1, v255, 4
	s_nop 4
	global_load_lds_dwordx4 v164, s[0:1]
	s_add_i32 m0, s73, 0x16000
	s_cmp_eq_u32 s6, 1
	global_load_lds_dwordx4 v168, s[0:1]
	v_readlane_b32 s0, v254, 22
	s_mov_b32 m0, s73
	v_readlane_b32 s1, v254, 23
	s_nop 4
	global_load_lds_dwordx4 v162, s[0:1]
	s_mov_b32 m0, s74
	s_nop 0
	global_load_lds_dwordx4 v166, s[0:1]
	v_readlane_b32 s0, v254, 24
	s_mov_b32 m0, s75
	v_readlane_b32 s1, v254, 25
	s_nop 4
	global_load_lds_dwordx4 v162, s[0:1]
	s_mov_b32 m0, s81
	s_nop 0
	global_load_lds_dwordx4 v166, s[0:1]
	s_cselect_b64 s[0:1], -1, 0
	s_cmp_lg_u32 s6, 1
	s_cbranch_scc1 .LBB0_254
	s_barrier
	s_setprio 1

;     __device__ __forceinline__ Pre prefetch(const Unit& u, int tid) const { return prenorm_load(stats, u.pn * BM, sW + (size_t)(u.pn >> 4) * SW_ROWS + u.pm * BM, tid); }
;     __device__ __forceinline__ Pre prefetch(const Unit& u, int tid) const { return prenorm_load(stats, u.pm * BM, sW + (size_t)(u.pm >> 4) * SW_ROWS + u.pn * BM, tid); }
;     __device__ __forceinline__ Pre prefetch(const Unit& u, int tid) const { return prenorm_load(stats, u.pm * BM, sW + (size_t)(u.pm >> 4) * SW_ROWS + u.pn * BM, tid); }
; #define PG8_STAGE(bufoff, gbase, voff) do { _Pragma("unroll") for (int _i = 0; _i < 2; ++_i) \
;         __builtin_amdgcn_global_load_lds((const unsigned*)((const char*)(gbase) + (voff)[_i]), (LAS unsigned*)(lds + (bufoff) + ldsw + _i * 8192), 16, 0, 0); } while (0)
; #define PG8_LDA(dst, b, h) do { _Pragma("unroll") for (int m = 0; m < 4; ++m) _Pragma("unroll") for (int k = 0; k < 2; ++k) dst[m][k] = *(const LAS bf16x8*)(lds + PG8_SA(b, h) + aoff + m * 2048 + k * 1024); } while (0)
; #define PG8_LDB(dst, b, h) do { _Pragma("unroll") for (int n = 0; n < 2; ++n) _Pragma("unroll") for (int k = 0; k < 2; ++k) dst[n][k] = *(const LAS bf16x8*)(lds + PG8_SB(b, h) + boff + n * 2048 + k * 1024); } while (0)
; #define PG8_WAIT_V(n) asm volatile("s_waitcnt vmcnt(" #n ")" ::: "memory")
; template <class Epi, class Sched>
; __device__ __forceinline__ void gemm_phase(LAS unsigned char* lds, const Gemm g, const Sched& S, const Epi& E, const int tid) {
;     ...
;     for (;;) {
;         const bool has_next = S.next(ui + 1, nxt);
;         const char* nA = has_next ? (const char*)g.A + (size_t)nxt.pm * tstep : cA; const char* nB = has_next ? (const char*)g.Bt + (size_t)nxt.pn * tstep : cB;
;         const typename Epi::Pre pre = E.prefetch(cur, tid);
;         for (int t = 0; t < nt; t += 2) {
;             const bool last = (t == nt - 2);
;             const char* a1 = cA + (size_t)(t + 1) * kstep;
;             const char* a2 = last ? nA : cA + (size_t)(t + 2) * kstep; const char* b2 = last ? nB : cB + (size_t)(t + 2) * kstep;
;             const char* a3 = a2 + kstep; const char* b3 = b2 + kstep;
;             PG8_LDB(B0, 0, 0); PG8_LDB(B1, 0, 1); PG8_SCHED; PG8_LDA(At, 0, 0); PG8_STAGE(PG8_SA(1, 1), a1 + hstep, voffA);
;             PG8_WAIT_V(8); PG8_WAIT_L(0); PG8_BAR; PG8_MMA(0, 0, At, B0); PG8_MMA(0, 1, At, B1); PG8_BAR; PG8_SCHED;
.LBB0_265:
	s_or_b64 exec, exec, s[38:39]
	s_ashr_i32 s23, s22, 31
	s_lshl_b64 s[38:39], s[22:23], 19
	s_add_u32 s38, s46, s38
	s_addc_u32 s39, s47, s39
	s_and_b64 s[56:57], s[4:5], exec
	s_cselect_b32 s23, s39, s7
	s_cselect_b32 s56, s38, s6
	s_ashr_i32 s55, s54, 31
	s_lshl_b64 s[58:59], s[54:55], 19
	s_add_u32 s62, s35, s58
	s_addc_u32 s63, s84, s59
	s_and_b64 s[58:59], s[4:5], exec
	s_cselect_b32 s55, s63, s65
	s_cselect_b32 s57, s62, s64
	s_add_u32 s6, s6, 0x40080
	s_addc_u32 s7, s7, 0
	s_add_u32 s58, s64, 0x100
	s_addc_u32 s59, s65, 0
	s_mov_b32 s60, -2
	s_add_u32 s61, s6, 0xfffc0080
	s_addc_u32 s64, s7, -1
	s_add_i32 s70, 0, 0x10000
	s_cmp_eq_u32 s60, 12
	s_cselect_b32 s67, s23, s64
	s_cselect_b32 s66, s56, s61
	v_add_u32_e32 v81, s70, v216
	s_cselect_b32 s65, s55, s59
	s_cselect_b32 s64, s57, s58
	s_add_i32 s61, 0, 0x14000
	ds_read_b128 v[88:91], v81
	ds_read_b128 v[92:95], v81 offset:1024
	ds_read_b128 v[144:147], v81 offset:2048
	ds_read_b128 v[148:151], v81 offset:3072
	v_add_u32_e32 v81, s61, v216
	ds_read_b128 v[152:155], v81
	ds_read_b128 v[156:159], v81 offset:1024
	ds_read_b128 v[178:181], v81 offset:2048
	ds_read_b128 v[182:185], v81 offset:3072
	v_lshl_add_u64 v[82:83], s[6:7], 0, v[174:175]
	s_add_i32 m0, s73, 0xc000
	ds_read_b128 v[186:189], v230
	ds_read_b128 v[198:201], v230 offset:1024
	ds_read_b128 v[202:205], v230 offset:2048
	ds_read_b128 v[206:209], v230 offset:3072
	ds_read_b128 v[234:237], v230 offset:4096
	ds_read_b128 v[238:241], v230 offset:5120
	ds_read_b128 v[242:245], v230 offset:6144
	ds_read_b128 v[246:249], v230 offset:7168
	global_load_lds_dwordx4 v[82:83], off
	v_lshl_add_u64 v[82:83], s[6:7], 0, v[176:177]
	s_add_i32 m0, s73, 0xe000
	s_nop 0
	global_load_lds_dwordx4 v[82:83], off
	s_waitcnt vmcnt(8)
	s_waitcnt lgkmcnt(0)
	s_barrier
	s_waitcnt lgkmcnt(0)
	v_mfma_f32_16x16x32_bf16 v[140:143], v[88:91], v[186:189], 0
	v_mfma_f32_16x16x32_bf16 v[136:139], v[144:147], v[186:189], 0
	v_mfma_f32_16x16x32_bf16 v[124:127], v[88:91], v[202:205], 0
	v_mfma_f32_16x16x32_bf16 v[120:123], v[144:147], v[202:205], 0
	v_mfma_f32_16x16x32_bf16 v[108:111], v[88:91], v[234:237], 0
	v_mfma_f32_16x16x32_bf16 v[104:107], v[144:147], v[234:237], 0
	v_mfma_f32_16x16x32_bf16 v[82:85], v[88:91], v[242:245], 0
	v_mfma_f32_16x16x32_bf16 v[76:79], v[144:147], v[242:245], 0
	v_mfma_f32_16x16x32_bf16 v[140:143], v[92:95], v[198:201], v[140:143]
	v_mfma_f32_16x16x32_bf16 v[136:139], v[148:151], v[198:201], v[136:139]
	v_mfma_f32_16x16x32_bf16 v[124:127], v[92:95], v[206:209], v[124:127]
	v_mfma_f32_16x16x32_bf16 v[120:123], v[148:151], v[206:209], v[120:123]
	v_mfma_f32_16x16x32_bf16 v[108:111], v[92:95], v[238:241], v[108:111]
	v_mfma_f32_16x16x32_bf16 v[104:107], v[148:151], v[238:241], v[104:107]
	v_mfma_f32_16x16x32_bf16 v[82:85], v[92:95], v[246:249], v[82:85]
	v_mfma_f32_16x16x32_bf16 v[76:79], v[148:151], v[246:249], v[76:79]
	v_mfma_f32_16x16x32_bf16 v[132:135], v[152:155], v[186:189], 0
	v_mfma_f32_16x16x32_bf16 v[128:131], v[178:181], v[186:189], 0
	v_mfma_f32_16x16x32_bf16 v[116:119], v[152:155], v[202:205], 0
	v_mfma_f32_16x16x32_bf16 v[112:115], v[178:181], v[202:205], 0
	v_mfma_f32_16x16x32_bf16 v[100:103], v[152:155], v[234:237], 0
	v_mfma_f32_16x16x32_bf16 v[96:99], v[178:181], v[234:237], 0
	v_mfma_f32_16x16x32_bf16 v[68:71], v[152:155], v[242:245], 0
	v_mfma_f32_16x16x32_bf16 v[64:67], v[178:181], v[242:245], 0
	v_mfma_f32_16x16x32_bf16 v[132:135], v[156:159], v[198:201], v[132:135]
	v_mfma_f32_16x16x32_bf16 v[128:131], v[182:185], v[198:201], v[128:131]
	v_mfma_f32_16x16x32_bf16 v[116:119], v[156:159], v[206:209], v[116:119]
	v_mfma_f32_16x16x32_bf16 v[112:115], v[182:185], v[206:209], v[112:115]
	v_mfma_f32_16x16x32_bf16 v[100:103], v[156:159], v[238:241], v[100:103]
	v_mfma_f32_16x16x32_bf16 v[96:99], v[182:185], v[238:241], v[96:99]
	v_mfma_f32_16x16x32_bf16 v[68:71], v[156:159], v[246:249], v[68:71]
	v_mfma_f32_16x16x32_bf16 v[64:67], v[182:185], v[246:249], v[64:67]
	s_barrier
	s_add_i32 s70, s70, s12
	v_lshl_add_u64 v[190:191], s[64:65], 0, v[164:165]
	s_mov_b32 m0, s70
	ds_read_b128 v[186:189], v230 offset:16384
	ds_read_b128 v[198:201], v230 offset:17408
	ds_read_b128 v[202:205], v230 offset:18432
	ds_read_b128 v[206:209], v230 offset:19456
	ds_read_b128 v[234:237], v230 offset:20480
	ds_read_b128 v[238:241], v230 offset:21504
	ds_read_b128 v[242:245], v230 offset:22528
	ds_read_b128 v[246:249], v230 offset:23552
	global_load_lds_dwordx4 v[190:191], off
	s_add_i32 m0, s70, 0x2000
	s_add_u32 s70, s64, 0x40000
	v_lshl_add_u64 v[250:251], s[64:65], 0, v[168:169]
	s_addc_u32 s71, s65, 0
	s_add_i32 s61, s61, s12
	global_load_lds_dwordx4 v[250:251], off
	v_lshl_add_u64 v[86:87], s[70:71], 0, v[164:165]
	s_mov_b32 m0, s61
	v_lshl_add_u64 v[224:225], s[66:67], 0, v[162:163]
	global_load_lds_dwordx4 v[86:87], off
	v_lshl_add_u64 v[86:87], s[70:71], 0, v[168:169]
	s_add_i32 m0, s61, 0x2000
	v_lshl_add_u64 v[226:227], s[66:67], 0, v[166:167]
	global_load_lds_dwordx4 v[86:87], off
	s_mov_b32 m0, s73
	s_nop 0
	global_load_lds_dwordx4 v[224:225], off
	s_mov_b32 m0, s74
	s_nop 0
	global_load_lds_dwordx4 v[226:227], off
	s_waitcnt vmcnt(8)
	s_waitcnt lgkmcnt(0)
	s_barrier
; #define PG8_STAGE(bufoff, gbase, voff) do { _Pragma("unroll") for (int _i = 0; _i < 2; ++_i) \
;         __builtin_amdgcn_global_load_lds((const unsigned*)((const char*)(gbase) + (voff)[_i]), (LAS unsigned*)(lds + (bufoff) + ldsw + _i * 8192), 16, 0, 0); } while (0)
; #define PG8_LDA(dst, b, h) do { _Pragma("unroll") for (int m = 0; m < 4; ++m) _Pragma("unroll") for (int k = 0; k < 2; ++k) dst[m][k] = *(const LAS bf16x8*)(lds + PG8_SA(b, h) + aoff + m * 2048 + k * 1024); } while (0)
; #define PG8_LDB(dst, b, h) do { _Pragma("unroll") for (int n = 0; n < 2; ++n) _Pragma("unroll") for (int k = 0; k < 2; ++k) dst[n][k] = *(const LAS bf16x8*)(lds + PG8_SB(b, h) + boff + n * 2048 + k * 1024); } while (0)
; #define PG8_MMA(ai, bj, At, Bt) do { __builtin_amdgcn_s_setprio(1); _Pragma("unroll") for (int m = 0; m < 4; ++m) _Pragma("unroll") for (int n = 0; n < 2; ++n) _Pragma("unroll") for (int k = 0; k < 2; ++k) \
;         acc[ai][bj][m][n] = __builtin_amdgcn_mfma_f32_16x16x32_bf16(Bt[n][k], At[m][k], acc[ai][bj][m][n], 0, 0, 0); __builtin_amdgcn_s_setprio(0); } while (0)
; #define PG8_WAIT_V(n) asm volatile("s_waitcnt vmcnt(" #n ")" ::: "memory")
; #define PG8_WAIT_L(n) asm volatile("s_waitcnt lgkmcnt(" #n ")" ::: "memory")
; #define PG8_BAR __builtin_amdgcn_s_barrier()
; #define PG8_SCHED __builtin_amdgcn_sched_barrier(0)
; template <class Epi, class Sched>
; __device__ __forceinline__ void gemm_phase(LAS unsigned char* lds, const Gemm g, const Sched& S, const Epi& E, const int tid) {
;     ...
;             PG8_WAIT_V(8); PG8_WAIT_L(0); PG8_BAR; PG8_MMA(0, 0, At, B0); PG8_MMA(0, 1, At, B1); PG8_BAR; PG8_SCHED;
;             PG8_LDA(At, 0, 1); PG8_STAGE(PG8_SB(0, 0), b2, voffB); PG8_STAGE(PG8_SB(0, 1), b2 + hstep, voffB); PG8_STAGE(PG8_SA(0, 0), a2, voffA);
;             PG8_WAIT_V(8); PG8_WAIT_L(0); PG8_BAR; PG8_MMA(1, 0, At, B0); PG8_MMA(1, 1, At, B1); PG8_BAR; PG8_SCHED;
;             PG8_LDB(B0, 1, 0); PG8_LDB(B1, 1, 1); PG8_SCHED; PG8_LDA(At, 1, 0); PG8_STAGE(PG8_SA(0, 1), a2 + hstep, voffA);
;             PG8_WAIT_V(8); PG8_WAIT_L(0); PG8_BAR; PG8_MMA(0, 0, At, B0); PG8_MMA(0, 1, At, B1); PG8_BAR; PG8_SCHED;
	s_waitcnt lgkmcnt(0)
	v_mfma_f32_16x16x32_bf16 v[60:63], v[88:91], v[186:189], 0
	v_mfma_f32_16x16x32_bf16 v[56:59], v[144:147], v[186:189], 0
	v_mfma_f32_16x16x32_bf16 v[44:47], v[88:91], v[202:205], 0
	v_mfma_f32_16x16x32_bf16 v[40:43], v[144:147], v[202:205], 0
	v_mfma_f32_16x16x32_bf16 v[28:31], v[88:91], v[234:237], 0
	v_mfma_f32_16x16x32_bf16 v[24:27], v[144:147], v[234:237], 0
	v_mfma_f32_16x16x32_bf16 v[12:15], v[88:91], v[242:245], 0
	v_mfma_f32_16x16x32_bf16 v[8:11], v[144:147], v[242:245], 0
	v_mfma_f32_16x16x32_bf16 v[60:63], v[92:95], v[198:201], v[60:63]
	v_mfma_f32_16x16x32_bf16 v[56:59], v[148:151], v[198:201], v[56:59]
	v_mfma_f32_16x16x32_bf16 v[44:47], v[92:95], v[206:209], v[44:47]
	v_mfma_f32_16x16x32_bf16 v[40:43], v[148:151], v[206:209], v[40:43]
	v_mfma_f32_16x16x32_bf16 v[28:31], v[92:95], v[238:241], v[28:31]
	v_mfma_f32_16x16x32_bf16 v[24:27], v[148:151], v[238:241], v[24:27]
	v_mfma_f32_16x16x32_bf16 v[12:15], v[92:95], v[246:249], v[12:15]
	v_mfma_f32_16x16x32_bf16 v[8:11], v[148:151], v[246:249], v[8:11]
	v_mfma_f32_16x16x32_bf16 v[52:55], v[152:155], v[186:189], 0
	v_mfma_f32_16x16x32_bf16 v[48:51], v[178:181], v[186:189], 0
	v_mfma_f32_16x16x32_bf16 v[36:39], v[152:155], v[202:205], 0
	v_mfma_f32_16x16x32_bf16 v[32:35], v[178:181], v[202:205], 0
	v_mfma_f32_16x16x32_bf16 v[20:23], v[152:155], v[234:237], 0
	v_mfma_f32_16x16x32_bf16 v[16:19], v[178:181], v[234:237], 0
	v_mfma_f32_16x16x32_bf16 v[4:7], v[152:155], v[242:245], 0
	v_mfma_f32_16x16x32_bf16 v[0:3], v[178:181], v[242:245], 0
	v_mfma_f32_16x16x32_bf16 v[52:55], v[156:159], v[198:201], v[52:55]
	v_mfma_f32_16x16x32_bf16 v[48:51], v[182:185], v[198:201], v[48:51]
	v_mfma_f32_16x16x32_bf16 v[36:39], v[156:159], v[206:209], v[36:39]
	v_mfma_f32_16x16x32_bf16 v[32:35], v[182:185], v[206:209], v[32:35]
	v_mfma_f32_16x16x32_bf16 v[20:23], v[156:159], v[238:241], v[20:23]
	v_mfma_f32_16x16x32_bf16 v[16:19], v[182:185], v[238:241], v[16:19]
	v_mfma_f32_16x16x32_bf16 v[4:7], v[156:159], v[246:249], v[4:7]
	v_mfma_f32_16x16x32_bf16 v[0:3], v[182:185], v[246:249], v[0:3]
	s_barrier
	s_add_i32 s61, 0, 0x18000
	v_add_u32_e32 v81, s61, v216
	s_add_i32 s70, 0, 0x1c000
	ds_read_b128 v[88:91], v81
	ds_read_b128 v[92:95], v81 offset:1024
	ds_read_b128 v[144:147], v81 offset:2048
	ds_read_b128 v[148:151], v81 offset:3072
	v_add_u32_e32 v81, s70, v216
	ds_read_b128 v[152:155], v81
	ds_read_b128 v[156:159], v81 offset:1024
	ds_read_b128 v[178:181], v81 offset:2048
	ds_read_b128 v[182:185], v81 offset:3072
	s_add_u32 s66, s66, 0x40000
	s_addc_u32 s67, s67, 0
	s_mov_b32 m0, s75
	v_lshl_add_u64 v[86:87], s[66:67], 0, v[162:163]
	ds_read_b128 v[186:189], v230 offset:32768
	ds_read_b128 v[198:201], v230 offset:33792
	ds_read_b128 v[202:205], v230 offset:34816
	ds_read_b128 v[206:209], v230 offset:35840
	ds_read_b128 v[234:237], v230 offset:36864
	ds_read_b128 v[238:241], v230 offset:37888
	ds_read_b128 v[242:245], v230 offset:38912
	ds_read_b128 v[246:249], v230 offset:39936
	global_load_lds_dwordx4 v[86:87], off
	v_lshl_add_u64 v[86:87], s[66:67], 0, v[166:167]
	s_mov_b32 m0, s81
	s_nop 0
	global_load_lds_dwordx4 v[86:87], off
	s_waitcnt vmcnt(8)
	s_waitcnt lgkmcnt(0)
	s_barrier
	s_waitcnt lgkmcnt(0)
	v_mfma_f32_16x16x32_bf16 v[140:143], v[88:91], v[186:189], v[140:143]
	v_mfma_f32_16x16x32_bf16 v[136:139], v[144:147], v[186:189], v[136:139]
	v_mfma_f32_16x16x32_bf16 v[124:127], v[88:91], v[202:205], v[124:127]
	v_mfma_f32_16x16x32_bf16 v[120:123], v[144:147], v[202:205], v[120:123]
	v_mfma_f32_16x16x32_bf16 v[108:111], v[88:91], v[234:237], v[108:111]
	v_mfma_f32_16x16x32_bf16 v[104:107], v[144:147], v[234:237], v[104:107]
	v_mfma_f32_16x16x32_bf16 v[82:85], v[88:91], v[242:245], v[82:85]
	v_mfma_f32_16x16x32_bf16 v[76:79], v[144:147], v[242:245], v[76:79]
	v_mfma_f32_16x16x32_bf16 v[140:143], v[92:95], v[198:201], v[140:143]
	v_mfma_f32_16x16x32_bf16 v[136:139], v[148:151], v[198:201], v[136:139]
	v_mfma_f32_16x16x32_bf16 v[124:127], v[92:95], v[206:209], v[124:127]
	v_mfma_f32_16x16x32_bf16 v[120:123], v[148:151], v[206:209], v[120:123]
	v_mfma_f32_16x16x32_bf16 v[108:111], v[92:95], v[238:241], v[108:111]
	v_mfma_f32_16x16x32_bf16 v[104:107], v[148:151], v[238:241], v[104:107]
	v_mfma_f32_16x16x32_bf16 v[84:87], v[92:95], v[246:249], v[82:85]
	v_mfma_f32_16x16x32_bf16 v[76:79], v[148:151], v[246:249], v[76:79]
	v_mfma_f32_16x16x32_bf16 v[132:135], v[152:155], v[186:189], v[132:135]
	v_mfma_f32_16x16x32_bf16 v[128:131], v[178:181], v[186:189], v[128:131]
	v_mfma_f32_16x16x32_bf16 v[116:119], v[152:155], v[202:205], v[116:119]
	v_mfma_f32_16x16x32_bf16 v[112:115], v[178:181], v[202:205], v[112:115]
	v_mfma_f32_16x16x32_bf16 v[100:103], v[152:155], v[234:237], v[100:103]
	v_mfma_f32_16x16x32_bf16 v[96:99], v[178:181], v[234:237], v[96:99]
	v_mfma_f32_16x16x32_bf16 v[68:71], v[152:155], v[242:245], v[68:71]
	v_mfma_f32_16x16x32_bf16 v[64:67], v[178:181], v[242:245], v[64:67]
	v_mfma_f32_16x16x32_bf16 v[132:135], v[156:159], v[198:201], v[132:135]
	v_mfma_f32_16x16x32_bf16 v[128:131], v[182:185], v[198:201], v[128:131]
	v_mfma_f32_16x16x32_bf16 v[116:119], v[156:159], v[206:209], v[116:119]
	v_mfma_f32_16x16x32_bf16 v[112:115], v[182:185], v[206:209], v[112:115]
	v_mfma_f32_16x16x32_bf16 v[100:103], v[156:159], v[238:241], v[100:103]
	v_mfma_f32_16x16x32_bf16 v[96:99], v[182:185], v[238:241], v[96:99]
	v_mfma_f32_16x16x32_bf16 v[68:71], v[156:159], v[246:249], v[68:71]
	v_mfma_f32_16x16x32_bf16 v[64:67], v[182:185], v[246:249], v[64:67]
	s_barrier
; #define PG8_STAGE(bufoff, gbase, voff) do { _Pragma("unroll") for (int _i = 0; _i < 2; ++_i) \
;         __builtin_amdgcn_global_load_lds((const unsigned*)((const char*)(gbase) + (voff)[_i]), (LAS unsigned*)(lds + (bufoff) + ldsw + _i * 8192), 16, 0, 0); } while (0)
; #define PG8_LDA(dst, b, h) do { _Pragma("unroll") for (int m = 0; m < 4; ++m) _Pragma("unroll") for (int k = 0; k < 2; ++k) dst[m][k] = *(const LAS bf16x8*)(lds + PG8_SA(b, h) + aoff + m * 2048 + k * 1024); } while (0)
; #define PG8_LDB(dst, b, h) do { _Pragma("unroll") for (int n = 0; n < 2; ++n) _Pragma("unroll") for (int k = 0; k < 2; ++k) dst[n][k] = *(const LAS bf16x8*)(lds + PG8_SB(b, h) + boff + n * 2048 + k * 1024); } while (0)
; #define PG8_WAIT_V(n) asm volatile("s_waitcnt vmcnt(" #n ")" ::: "memory")
; #define PG8_BAR __builtin_amdgcn_s_barrier()
; template <class Epi, class Sched>
; __device__ __forceinline__ void gemm_phase(LAS unsigned char* lds, const Gemm g, const Sched& S, const Epi& E, const int tid) {
;     ...
;         for (int t = 0; t < nt; t += 2) {
;             const bool last = (t == nt - 2);
;             const char* a1 = cA + (size_t)(t + 1) * kstep;
;             const char* a2 = last ? nA : cA + (size_t)(t + 2) * kstep; const char* b2 = last ? nB : cB + (size_t)(t + 2) * kstep;
;             const char* a3 = a2 + kstep; const char* b3 = b2 + kstep;
;             PG8_LDB(B0, 0, 0); PG8_LDB(B1, 0, 1); PG8_SCHED; PG8_LDA(At, 0, 0); PG8_STAGE(PG8_SA(1, 1), a1 + hstep, voffA);
;             PG8_WAIT_V(8); PG8_WAIT_L(0); PG8_BAR; PG8_MMA(0, 0, At, B0); PG8_MMA(0, 1, At, B1); PG8_BAR; PG8_SCHED;
;             PG8_LDA(At, 0, 1); PG8_STAGE(PG8_SB(0, 0), b2, voffB); PG8_STAGE(PG8_SB(0, 1), b2 + hstep, voffB); PG8_STAGE(PG8_SA(0, 0), a2, voffA);
;             PG8_WAIT_V(8); PG8_WAIT_L(0); PG8_BAR; PG8_MMA(1, 0, At, B0); PG8_MMA(1, 1, At, B1); PG8_BAR; PG8_SCHED;
;             PG8_LDB(B0, 1, 0); PG8_LDB(B1, 1, 1); PG8_SCHED; PG8_LDA(At, 1, 0); PG8_STAGE(PG8_SA(0, 1), a2 + hstep, voffA);
;             PG8_WAIT_V(8); PG8_WAIT_L(0); PG8_BAR; PG8_MMA(0, 0, At, B0); PG8_MMA(0, 1, At, B1); PG8_BAR; PG8_SCHED;
;             PG8_LDA(At, 1, 1); PG8_STAGE(PG8_SB(1, 0), b3, voffB); PG8_STAGE(PG8_SB(1, 1), b3 + hstep, voffB); PG8_STAGE(PG8_SA(1, 0), a3, voffA);
;             PG8_WAIT_V(8); PG8_WAIT_L(0); PG8_BAR; PG8_MMA(1, 0, At, B0); PG8_MMA(1, 1, At, B1); PG8_BAR; PG8_SCHED;
;         }
	s_add_i32 s61, s61, s12
	v_lshl_add_u64 v[82:83], v[190:191], 0, s[68:69]
	s_mov_b32 m0, s61
	ds_read_b128 v[186:189], v230 offset:49152
	ds_read_b128 v[198:201], v230 offset:50176
	ds_read_b128 v[202:205], v230 offset:51200
	ds_read_b128 v[206:209], v230 offset:52224
	ds_read_b128 v[234:237], v230 offset:53248
	ds_read_b128 v[238:241], v230 offset:54272
	ds_read_b128 v[242:245], v230 offset:55296
	ds_read_b128 v[246:249], v230 offset:56320
	global_load_lds_dwordx4 v[82:83], off
	s_add_i32 m0, s61, 0x2000
	s_add_u32 s64, s64, 0x40080
	v_lshl_add_u64 v[82:83], v[250:251], 0, s[68:69]
	s_addc_u32 s65, s65, 0
	s_add_i32 s61, s70, s12
	global_load_lds_dwordx4 v[82:83], off
	v_lshl_add_u64 v[82:83], s[64:65], 0, v[164:165]
	s_mov_b32 m0, s61
	s_nop 0
	global_load_lds_dwordx4 v[82:83], off
	v_lshl_add_u64 v[82:83], s[64:65], 0, v[168:169]
	s_add_i32 m0, s61, 0x2000
	s_nop 0
	global_load_lds_dwordx4 v[82:83], off
	v_lshl_add_u64 v[82:83], v[224:225], 0, s[68:69]
	s_mov_b32 m0, s82
	s_nop 0
	global_load_lds_dwordx4 v[82:83], off
	v_lshl_add_u64 v[82:83], v[226:227], 0, s[68:69]
	s_mov_b32 m0, s83
	s_nop 0
	global_load_lds_dwordx4 v[82:83], off
	s_waitcnt vmcnt(8)
	s_waitcnt lgkmcnt(0)
	s_barrier
	s_waitcnt lgkmcnt(0)
	v_mfma_f32_16x16x32_bf16 v[60:63], v[88:91], v[186:189], v[60:63]
	v_mfma_f32_16x16x32_bf16 v[56:59], v[144:147], v[186:189], v[56:59]
	v_mfma_f32_16x16x32_bf16 v[44:47], v[88:91], v[202:205], v[44:47]
	v_mfma_f32_16x16x32_bf16 v[40:43], v[144:147], v[202:205], v[40:43]
	v_mfma_f32_16x16x32_bf16 v[28:31], v[88:91], v[234:237], v[28:31]
	v_mfma_f32_16x16x32_bf16 v[24:27], v[144:147], v[234:237], v[24:27]
	v_mfma_f32_16x16x32_bf16 v[12:15], v[88:91], v[242:245], v[12:15]
	v_mfma_f32_16x16x32_bf16 v[8:11], v[144:147], v[242:245], v[8:11]
	v_mfma_f32_16x16x32_bf16 v[60:63], v[92:95], v[198:201], v[60:63]
	v_mfma_f32_16x16x32_bf16 v[56:59], v[148:151], v[198:201], v[56:59]
	v_mfma_f32_16x16x32_bf16 v[44:47], v[92:95], v[206:209], v[44:47]
	v_mfma_f32_16x16x32_bf16 v[40:43], v[148:151], v[206:209], v[40:43]
	v_mfma_f32_16x16x32_bf16 v[28:31], v[92:95], v[238:241], v[28:31]
	v_mfma_f32_16x16x32_bf16 v[24:27], v[148:151], v[238:241], v[24:27]
	v_mfma_f32_16x16x32_bf16 v[12:15], v[92:95], v[246:249], v[12:15]
	v_mfma_f32_16x16x32_bf16 v[8:11], v[148:151], v[246:249], v[8:11]
	v_mfma_f32_16x16x32_bf16 v[52:55], v[152:155], v[186:189], v[52:55]
	v_mfma_f32_16x16x32_bf16 v[48:51], v[178:181], v[186:189], v[48:51]
	v_mfma_f32_16x16x32_bf16 v[36:39], v[152:155], v[202:205], v[36:39]
	v_mfma_f32_16x16x32_bf16 v[32:35], v[178:181], v[202:205], v[32:35]
	v_mfma_f32_16x16x32_bf16 v[20:23], v[152:155], v[234:237], v[20:23]
	v_mfma_f32_16x16x32_bf16 v[16:19], v[178:181], v[234:237], v[16:19]
	v_mfma_f32_16x16x32_bf16 v[4:7], v[152:155], v[242:245], v[4:7]
	v_mfma_f32_16x16x32_bf16 v[0:3], v[178:181], v[242:245], v[0:3]
	v_mfma_f32_16x16x32_bf16 v[52:55], v[156:159], v[198:201], v[52:55]
	v_mfma_f32_16x16x32_bf16 v[48:51], v[182:185], v[198:201], v[48:51]
	v_mfma_f32_16x16x32_bf16 v[36:39], v[156:159], v[206:209], v[36:39]
	v_mfma_f32_16x16x32_bf16 v[32:35], v[182:185], v[206:209], v[32:35]
	v_mfma_f32_16x16x32_bf16 v[20:23], v[156:159], v[238:241], v[20:23]
	v_mfma_f32_16x16x32_bf16 v[16:19], v[182:185], v[238:241], v[16:19]
	v_mfma_f32_16x16x32_bf16 v[4:7], v[156:159], v[246:249], v[4:7]
	v_mfma_f32_16x16x32_bf16 v[0:3], v[182:185], v[246:249], v[0:3]
	s_barrier
	s_add_i32 s60, s60, 2
	s_add_u32 s6, s6, 0x100
	s_addc_u32 s7, s7, 0
	s_add_u32 s58, s58, 0x100
	s_addc_u32 s59, s59, 0
	s_cmp_gt_u32 s60, 13
.LBB0_266:
	s_add_u32 s61, s6, 0xfffc0080
	s_addc_u32 s64, s7, -1
	s_add_i32 s70, 0, 0x10000
	s_cmp_eq_u32 s60, 12
	s_cselect_b32 s67, s23, s64
	s_cselect_b32 s66, s56, s61
	v_add_u32_e32 v81, s70, v216
	s_cselect_b32 s65, s55, s59
	s_cselect_b32 s64, s57, s58
	s_add_i32 s61, 0, 0x14000
	ds_read_b128 v[88:91], v81
	ds_read_b128 v[92:95], v81 offset:1024
	ds_read_b128 v[144:147], v81 offset:2048
	ds_read_b128 v[148:151], v81 offset:3072
	v_add_u32_e32 v81, s61, v216
	ds_read_b128 v[152:155], v81
	ds_read_b128 v[156:159], v81 offset:1024
	ds_read_b128 v[178:181], v81 offset:2048
	ds_read_b128 v[182:185], v81 offset:3072
	v_lshl_add_u64 v[82:83], s[6:7], 0, v[174:175]
	s_add_i32 m0, s73, 0xc000
	ds_read_b128 v[186:189], v230
	ds_read_b128 v[198:201], v230 offset:1024
	ds_read_b128 v[202:205], v230 offset:2048
	ds_read_b128 v[206:209], v230 offset:3072
	ds_read_b128 v[234:237], v230 offset:4096
	ds_read_b128 v[238:241], v230 offset:5120
	ds_read_b128 v[242:245], v230 offset:6144
	ds_read_b128 v[246:249], v230 offset:7168
	global_load_lds_dwordx4 v[82:83], off
	v_lshl_add_u64 v[82:83], s[6:7], 0, v[176:177]
	s_add_i32 m0, s73, 0xe000
	s_nop 0
	global_load_lds_dwordx4 v[82:83], off
	s_waitcnt vmcnt(8)
	s_waitcnt lgkmcnt(0)
	s_barrier
; #define PG8_STAGE(bufoff, gbase, voff) do { _Pragma("unroll") for (int _i = 0; _i < 2; ++_i) \
;         __builtin_amdgcn_global_load_lds((const unsigned*)((const char*)(gbase) + (voff)[_i]), (LAS unsigned*)(lds + (bufoff) + ldsw + _i * 8192), 16, 0, 0); } while (0)
; #define PG8_LDA(dst, b, h) do { _Pragma("unroll") for (int m = 0; m < 4; ++m) _Pragma("unroll") for (int k = 0; k < 2; ++k) dst[m][k] = *(const LAS bf16x8*)(lds + PG8_SA(b, h) + aoff + m * 2048 + k * 1024); } while (0)
; #define PG8_LDB(dst, b, h) do { _Pragma("unroll") for (int n = 0; n < 2; ++n) _Pragma("unroll") for (int k = 0; k < 2; ++k) dst[n][k] = *(const LAS bf16x8*)(lds + PG8_SB(b, h) + boff + n * 2048 + k * 1024); } while (0)
; #define PG8_WAIT_V(n) asm volatile("s_waitcnt vmcnt(" #n ")" ::: "memory")
; #define PG8_BAR __builtin_amdgcn_s_barrier()
; template <class Epi, class Sched>
; __device__ __forceinline__ void gemm_phase(LAS unsigned char* lds, const Gemm g, const Sched& S, const Epi& E, const int tid) {
;     ...
;         for (int t = 0; t < nt; t += 2) {
;             const bool last = (t == nt - 2);
;             const char* a1 = cA + (size_t)(t + 1) * kstep;
;             const char* a2 = last ? nA : cA + (size_t)(t + 2) * kstep; const char* b2 = last ? nB : cB + (size_t)(t + 2) * kstep;
;             const char* a3 = a2 + kstep; const char* b3 = b2 + kstep;
;             PG8_LDB(B0, 0, 0); PG8_LDB(B1, 0, 1); PG8_SCHED; PG8_LDA(At, 0, 0); PG8_STAGE(PG8_SA(1, 1), a1 + hstep, voffA);
;             PG8_WAIT_V(8); PG8_WAIT_L(0); PG8_BAR; PG8_MMA(0, 0, At, B0); PG8_MMA(0, 1, At, B1); PG8_BAR; PG8_SCHED;
;             PG8_LDA(At, 0, 1); PG8_STAGE(PG8_SB(0, 0), b2, voffB); PG8_STAGE(PG8_SB(0, 1), b2 + hstep, voffB); PG8_STAGE(PG8_SA(0, 0), a2, voffA);
;             PG8_WAIT_V(8); PG8_WAIT_L(0); PG8_BAR; PG8_MMA(1, 0, At, B0); PG8_MMA(1, 1, At, B1); PG8_BAR; PG8_SCHED;
;             PG8_LDB(B0, 1, 0); PG8_LDB(B1, 1, 1); PG8_SCHED; PG8_LDA(At, 1, 0); PG8_STAGE(PG8_SA(0, 1), a2 + hstep, voffA);
;             PG8_WAIT_V(8); PG8_WAIT_L(0); PG8_BAR; PG8_MMA(0, 0, At, B0); PG8_MMA(0, 1, At, B1); PG8_BAR; PG8_SCHED;
;             PG8_LDA(At, 1, 1); PG8_STAGE(PG8_SB(1, 0), b3, voffB); PG8_STAGE(PG8_SB(1, 1), b3 + hstep, voffB); PG8_STAGE(PG8_SA(1, 0), a3, voffA);
;             PG8_WAIT_V(8); PG8_WAIT_L(0); PG8_BAR; PG8_MMA(1, 0, At, B0); PG8_MMA(1, 1, At, B1); PG8_BAR; PG8_SCHED;
;         }
	s_waitcnt lgkmcnt(0)
	v_mfma_f32_16x16x32_bf16 v[140:143], v[88:91], v[186:189], v[140:143]
	v_mfma_f32_16x16x32_bf16 v[136:139], v[144:147], v[186:189], v[136:139]
	v_mfma_f32_16x16x32_bf16 v[124:127], v[88:91], v[202:205], v[124:127]
	v_mfma_f32_16x16x32_bf16 v[120:123], v[144:147], v[202:205], v[120:123]
	v_mfma_f32_16x16x32_bf16 v[108:111], v[88:91], v[234:237], v[108:111]
	v_mfma_f32_16x16x32_bf16 v[104:107], v[144:147], v[234:237], v[104:107]
	v_mfma_f32_16x16x32_bf16 v[82:85], v[88:91], v[242:245], v[84:87]
	v_mfma_f32_16x16x32_bf16 v[76:79], v[144:147], v[242:245], v[76:79]
	v_mfma_f32_16x16x32_bf16 v[140:143], v[92:95], v[198:201], v[140:143]
	v_mfma_f32_16x16x32_bf16 v[136:139], v[148:151], v[198:201], v[136:139]
	v_mfma_f32_16x16x32_bf16 v[124:127], v[92:95], v[206:209], v[124:127]
	v_mfma_f32_16x16x32_bf16 v[120:123], v[148:151], v[206:209], v[120:123]
	v_mfma_f32_16x16x32_bf16 v[108:111], v[92:95], v[238:241], v[108:111]
	v_mfma_f32_16x16x32_bf16 v[104:107], v[148:151], v[238:241], v[104:107]
	v_mfma_f32_16x16x32_bf16 v[82:85], v[92:95], v[246:249], v[82:85]
	v_mfma_f32_16x16x32_bf16 v[76:79], v[148:151], v[246:249], v[76:79]
	v_mfma_f32_16x16x32_bf16 v[132:135], v[152:155], v[186:189], v[132:135]
	v_mfma_f32_16x16x32_bf16 v[128:131], v[178:181], v[186:189], v[128:131]
	v_mfma_f32_16x16x32_bf16 v[116:119], v[152:155], v[202:205], v[116:119]
	v_mfma_f32_16x16x32_bf16 v[112:115], v[178:181], v[202:205], v[112:115]
	v_mfma_f32_16x16x32_bf16 v[100:103], v[152:155], v[234:237], v[100:103]
	v_mfma_f32_16x16x32_bf16 v[96:99], v[178:181], v[234:237], v[96:99]
	v_mfma_f32_16x16x32_bf16 v[68:71], v[152:155], v[242:245], v[68:71]
	v_mfma_f32_16x16x32_bf16 v[64:67], v[178:181], v[242:245], v[64:67]
	v_mfma_f32_16x16x32_bf16 v[132:135], v[156:159], v[198:201], v[132:135]
	v_mfma_f32_16x16x32_bf16 v[128:131], v[182:185], v[198:201], v[128:131]
	v_mfma_f32_16x16x32_bf16 v[116:119], v[156:159], v[206:209], v[116:119]
	v_mfma_f32_16x16x32_bf16 v[112:115], v[182:185], v[206:209], v[112:115]
	v_mfma_f32_16x16x32_bf16 v[100:103], v[156:159], v[238:241], v[100:103]
	v_mfma_f32_16x16x32_bf16 v[96:99], v[182:185], v[238:241], v[96:99]
	v_mfma_f32_16x16x32_bf16 v[68:71], v[156:159], v[246:249], v[68:71]
	v_mfma_f32_16x16x32_bf16 v[64:67], v[182:185], v[246:249], v[64:67]
	s_barrier
	s_add_i32 s70, s70, s12
	v_lshl_add_u64 v[190:191], s[64:65], 0, v[164:165]
	s_mov_b32 m0, s70
	ds_read_b128 v[186:189], v230 offset:16384
	ds_read_b128 v[198:201], v230 offset:17408
	ds_read_b128 v[202:205], v230 offset:18432
	ds_read_b128 v[206:209], v230 offset:19456
	ds_read_b128 v[234:237], v230 offset:20480
	ds_read_b128 v[238:241], v230 offset:21504
	ds_read_b128 v[242:245], v230 offset:22528
	ds_read_b128 v[246:249], v230 offset:23552
	global_load_lds_dwordx4 v[190:191], off
	s_add_i32 m0, s70, 0x2000
	s_add_u32 s70, s64, 0x40000
	v_lshl_add_u64 v[250:251], s[64:65], 0, v[168:169]
	s_addc_u32 s71, s65, 0
	s_add_i32 s61, s61, s12
	global_load_lds_dwordx4 v[250:251], off
	v_lshl_add_u64 v[86:87], s[70:71], 0, v[164:165]
	s_mov_b32 m0, s61
	v_lshl_add_u64 v[224:225], s[66:67], 0, v[162:163]
	global_load_lds_dwordx4 v[86:87], off
	v_lshl_add_u64 v[86:87], s[70:71], 0, v[168:169]
	s_add_i32 m0, s61, 0x2000
	v_lshl_add_u64 v[226:227], s[66:67], 0, v[166:167]
	global_load_lds_dwordx4 v[86:87], off
	s_mov_b32 m0, s73
	s_nop 0
	global_load_lds_dwordx4 v[224:225], off
	s_mov_b32 m0, s74
	s_nop 0
	global_load_lds_dwordx4 v[226:227], off
	s_waitcnt vmcnt(8)
	s_waitcnt lgkmcnt(0)
	s_barrier
	s_waitcnt lgkmcnt(0)
	v_mfma_f32_16x16x32_bf16 v[60:63], v[88:91], v[186:189], v[60:63]
	v_mfma_f32_16x16x32_bf16 v[56:59], v[144:147], v[186:189], v[56:59]
	v_mfma_f32_16x16x32_bf16 v[44:47], v[88:91], v[202:205], v[44:47]
	v_mfma_f32_16x16x32_bf16 v[40:43], v[144:147], v[202:205], v[40:43]
	v_mfma_f32_16x16x32_bf16 v[28:31], v[88:91], v[234:237], v[28:31]
	v_mfma_f32_16x16x32_bf16 v[24:27], v[144:147], v[234:237], v[24:27]
	v_mfma_f32_16x16x32_bf16 v[12:15], v[88:91], v[242:245], v[12:15]
	v_mfma_f32_16x16x32_bf16 v[8:11], v[144:147], v[242:245], v[8:11]
	v_mfma_f32_16x16x32_bf16 v[60:63], v[92:95], v[198:201], v[60:63]
	v_mfma_f32_16x16x32_bf16 v[56:59], v[148:151], v[198:201], v[56:59]
	v_mfma_f32_16x16x32_bf16 v[44:47], v[92:95], v[206:209], v[44:47]
	v_mfma_f32_16x16x32_bf16 v[40:43], v[148:151], v[206:209], v[40:43]
	v_mfma_f32_16x16x32_bf16 v[28:31], v[92:95], v[238:241], v[28:31]
	v_mfma_f32_16x16x32_bf16 v[24:27], v[148:151], v[238:241], v[24:27]
	v_mfma_f32_16x16x32_bf16 v[12:15], v[92:95], v[246:249], v[12:15]
	v_mfma_f32_16x16x32_bf16 v[8:11], v[148:151], v[246:249], v[8:11]
	v_mfma_f32_16x16x32_bf16 v[52:55], v[152:155], v[186:189], v[52:55]
	v_mfma_f32_16x16x32_bf16 v[48:51], v[178:181], v[186:189], v[48:51]
	v_mfma_f32_16x16x32_bf16 v[36:39], v[152:155], v[202:205], v[36:39]
	v_mfma_f32_16x16x32_bf16 v[32:35], v[178:181], v[202:205], v[32:35]
	v_mfma_f32_16x16x32_bf16 v[20:23], v[152:155], v[234:237], v[20:23]
	v_mfma_f32_16x16x32_bf16 v[16:19], v[178:181], v[234:237], v[16:19]
	v_mfma_f32_16x16x32_bf16 v[4:7], v[152:155], v[242:245], v[4:7]
	v_mfma_f32_16x16x32_bf16 v[0:3], v[178:181], v[242:245], v[0:3]
	v_mfma_f32_16x16x32_bf16 v[52:55], v[156:159], v[198:201], v[52:55]
	v_mfma_f32_16x16x32_bf16 v[48:51], v[182:185], v[198:201], v[48:51]
	v_mfma_f32_16x16x32_bf16 v[36:39], v[156:159], v[206:209], v[36:39]
	v_mfma_f32_16x16x32_bf16 v[32:35], v[182:185], v[206:209], v[32:35]
	v_mfma_f32_16x16x32_bf16 v[20:23], v[156:159], v[238:241], v[20:23]
	v_mfma_f32_16x16x32_bf16 v[16:19], v[182:185], v[238:241], v[16:19]
	v_mfma_f32_16x16x32_bf16 v[4:7], v[156:159], v[246:249], v[4:7]
	v_mfma_f32_16x16x32_bf16 v[0:3], v[182:185], v[246:249], v[0:3]
	s_barrier
; #define PG8_STAGE(bufoff, gbase, voff) do { _Pragma("unroll") for (int _i = 0; _i < 2; ++_i) \
;         __builtin_amdgcn_global_load_lds((const unsigned*)((const char*)(gbase) + (voff)[_i]), (LAS unsigned*)(lds + (bufoff) + ldsw + _i * 8192), 16, 0, 0); } while (0)
; #define PG8_LDA(dst, b, h) do { _Pragma("unroll") for (int m = 0; m < 4; ++m) _Pragma("unroll") for (int k = 0; k < 2; ++k) dst[m][k] = *(const LAS bf16x8*)(lds + PG8_SA(b, h) + aoff + m * 2048 + k * 1024); } while (0)
; #define PG8_LDB(dst, b, h) do { _Pragma("unroll") for (int n = 0; n < 2; ++n) _Pragma("unroll") for (int k = 0; k < 2; ++k) dst[n][k] = *(const LAS bf16x8*)(lds + PG8_SB(b, h) + boff + n * 2048 + k * 1024); } while (0)
; #define PG8_WAIT_V(n) asm volatile("s_waitcnt vmcnt(" #n ")" ::: "memory")
; #define PG8_BAR __builtin_amdgcn_s_barrier()
; template <class Epi, class Sched>
; __device__ __forceinline__ void gemm_phase(LAS unsigned char* lds, const Gemm g, const Sched& S, const Epi& E, const int tid) {
;     ...
;         for (int t = 0; t < nt; t += 2) {
;             const bool last = (t == nt - 2);
;             const char* a1 = cA + (size_t)(t + 1) * kstep;
;             const char* a2 = last ? nA : cA + (size_t)(t + 2) * kstep; const char* b2 = last ? nB : cB + (size_t)(t + 2) * kstep;
;             const char* a3 = a2 + kstep; const char* b3 = b2 + kstep;
;             PG8_LDB(B0, 0, 0); PG8_LDB(B1, 0, 1); PG8_SCHED; PG8_LDA(At, 0, 0); PG8_STAGE(PG8_SA(1, 1), a1 + hstep, voffA);
;             PG8_WAIT_V(8); PG8_WAIT_L(0); PG8_BAR; PG8_MMA(0, 0, At, B0); PG8_MMA(0, 1, At, B1); PG8_BAR; PG8_SCHED;
;             PG8_LDA(At, 0, 1); PG8_STAGE(PG8_SB(0, 0), b2, voffB); PG8_STAGE(PG8_SB(0, 1), b2 + hstep, voffB); PG8_STAGE(PG8_SA(0, 0), a2, voffA);
;             PG8_WAIT_V(8); PG8_WAIT_L(0); PG8_BAR; PG8_MMA(1, 0, At, B0); PG8_MMA(1, 1, At, B1); PG8_BAR; PG8_SCHED;
;             PG8_LDB(B0, 1, 0); PG8_LDB(B1, 1, 1); PG8_SCHED; PG8_LDA(At, 1, 0); PG8_STAGE(PG8_SA(0, 1), a2 + hstep, voffA);
;             PG8_WAIT_V(8); PG8_WAIT_L(0); PG8_BAR; PG8_MMA(0, 0, At, B0); PG8_MMA(0, 1, At, B1); PG8_BAR; PG8_SCHED;
;             PG8_LDA(At, 1, 1); PG8_STAGE(PG8_SB(1, 0), b3, voffB); PG8_STAGE(PG8_SB(1, 1), b3 + hstep, voffB); PG8_STAGE(PG8_SA(1, 0), a3, voffA);
;             PG8_WAIT_V(8); PG8_WAIT_L(0); PG8_BAR; PG8_MMA(1, 0, At, B0); PG8_MMA(1, 1, At, B1); PG8_BAR; PG8_SCHED;
;         }
	s_add_i32 s61, 0, 0x18000
	v_add_u32_e32 v81, s61, v216
	s_add_i32 s70, 0, 0x1c000
	ds_read_b128 v[88:91], v81
	ds_read_b128 v[92:95], v81 offset:1024
	ds_read_b128 v[144:147], v81 offset:2048
	ds_read_b128 v[148:151], v81 offset:3072
	v_add_u32_e32 v81, s70, v216
	ds_read_b128 v[152:155], v81
	ds_read_b128 v[156:159], v81 offset:1024
	ds_read_b128 v[178:181], v81 offset:2048
	ds_read_b128 v[182:185], v81 offset:3072
	s_add_u32 s66, s66, 0x40000
	s_addc_u32 s67, s67, 0
	s_mov_b32 m0, s75
	v_lshl_add_u64 v[86:87], s[66:67], 0, v[162:163]
	ds_read_b128 v[186:189], v230 offset:32768
	ds_read_b128 v[198:201], v230 offset:33792
	ds_read_b128 v[202:205], v230 offset:34816
	ds_read_b128 v[206:209], v230 offset:35840
	ds_read_b128 v[234:237], v230 offset:36864
	ds_read_b128 v[238:241], v230 offset:37888
	ds_read_b128 v[242:245], v230 offset:38912
	ds_read_b128 v[246:249], v230 offset:39936
	global_load_lds_dwordx4 v[86:87], off
	v_lshl_add_u64 v[86:87], s[66:67], 0, v[166:167]
	s_mov_b32 m0, s81
	s_nop 0
	global_load_lds_dwordx4 v[86:87], off
	s_waitcnt vmcnt(8)
	s_waitcnt lgkmcnt(0)
	s_barrier
	s_waitcnt lgkmcnt(0)
	v_mfma_f32_16x16x32_bf16 v[140:143], v[88:91], v[186:189], v[140:143]
	v_mfma_f32_16x16x32_bf16 v[136:139], v[144:147], v[186:189], v[136:139]
	v_mfma_f32_16x16x32_bf16 v[124:127], v[88:91], v[202:205], v[124:127]
	v_mfma_f32_16x16x32_bf16 v[120:123], v[144:147], v[202:205], v[120:123]
	v_mfma_f32_16x16x32_bf16 v[108:111], v[88:91], v[234:237], v[108:111]
	v_mfma_f32_16x16x32_bf16 v[104:107], v[144:147], v[234:237], v[104:107]
	v_mfma_f32_16x16x32_bf16 v[82:85], v[88:91], v[242:245], v[82:85]
	v_mfma_f32_16x16x32_bf16 v[76:79], v[144:147], v[242:245], v[76:79]
	v_mfma_f32_16x16x32_bf16 v[140:143], v[92:95], v[198:201], v[140:143]
	v_mfma_f32_16x16x32_bf16 v[136:139], v[148:151], v[198:201], v[136:139]
	v_mfma_f32_16x16x32_bf16 v[124:127], v[92:95], v[206:209], v[124:127]
	v_mfma_f32_16x16x32_bf16 v[120:123], v[148:151], v[206:209], v[120:123]
	v_mfma_f32_16x16x32_bf16 v[108:111], v[92:95], v[238:241], v[108:111]
	v_mfma_f32_16x16x32_bf16 v[104:107], v[148:151], v[238:241], v[104:107]
	v_mfma_f32_16x16x32_bf16 v[84:87], v[92:95], v[246:249], v[82:85]
	v_mfma_f32_16x16x32_bf16 v[76:79], v[148:151], v[246:249], v[76:79]
	v_mfma_f32_16x16x32_bf16 v[132:135], v[152:155], v[186:189], v[132:135]
	v_mfma_f32_16x16x32_bf16 v[128:131], v[178:181], v[186:189], v[128:131]
	v_mfma_f32_16x16x32_bf16 v[116:119], v[152:155], v[202:205], v[116:119]
	v_mfma_f32_16x16x32_bf16 v[112:115], v[178:181], v[202:205], v[112:115]
	v_mfma_f32_16x16x32_bf16 v[100:103], v[152:155], v[234:237], v[100:103]
	v_mfma_f32_16x16x32_bf16 v[96:99], v[178:181], v[234:237], v[96:99]
	v_mfma_f32_16x16x32_bf16 v[68:71], v[152:155], v[242:245], v[68:71]
	v_mfma_f32_16x16x32_bf16 v[64:67], v[178:181], v[242:245], v[64:67]
	v_mfma_f32_16x16x32_bf16 v[132:135], v[156:159], v[198:201], v[132:135]
	v_mfma_f32_16x16x32_bf16 v[128:131], v[182:185], v[198:201], v[128:131]
	v_mfma_f32_16x16x32_bf16 v[116:119], v[156:159], v[206:209], v[116:119]
	v_mfma_f32_16x16x32_bf16 v[112:115], v[182:185], v[206:209], v[112:115]
	v_mfma_f32_16x16x32_bf16 v[100:103], v[156:159], v[238:241], v[100:103]
	v_mfma_f32_16x16x32_bf16 v[96:99], v[182:185], v[238:241], v[96:99]
	v_mfma_f32_16x16x32_bf16 v[68:71], v[156:159], v[246:249], v[68:71]
	v_mfma_f32_16x16x32_bf16 v[64:67], v[182:185], v[246:249], v[64:67]
	s_barrier
; #define PG8_STAGE(bufoff, gbase, voff) do { _Pragma("unroll") for (int _i = 0; _i < 2; ++_i) \
;         __builtin_amdgcn_global_load_lds((const unsigned*)((const char*)(gbase) + (voff)[_i]), (LAS unsigned*)(lds + (bufoff) + ldsw + _i * 8192), 16, 0, 0); } while (0)
; #define PG8_LDA(dst, b, h) do { _Pragma("unroll") for (int m = 0; m < 4; ++m) _Pragma("unroll") for (int k = 0; k < 2; ++k) dst[m][k] = *(const LAS bf16x8*)(lds + PG8_SA(b, h) + aoff + m * 2048 + k * 1024); } while (0)
; #define PG8_LDB(dst, b, h) do { _Pragma("unroll") for (int n = 0; n < 2; ++n) _Pragma("unroll") for (int k = 0; k < 2; ++k) dst[n][k] = *(const LAS bf16x8*)(lds + PG8_SB(b, h) + boff + n * 2048 + k * 1024); } while (0)
; #define PG8_WAIT_V(n) asm volatile("s_waitcnt vmcnt(" #n ")" ::: "memory")
; #define PG8_BAR __builtin_amdgcn_s_barrier()
; template <class Epi, class Sched>
; __device__ __forceinline__ void gemm_phase(LAS unsigned char* lds, const Gemm g, const Sched& S, const Epi& E, const int tid) {
;     ...
;         for (int t = 0; t < nt; t += 2) {
;             const bool last = (t == nt - 2);
;             const char* a1 = cA + (size_t)(t + 1) * kstep;
;             const char* a2 = last ? nA : cA + (size_t)(t + 2) * kstep; const char* b2 = last ? nB : cB + (size_t)(t + 2) * kstep;
;             const char* a3 = a2 + kstep; const char* b3 = b2 + kstep;
;             PG8_LDB(B0, 0, 0); PG8_LDB(B1, 0, 1); PG8_SCHED; PG8_LDA(At, 0, 0); PG8_STAGE(PG8_SA(1, 1), a1 + hstep, voffA);
;             PG8_WAIT_V(8); PG8_WAIT_L(0); PG8_BAR; PG8_MMA(0, 0, At, B0); PG8_MMA(0, 1, At, B1); PG8_BAR; PG8_SCHED;
;             PG8_LDA(At, 0, 1); PG8_STAGE(PG8_SB(0, 0), b2, voffB); PG8_STAGE(PG8_SB(0, 1), b2 + hstep, voffB); PG8_STAGE(PG8_SA(0, 0), a2, voffA);
;             PG8_WAIT_V(8); PG8_WAIT_L(0); PG8_BAR; PG8_MMA(1, 0, At, B0); PG8_MMA(1, 1, At, B1); PG8_BAR; PG8_SCHED;
;             PG8_LDB(B0, 1, 0); PG8_LDB(B1, 1, 1); PG8_SCHED; PG8_LDA(At, 1, 0); PG8_STAGE(PG8_SA(0, 1), a2 + hstep, voffA);
;             PG8_WAIT_V(8); PG8_WAIT_L(0); PG8_BAR; PG8_MMA(0, 0, At, B0); PG8_MMA(0, 1, At, B1); PG8_BAR; PG8_SCHED;
;             PG8_LDA(At, 1, 1); PG8_STAGE(PG8_SB(1, 0), b3, voffB); PG8_STAGE(PG8_SB(1, 1), b3 + hstep, voffB); PG8_STAGE(PG8_SA(1, 0), a3, voffA);
;             PG8_WAIT_V(8); PG8_WAIT_L(0); PG8_BAR; PG8_MMA(1, 0, At, B0); PG8_MMA(1, 1, At, B1); PG8_BAR; PG8_SCHED;
;         }
	s_add_i32 s61, s61, s12
	v_lshl_add_u64 v[82:83], v[190:191], 0, s[68:69]
	s_mov_b32 m0, s61
	ds_read_b128 v[186:189], v230 offset:49152
	ds_read_b128 v[198:201], v230 offset:50176
	ds_read_b128 v[202:205], v230 offset:51200
	ds_read_b128 v[206:209], v230 offset:52224
	ds_read_b128 v[234:237], v230 offset:53248
	ds_read_b128 v[238:241], v230 offset:54272
	ds_read_b128 v[242:245], v230 offset:55296
	ds_read_b128 v[246:249], v230 offset:56320
	global_load_lds_dwordx4 v[82:83], off
	s_add_i32 m0, s61, 0x2000
	s_add_u32 s64, s64, 0x40080
	v_lshl_add_u64 v[82:83], v[250:251], 0, s[68:69]
	s_addc_u32 s65, s65, 0
	s_add_i32 s61, s70, s12
	global_load_lds_dwordx4 v[82:83], off
	v_lshl_add_u64 v[82:83], s[64:65], 0, v[164:165]
	s_mov_b32 m0, s61
	s_nop 0
	global_load_lds_dwordx4 v[82:83], off
	v_lshl_add_u64 v[82:83], s[64:65], 0, v[168:169]
	s_add_i32 m0, s61, 0x2000
	s_nop 0
	global_load_lds_dwordx4 v[82:83], off
	v_lshl_add_u64 v[82:83], v[224:225], 0, s[68:69]
	s_mov_b32 m0, s82
	s_nop 0
	global_load_lds_dwordx4 v[82:83], off
	v_lshl_add_u64 v[82:83], v[226:227], 0, s[68:69]
	s_mov_b32 m0, s83
	s_nop 0
	global_load_lds_dwordx4 v[82:83], off
	s_waitcnt vmcnt(8)
	s_waitcnt lgkmcnt(0)
	s_barrier
	s_waitcnt lgkmcnt(0)
	v_mfma_f32_16x16x32_bf16 v[60:63], v[88:91], v[186:189], v[60:63]
	v_mfma_f32_16x16x32_bf16 v[56:59], v[144:147], v[186:189], v[56:59]
	v_mfma_f32_16x16x32_bf16 v[44:47], v[88:91], v[202:205], v[44:47]
	v_mfma_f32_16x16x32_bf16 v[40:43], v[144:147], v[202:205], v[40:43]
	v_mfma_f32_16x16x32_bf16 v[28:31], v[88:91], v[234:237], v[28:31]
	v_mfma_f32_16x16x32_bf16 v[24:27], v[144:147], v[234:237], v[24:27]
	v_mfma_f32_16x16x32_bf16 v[12:15], v[88:91], v[242:245], v[12:15]
	v_mfma_f32_16x16x32_bf16 v[8:11], v[144:147], v[242:245], v[8:11]
	v_mfma_f32_16x16x32_bf16 v[60:63], v[92:95], v[198:201], v[60:63]
	v_mfma_f32_16x16x32_bf16 v[56:59], v[148:151], v[198:201], v[56:59]
	v_mfma_f32_16x16x32_bf16 v[44:47], v[92:95], v[206:209], v[44:47]
	v_mfma_f32_16x16x32_bf16 v[40:43], v[148:151], v[206:209], v[40:43]
	v_mfma_f32_16x16x32_bf16 v[28:31], v[92:95], v[238:241], v[28:31]
	v_mfma_f32_16x16x32_bf16 v[24:27], v[148:151], v[238:241], v[24:27]
	v_mfma_f32_16x16x32_bf16 v[12:15], v[92:95], v[246:249], v[12:15]
	v_mfma_f32_16x16x32_bf16 v[8:11], v[148:151], v[246:249], v[8:11]
	v_mfma_f32_16x16x32_bf16 v[52:55], v[152:155], v[186:189], v[52:55]
	v_mfma_f32_16x16x32_bf16 v[48:51], v[178:181], v[186:189], v[48:51]
	v_mfma_f32_16x16x32_bf16 v[36:39], v[152:155], v[202:205], v[36:39]
	v_mfma_f32_16x16x32_bf16 v[32:35], v[178:181], v[202:205], v[32:35]
	v_mfma_f32_16x16x32_bf16 v[20:23], v[152:155], v[234:237], v[20:23]
	v_mfma_f32_16x16x32_bf16 v[16:19], v[178:181], v[234:237], v[16:19]
	v_mfma_f32_16x16x32_bf16 v[4:7], v[152:155], v[242:245], v[4:7]
	v_mfma_f32_16x16x32_bf16 v[0:3], v[178:181], v[242:245], v[0:3]
	v_mfma_f32_16x16x32_bf16 v[52:55], v[156:159], v[198:201], v[52:55]
	v_mfma_f32_16x16x32_bf16 v[48:51], v[182:185], v[198:201], v[48:51]
	v_mfma_f32_16x16x32_bf16 v[36:39], v[156:159], v[206:209], v[36:39]
	v_mfma_f32_16x16x32_bf16 v[32:35], v[182:185], v[206:209], v[32:35]
	v_mfma_f32_16x16x32_bf16 v[20:23], v[156:159], v[238:241], v[20:23]
	v_mfma_f32_16x16x32_bf16 v[16:19], v[182:185], v[238:241], v[16:19]
	v_mfma_f32_16x16x32_bf16 v[4:7], v[156:159], v[246:249], v[4:7]
	v_mfma_f32_16x16x32_bf16 v[0:3], v[182:185], v[246:249], v[0:3]
	s_barrier
	s_add_i32 s60, s60, 2
	s_add_u32 s6, s6, 0x100
	s_addc_u32 s7, s7, 0
	s_add_u32 s58, s58, 0x100
	s_addc_u32 s59, s59, 0
	s_cmp_gt_u32 s60, 13
	s_cbranch_scc0 .LBB0_266
	s_and_b64 vcc, exec, s[50:51]
	s_cbranch_vccz .LBB0_269
	s_barrier

; #define PG8_STAGE(bufoff, gbase, voff) do { _Pragma("unroll") for (int _i = 0; _i < 2; ++_i) \
;         __builtin_amdgcn_global_load_lds((const unsigned*)((const char*)(gbase) + (voff)[_i]), (LAS unsigned*)(lds + (bufoff) + ldsw + _i * 8192), 16, 0, 0); } while (0)
; #define PG8_WAIT_V(n) asm volatile("s_waitcnt vmcnt(" #n ")" ::: "memory")
; #define PG8_BAR __builtin_amdgcn_s_barrier()
; template <class Epi, class Sched>
; __device__ __forceinline__ void gemm_phase(LAS unsigned char* lds, const Gemm g, const Sched& S, const Epi& E, const int tid) {
;     ...
;     const char* cA = (const char*)g.A + (size_t)cur.pm * tstep; const char* cB = (const char*)g.Bt + (size_t)cur.pn * tstep;
;     PG8_STAGE(PG8_SB(0, 0), cB, voffB); PG8_STAGE(PG8_SB(0, 1), cB + hstep, voffB); PG8_STAGE(PG8_SA(0, 0), cA, voffA); PG8_STAGE(PG8_SA(0, 1), cA + hstep, voffA);
;     if (wr == 1) PG8_BAR;
;     PG8_WAIT_V(2); PG8_BAR;
;     PG8_STAGE(PG8_SB(1, 0), cB + kstep, voffB); PG8_STAGE(PG8_SA(1, 0), cA + kstep, voffA); PG8_STAGE(PG8_SB(1, 1), cB + hstep + kstep, voffB);
;     PG8_WAIT_V(6); PG8_BAR;
;     ...
;     PG8_WAIT_V(0);
;     PG8_BAR;
.LBB0_310:
	s_setprio 0
	s_waitcnt vmcnt(0)
	v_readlane_b32 s64, v254, 46
	s_movk_i32 s15, 0x161
	v_readlane_b32 s65, v254, 47
	s_barrier
	v_readlane_b32 s12, v254, 48
.LBB0_311:
	v_readlane_b32 s0, v253, 48
	v_readlane_b32 s1, v253, 49
	s_andn2_b64 vcc, exec, s[0:1]
	v_readfirstlane_b32 s4, v160
	s_cbranch_vccnz .LBB0_335
	s_ashr_i32 s6, s4, 6
	s_lshl_b32 s52, s6, 10
	s_add_i32 s53, s52, 0
	v_readlane_b32 s0, v254, 35
	s_add_i32 m0, s53, 0x10000
	v_readlane_b32 s1, v254, 36
	s_add_i32 s56, s53, 0x2000
	s_add_i32 s57, s53, 0x4000
	s_add_i32 s58, s53, 0x6000
	s_ashr_i32 s5, s4, 8
	s_nop 0
	global_load_lds_dwordx4 v164, s[0:1]
	s_add_i32 m0, s53, 0x12000
	s_nop 0
	global_load_lds_dwordx4 v168, s[0:1]
	v_readlane_b32 s0, v254, 33
	s_add_i32 m0, s53, 0x14000
	v_readlane_b32 s1, v254, 34
	s_nop 4
	global_load_lds_dwordx4 v164, s[0:1]
	s_add_i32 m0, s53, 0x16000
	s_cmp_eq_u32 s5, 1
	global_load_lds_dwordx4 v168, s[0:1]
	v_readlane_b32 s0, v255, 9
	s_mov_b32 m0, s53
	v_readlane_b32 s1, v255, 10
	s_nop 4
	global_load_lds_dwordx4 v162, s[0:1]
	s_mov_b32 m0, s56
	s_nop 0
	global_load_lds_dwordx4 v166, s[0:1]
	v_readlane_b32 s0, v255, 11
	s_mov_b32 m0, s57
	v_readlane_b32 s1, v255, 12
	s_nop 4
	global_load_lds_dwordx4 v162, s[0:1]
	s_mov_b32 m0, s58
	s_nop 0
	global_load_lds_dwordx4 v166, s[0:1]
	s_cselect_b64 s[0:1], -1, 0
	s_cmp_lg_u32 s5, 1
	s_cbranch_scc1 .LBB0_314
	s_barrier
	s_setprio 1

;     __device__ __forceinline__ Pre prefetch(const Unit& u, int tid) const { return prenorm_load(stats, u.pn * BM, sW + (size_t)(u.pn >> 4) * SW_ROWS + u.pm * BM, tid); }
;     __device__ __forceinline__ Pre prefetch(const Unit& u, int tid) const { return prenorm_load(stats, u.pm * BM, sW + (size_t)(u.pm >> 4) * SW_ROWS + u.pn * BM, tid); }
;     __device__ __forceinline__ Pre prefetch(const Unit& u, int tid) const { return prenorm_load(stats, u.pm * BM, sW + (size_t)(u.pm >> 4) * SW_ROWS + u.pn * BM, tid); }
; template <class Epi, class Sched>
; __device__ __forceinline__ void gemm_phase(LAS unsigned char* lds, const Gemm g, const Sched& S, const Epi& E, const int tid) {
;     ...
;         const bool has_next = S.next(ui + 1, nxt);
;         const char* nA = has_next ? (const char*)g.A + (size_t)nxt.pm * tstep : cA; const char* nB = has_next ? (const char*)g.Bt + (size_t)nxt.pn * tstep : cB;
;         const typename Epi::Pre pre = E.prefetch(cur, tid);
;         for (int t = 0; t < nt; t += 2) {
;             const bool last = (t == nt - 2);
;             const char* a1 = cA + (size_t)(t + 1) * kstep;
;             const char* a2 = last ? nA : cA + (size_t)(t + 2) * kstep; const char* b2 = last ? nB : cB + (size_t)(t + 2) * kstep;
;             const char* a3 = a2 + kstep; const char* b3 = b2 + kstep;
;             PG8_LDB(B0, 0, 0); PG8_LDB(B1, 0, 1); PG8_SCHED; PG8_LDA(At, 0, 0); PG8_STAGE(PG8_SA(1, 1), a1 + hstep, voffA);
;             PG8_WAIT_V(8); PG8_WAIT_L(0); PG8_BAR; PG8_MMA(0, 0, At, B0); PG8_MMA(0, 1, At, B1); PG8_BAR; PG8_SCHED;
;             PG8_LDA(At, 0, 1); PG8_STAGE(PG8_SB(0, 0), b2, voffB); PG8_STAGE(PG8_SB(0, 1), b2 + hstep, voffB); PG8_STAGE(PG8_SA(0, 0), a2, voffA);
;             PG8_WAIT_V(8); PG8_WAIT_L(0); PG8_BAR; PG8_MMA(1, 0, At, B0); PG8_MMA(1, 1, At, B1); PG8_BAR; PG8_SCHED;
;             PG8_LDB(B0, 1, 0); PG8_LDB(B1, 1, 1); PG8_SCHED; PG8_LDA(At, 1, 0); PG8_STAGE(PG8_SA(0, 1), a2 + hstep, voffA);
;             PG8_WAIT_V(8); PG8_WAIT_L(0); PG8_BAR; PG8_MMA(0, 0, At, B0); PG8_MMA(0, 1, At, B1); PG8_BAR; PG8_SCHED;
;             PG8_LDA(At, 1, 1); PG8_STAGE(PG8_SB(1, 0), b3, voffB); PG8_STAGE(PG8_SB(1, 1), b3 + hstep, voffB); PG8_STAGE(PG8_SA(1, 0), a3, voffA);
;             PG8_WAIT_V(8); PG8_WAIT_L(0); PG8_BAR; PG8_MMA(1, 0, At, B0); PG8_MMA(1, 1, At, B1); PG8_BAR; PG8_SCHED;
;         }
.LBB0_325:
	s_or_b64 exec, exec, s[50:51]
	s_ashr_i32 s39, s38, 31
	s_lshl_b64 s[50:51], s[38:39], 19
	s_add_u32 s50, s85, s50
	s_addc_u32 s51, s86, s51
	s_and_b64 s[54:55], s[4:5], exec
	s_cselect_b32 s39, s51, s63
	s_cselect_b32 s74, s50, s62
	s_ashr_i32 s23, s22, 31
	s_lshl_b64 s[54:55], s[22:23], 19
	s_add_u32 s54, s46, s54
	s_addc_u32 s55, s47, s55
	s_and_b64 s[66:67], s[4:5], exec
	s_cselect_b32 s23, s55, s65
	s_cselect_b32 s75, s54, s64
	s_add_u32 s62, s62, 0x40080
	s_addc_u32 s63, s63, 0
	s_add_u32 s78, s64, 0x100
	s_addc_u32 s79, s65, 0
	s_mov_b32 s81, -2
	s_waitcnt lgkmcnt(0)
	s_add_u32 s64, s62, 0xfffc0080
	s_addc_u32 s65, s63, -1
	s_add_i32 s82, 0, 0x10000
	s_cmp_eq_u32 s81, 12
	s_cselect_b32 s67, s39, s65
	s_cselect_b32 s66, s74, s64
	v_add_u32_e32 v69, s82, v154
	s_cselect_b32 s65, s23, s79
	s_cselect_b32 s64, s75, s78
	s_add_i32 s90, 0, 0x14000
	ds_read_b128 v[70:73], v69
	ds_read_b128 v[74:77], v69 offset:1024
	ds_read_b128 v[172:175], v69 offset:2048
	ds_read_b128 v[176:179], v69 offset:3072
	v_add_u32_e32 v69, s90, v154
	ds_read_b128 v[180:183], v69
	ds_read_b128 v[184:187], v69 offset:1024
	ds_read_b128 v[188:191], v69 offset:2048
	ds_read_b128 v[198:201], v69 offset:3072
	v_lshl_add_u64 v[78:79], s[62:63], 0, v[144:145]
	s_add_i32 m0, s53, 0xc000
	ds_read_b128 v[202:205], v171
	ds_read_b128 v[206:209], v171 offset:1024
	ds_read_b128 v[210:213], v171 offset:2048
	ds_read_b128 v[214:217], v171 offset:3072
	ds_read_b128 v[218:221], v171 offset:4096
	ds_read_b128 v[230:233], v171 offset:5120
	ds_read_b128 v[234:237], v171 offset:6144
	ds_read_b128 v[238:241], v171 offset:7168
	global_load_lds_dwordx4 v[78:79], off
	v_lshl_add_u64 v[78:79], s[62:63], 0, v[146:147]
	s_add_i32 m0, s53, 0xe000
	s_nop 0
	global_load_lds_dwordx4 v[78:79], off
	s_waitcnt vmcnt(8)
	s_waitcnt lgkmcnt(0)
	s_barrier
	s_waitcnt lgkmcnt(0)
	v_mfma_f32_16x16x32_bf16 v[140:143], v[70:73], v[202:205], 0
	v_mfma_f32_16x16x32_bf16 v[136:139], v[172:175], v[202:205], 0
	v_mfma_f32_16x16x32_bf16 v[132:135], v[70:73], v[210:213], 0
	v_mfma_f32_16x16x32_bf16 v[128:131], v[172:175], v[210:213], 0
	v_mfma_f32_16x16x32_bf16 v[116:119], v[70:73], v[218:221], 0
	v_mfma_f32_16x16x32_bf16 v[112:115], v[172:175], v[218:221], 0
	v_mfma_f32_16x16x32_bf16 v[100:103], v[70:73], v[234:237], 0
	v_mfma_f32_16x16x32_bf16 v[96:99], v[172:175], v[234:237], 0
	v_mfma_f32_16x16x32_bf16 v[140:143], v[74:77], v[206:209], v[140:143]
	v_mfma_f32_16x16x32_bf16 v[136:139], v[176:179], v[206:209], v[136:139]
	v_mfma_f32_16x16x32_bf16 v[132:135], v[74:77], v[214:217], v[132:135]
	v_mfma_f32_16x16x32_bf16 v[128:131], v[176:179], v[214:217], v[128:131]
	v_mfma_f32_16x16x32_bf16 v[116:119], v[74:77], v[230:233], v[116:119]
	v_mfma_f32_16x16x32_bf16 v[112:115], v[176:179], v[230:233], v[112:115]
	v_mfma_f32_16x16x32_bf16 v[100:103], v[74:77], v[238:241], v[100:103]
	v_mfma_f32_16x16x32_bf16 v[96:99], v[176:179], v[238:241], v[96:99]
	v_mfma_f32_16x16x32_bf16 v[124:127], v[180:183], v[202:205], 0
	v_mfma_f32_16x16x32_bf16 v[120:123], v[188:191], v[202:205], 0
	v_mfma_f32_16x16x32_bf16 v[108:111], v[180:183], v[210:213], 0
	v_mfma_f32_16x16x32_bf16 v[104:107], v[188:191], v[210:213], 0
	v_mfma_f32_16x16x32_bf16 v[92:95], v[180:183], v[218:221], 0
	v_mfma_f32_16x16x32_bf16 v[88:91], v[188:191], v[218:221], 0
	v_mfma_f32_16x16x32_bf16 v[84:87], v[180:183], v[234:237], 0
	v_mfma_f32_16x16x32_bf16 v[78:81], v[188:191], v[234:237], 0
	v_mfma_f32_16x16x32_bf16 v[124:127], v[184:187], v[206:209], v[124:127]
	v_mfma_f32_16x16x32_bf16 v[120:123], v[198:201], v[206:209], v[120:123]
	v_mfma_f32_16x16x32_bf16 v[108:111], v[184:187], v[214:217], v[108:111]
	v_mfma_f32_16x16x32_bf16 v[104:107], v[198:201], v[214:217], v[104:107]
	v_mfma_f32_16x16x32_bf16 v[92:95], v[184:187], v[230:233], v[92:95]
	v_mfma_f32_16x16x32_bf16 v[88:91], v[198:201], v[230:233], v[88:91]
	v_mfma_f32_16x16x32_bf16 v[84:87], v[184:187], v[238:241], v[84:87]
	v_mfma_f32_16x16x32_bf16 v[78:81], v[198:201], v[238:241], v[78:81]
	s_barrier
	s_add_i32 s82, s82, s52
	v_lshl_add_u64 v[224:225], s[64:65], 0, v[164:165]
	s_mov_b32 m0, s82
	ds_read_b128 v[202:205], v171 offset:16384
	ds_read_b128 v[206:209], v171 offset:17408
	ds_read_b128 v[210:213], v171 offset:18432
	ds_read_b128 v[214:217], v171 offset:19456
	ds_read_b128 v[218:221], v171 offset:20480
	ds_read_b128 v[230:233], v171 offset:21504
	ds_read_b128 v[234:237], v171 offset:22528
	ds_read_b128 v[238:241], v171 offset:23552
	global_load_lds_dwordx4 v[224:225], off
	s_add_i32 m0, s82, 0x2000
	s_add_u32 s82, s64, 0x40000
	v_lshl_add_u64 v[226:227], s[64:65], 0, v[168:169]
	s_addc_u32 s83, s65, 0
	s_add_i32 s90, s90, s52
	global_load_lds_dwordx4 v[226:227], off
	v_lshl_add_u64 v[82:83], s[82:83], 0, v[164:165]
	s_mov_b32 m0, s90
	v_lshl_add_u64 v[242:243], s[66:67], 0, v[162:163]
	global_load_lds_dwordx4 v[82:83], off
	v_lshl_add_u64 v[82:83], s[82:83], 0, v[168:169]
	s_add_i32 m0, s90, 0x2000
	v_lshl_add_u64 v[244:245], s[66:67], 0, v[166:167]
	global_load_lds_dwordx4 v[82:83], off
	s_mov_b32 m0, s53
	s_nop 0
	global_load_lds_dwordx4 v[242:243], off
	s_mov_b32 m0, s56
	s_nop 0
	global_load_lds_dwordx4 v[244:245], off
	s_waitcnt vmcnt(8)
	s_waitcnt lgkmcnt(0)
	s_barrier
; #define PG8_STAGE(bufoff, gbase, voff) do { _Pragma("unroll") for (int _i = 0; _i < 2; ++_i) \
;         __builtin_amdgcn_global_load_lds((const unsigned*)((const char*)(gbase) + (voff)[_i]), (LAS unsigned*)(lds + (bufoff) + ldsw + _i * 8192), 16, 0, 0); } while (0)
; #define PG8_LDA(dst, b, h) do { _Pragma("unroll") for (int m = 0; m < 4; ++m) _Pragma("unroll") for (int k = 0; k < 2; ++k) dst[m][k] = *(const LAS bf16x8*)(lds + PG8_SA(b, h) + aoff + m * 2048 + k * 1024); } while (0)
; #define PG8_LDB(dst, b, h) do { _Pragma("unroll") for (int n = 0; n < 2; ++n) _Pragma("unroll") for (int k = 0; k < 2; ++k) dst[n][k] = *(const LAS bf16x8*)(lds + PG8_SB(b, h) + boff + n * 2048 + k * 1024); } while (0)
; #define PG8_WAIT_V(n) asm volatile("s_waitcnt vmcnt(" #n ")" ::: "memory")
; #define PG8_BAR __builtin_amdgcn_s_barrier()
; template <class Epi, class Sched>
; __device__ __forceinline__ void gemm_phase(LAS unsigned char* lds, const Gemm g, const Sched& S, const Epi& E, const int tid) {
;     ...
;         for (int t = 0; t < nt; t += 2) {
;             const bool last = (t == nt - 2);
;             const char* a1 = cA + (size_t)(t + 1) * kstep;
;             const char* a2 = last ? nA : cA + (size_t)(t + 2) * kstep; const char* b2 = last ? nB : cB + (size_t)(t + 2) * kstep;
;             const char* a3 = a2 + kstep; const char* b3 = b2 + kstep;
;             PG8_LDB(B0, 0, 0); PG8_LDB(B1, 0, 1); PG8_SCHED; PG8_LDA(At, 0, 0); PG8_STAGE(PG8_SA(1, 1), a1 + hstep, voffA);
;             PG8_WAIT_V(8); PG8_WAIT_L(0); PG8_BAR; PG8_MMA(0, 0, At, B0); PG8_MMA(0, 1, At, B1); PG8_BAR; PG8_SCHED;
;             PG8_LDA(At, 0, 1); PG8_STAGE(PG8_SB(0, 0), b2, voffB); PG8_STAGE(PG8_SB(0, 1), b2 + hstep, voffB); PG8_STAGE(PG8_SA(0, 0), a2, voffA);
;             PG8_WAIT_V(8); PG8_WAIT_L(0); PG8_BAR; PG8_MMA(1, 0, At, B0); PG8_MMA(1, 1, At, B1); PG8_BAR; PG8_SCHED;
;             PG8_LDB(B0, 1, 0); PG8_LDB(B1, 1, 1); PG8_SCHED; PG8_LDA(At, 1, 0); PG8_STAGE(PG8_SA(0, 1), a2 + hstep, voffA);
;             PG8_WAIT_V(8); PG8_WAIT_L(0); PG8_BAR; PG8_MMA(0, 0, At, B0); PG8_MMA(0, 1, At, B1); PG8_BAR; PG8_SCHED;
;             PG8_LDA(At, 1, 1); PG8_STAGE(PG8_SB(1, 0), b3, voffB); PG8_STAGE(PG8_SB(1, 1), b3 + hstep, voffB); PG8_STAGE(PG8_SA(1, 0), a3, voffA);
;             PG8_WAIT_V(8); PG8_WAIT_L(0); PG8_BAR; PG8_MMA(1, 0, At, B0); PG8_MMA(1, 1, At, B1); PG8_BAR; PG8_SCHED;
;         }
	s_waitcnt lgkmcnt(0)
	v_mfma_f32_16x16x32_bf16 v[60:63], v[70:73], v[202:205], 0
	v_mfma_f32_16x16x32_bf16 v[56:59], v[172:175], v[202:205], 0
	v_mfma_f32_16x16x32_bf16 v[52:55], v[70:73], v[210:213], 0
	v_mfma_f32_16x16x32_bf16 v[44:47], v[172:175], v[210:213], 0
	v_mfma_f32_16x16x32_bf16 v[28:31], v[70:73], v[218:221], 0
	v_mfma_f32_16x16x32_bf16 v[24:27], v[172:175], v[218:221], 0
	v_mfma_f32_16x16x32_bf16 v[16:19], v[70:73], v[234:237], 0
	v_mfma_f32_16x16x32_bf16 v[8:11], v[172:175], v[234:237], 0
	v_mfma_f32_16x16x32_bf16 v[60:63], v[74:77], v[206:209], v[60:63]
	v_mfma_f32_16x16x32_bf16 v[56:59], v[176:179], v[206:209], v[56:59]
	v_mfma_f32_16x16x32_bf16 v[52:55], v[74:77], v[214:217], v[52:55]
	v_mfma_f32_16x16x32_bf16 v[44:47], v[176:179], v[214:217], v[44:47]
	v_mfma_f32_16x16x32_bf16 v[28:31], v[74:77], v[230:233], v[28:31]
	v_mfma_f32_16x16x32_bf16 v[24:27], v[176:179], v[230:233], v[24:27]
	v_mfma_f32_16x16x32_bf16 v[16:19], v[74:77], v[238:241], v[16:19]
	v_mfma_f32_16x16x32_bf16 v[8:11], v[176:179], v[238:241], v[8:11]
	v_mfma_f32_16x16x32_bf16 v[48:51], v[180:183], v[202:205], 0
	v_mfma_f32_16x16x32_bf16 v[40:43], v[188:191], v[202:205], 0
	v_mfma_f32_16x16x32_bf16 v[36:39], v[180:183], v[210:213], 0
	v_mfma_f32_16x16x32_bf16 v[32:35], v[188:191], v[210:213], 0
	v_mfma_f32_16x16x32_bf16 v[20:23], v[180:183], v[218:221], 0
	v_mfma_f32_16x16x32_bf16 v[12:15], v[188:191], v[218:221], 0
	v_mfma_f32_16x16x32_bf16 v[4:7], v[180:183], v[234:237], 0
	v_mfma_f32_16x16x32_bf16 v[0:3], v[188:191], v[234:237], 0
	v_mfma_f32_16x16x32_bf16 v[48:51], v[184:187], v[206:209], v[48:51]
	v_mfma_f32_16x16x32_bf16 v[40:43], v[198:201], v[206:209], v[40:43]
	v_mfma_f32_16x16x32_bf16 v[36:39], v[184:187], v[214:217], v[36:39]
	v_mfma_f32_16x16x32_bf16 v[32:35], v[198:201], v[214:217], v[32:35]
	v_mfma_f32_16x16x32_bf16 v[20:23], v[184:187], v[230:233], v[20:23]
	v_mfma_f32_16x16x32_bf16 v[12:15], v[198:201], v[230:233], v[12:15]
	v_mfma_f32_16x16x32_bf16 v[4:7], v[184:187], v[238:241], v[4:7]
	v_mfma_f32_16x16x32_bf16 v[0:3], v[198:201], v[238:241], v[0:3]
	s_barrier
	s_add_i32 s82, 0, 0x18000
	v_add_u32_e32 v69, s82, v154
	s_add_i32 s83, 0, 0x1c000
	ds_read_b128 v[70:73], v69
	ds_read_b128 v[74:77], v69 offset:1024
	ds_read_b128 v[172:175], v69 offset:2048
	ds_read_b128 v[176:179], v69 offset:3072
	v_add_u32_e32 v69, s83, v154
	ds_read_b128 v[180:183], v69
	ds_read_b128 v[184:187], v69 offset:1024
	ds_read_b128 v[188:191], v69 offset:2048
	ds_read_b128 v[198:201], v69 offset:3072
	s_add_u32 s66, s66, 0x40000
	s_addc_u32 s67, s67, 0
	s_mov_b32 m0, s57
	v_lshl_add_u64 v[82:83], s[66:67], 0, v[162:163]
	ds_read_b128 v[202:205], v171 offset:32768
	ds_read_b128 v[206:209], v171 offset:33792
	ds_read_b128 v[210:213], v171 offset:34816
	ds_read_b128 v[214:217], v171 offset:35840
	ds_read_b128 v[218:221], v171 offset:36864
	ds_read_b128 v[230:233], v171 offset:37888
	ds_read_b128 v[234:237], v171 offset:38912
	ds_read_b128 v[238:241], v171 offset:39936
	global_load_lds_dwordx4 v[82:83], off
	v_lshl_add_u64 v[82:83], s[66:67], 0, v[166:167]
	s_mov_b32 m0, s58
	s_nop 0
	global_load_lds_dwordx4 v[82:83], off
	s_waitcnt vmcnt(8)
	s_waitcnt lgkmcnt(0)
	s_barrier
	s_waitcnt lgkmcnt(0)
	v_mfma_f32_16x16x32_bf16 v[140:143], v[70:73], v[202:205], v[140:143]
	v_mfma_f32_16x16x32_bf16 v[136:139], v[172:175], v[202:205], v[136:139]
	v_mfma_f32_16x16x32_bf16 v[132:135], v[70:73], v[210:213], v[132:135]
	v_mfma_f32_16x16x32_bf16 v[128:131], v[172:175], v[210:213], v[128:131]
	v_mfma_f32_16x16x32_bf16 v[116:119], v[70:73], v[218:221], v[116:119]
	v_mfma_f32_16x16x32_bf16 v[112:115], v[172:175], v[218:221], v[112:115]
	v_mfma_f32_16x16x32_bf16 v[100:103], v[70:73], v[234:237], v[100:103]
	v_mfma_f32_16x16x32_bf16 v[96:99], v[172:175], v[234:237], v[96:99]
	v_mfma_f32_16x16x32_bf16 v[140:143], v[74:77], v[206:209], v[140:143]
	v_mfma_f32_16x16x32_bf16 v[136:139], v[176:179], v[206:209], v[136:139]
	v_mfma_f32_16x16x32_bf16 v[132:135], v[74:77], v[214:217], v[132:135]
	v_mfma_f32_16x16x32_bf16 v[128:131], v[176:179], v[214:217], v[128:131]
	v_mfma_f32_16x16x32_bf16 v[116:119], v[74:77], v[230:233], v[116:119]
	v_mfma_f32_16x16x32_bf16 v[112:115], v[176:179], v[230:233], v[112:115]
	v_mfma_f32_16x16x32_bf16 v[100:103], v[74:77], v[238:241], v[100:103]
	v_mfma_f32_16x16x32_bf16 v[96:99], v[176:179], v[238:241], v[96:99]
	v_mfma_f32_16x16x32_bf16 v[124:127], v[180:183], v[202:205], v[124:127]
	v_mfma_f32_16x16x32_bf16 v[120:123], v[188:191], v[202:205], v[120:123]
	v_mfma_f32_16x16x32_bf16 v[108:111], v[180:183], v[210:213], v[108:111]
	v_mfma_f32_16x16x32_bf16 v[104:107], v[188:191], v[210:213], v[104:107]
	v_mfma_f32_16x16x32_bf16 v[92:95], v[180:183], v[218:221], v[92:95]
	v_mfma_f32_16x16x32_bf16 v[88:91], v[188:191], v[218:221], v[88:91]
	v_mfma_f32_16x16x32_bf16 v[82:85], v[180:183], v[234:237], v[84:87]
	v_mfma_f32_16x16x32_bf16 v[78:81], v[188:191], v[234:237], v[78:81]
	v_mfma_f32_16x16x32_bf16 v[124:127], v[184:187], v[206:209], v[124:127]
	v_mfma_f32_16x16x32_bf16 v[120:123], v[198:201], v[206:209], v[120:123]
	v_mfma_f32_16x16x32_bf16 v[108:111], v[184:187], v[214:217], v[108:111]
	v_mfma_f32_16x16x32_bf16 v[104:107], v[198:201], v[214:217], v[104:107]
	v_mfma_f32_16x16x32_bf16 v[92:95], v[184:187], v[230:233], v[92:95]
	v_mfma_f32_16x16x32_bf16 v[88:91], v[198:201], v[230:233], v[88:91]
	v_mfma_f32_16x16x32_bf16 v[84:87], v[184:187], v[238:241], v[82:85]
	v_mfma_f32_16x16x32_bf16 v[80:83], v[198:201], v[238:241], v[78:81]
	s_barrier
; #define PG8_STAGE(bufoff, gbase, voff) do { _Pragma("unroll") for (int _i = 0; _i < 2; ++_i) \
;         __builtin_amdgcn_global_load_lds((const unsigned*)((const char*)(gbase) + (voff)[_i]), (LAS unsigned*)(lds + (bufoff) + ldsw + _i * 8192), 16, 0, 0); } while (0)
; #define PG8_LDA(dst, b, h) do { _Pragma("unroll") for (int m = 0; m < 4; ++m) _Pragma("unroll") for (int k = 0; k < 2; ++k) dst[m][k] = *(const LAS bf16x8*)(lds + PG8_SA(b, h) + aoff + m * 2048 + k * 1024); } while (0)
; #define PG8_LDB(dst, b, h) do { _Pragma("unroll") for (int n = 0; n < 2; ++n) _Pragma("unroll") for (int k = 0; k < 2; ++k) dst[n][k] = *(const LAS bf16x8*)(lds + PG8_SB(b, h) + boff + n * 2048 + k * 1024); } while (0)
; #define PG8_WAIT_V(n) asm volatile("s_waitcnt vmcnt(" #n ")" ::: "memory")
; #define PG8_BAR __builtin_amdgcn_s_barrier()
; template <class Epi, class Sched>
; __device__ __forceinline__ void gemm_phase(LAS unsigned char* lds, const Gemm g, const Sched& S, const Epi& E, const int tid) {
;     ...
;         for (int t = 0; t < nt; t += 2) {
;             const bool last = (t == nt - 2);
;             const char* a1 = cA + (size_t)(t + 1) * kstep;
;             const char* a2 = last ? nA : cA + (size_t)(t + 2) * kstep; const char* b2 = last ? nB : cB + (size_t)(t + 2) * kstep;
;             const char* a3 = a2 + kstep; const char* b3 = b2 + kstep;
;             PG8_LDB(B0, 0, 0); PG8_LDB(B1, 0, 1); PG8_SCHED; PG8_LDA(At, 0, 0); PG8_STAGE(PG8_SA(1, 1), a1 + hstep, voffA);
;             PG8_WAIT_V(8); PG8_WAIT_L(0); PG8_BAR; PG8_MMA(0, 0, At, B0); PG8_MMA(0, 1, At, B1); PG8_BAR; PG8_SCHED;
;             PG8_LDA(At, 0, 1); PG8_STAGE(PG8_SB(0, 0), b2, voffB); PG8_STAGE(PG8_SB(0, 1), b2 + hstep, voffB); PG8_STAGE(PG8_SA(0, 0), a2, voffA);
;             PG8_WAIT_V(8); PG8_WAIT_L(0); PG8_BAR; PG8_MMA(1, 0, At, B0); PG8_MMA(1, 1, At, B1); PG8_BAR; PG8_SCHED;
;             PG8_LDB(B0, 1, 0); PG8_LDB(B1, 1, 1); PG8_SCHED; PG8_LDA(At, 1, 0); PG8_STAGE(PG8_SA(0, 1), a2 + hstep, voffA);
;             PG8_WAIT_V(8); PG8_WAIT_L(0); PG8_BAR; PG8_MMA(0, 0, At, B0); PG8_MMA(0, 1, At, B1); PG8_BAR; PG8_SCHED;
;             PG8_LDA(At, 1, 1); PG8_STAGE(PG8_SB(1, 0), b3, voffB); PG8_STAGE(PG8_SB(1, 1), b3 + hstep, voffB); PG8_STAGE(PG8_SA(1, 0), a3, voffA);
;             PG8_WAIT_V(8); PG8_WAIT_L(0); PG8_BAR; PG8_MMA(1, 0, At, B0); PG8_MMA(1, 1, At, B1); PG8_BAR; PG8_SCHED;
;         }
	s_add_i32 s66, s82, s52
	v_lshl_add_u64 v[78:79], v[224:225], 0, s[68:69]
	s_mov_b32 m0, s66
	ds_read_b128 v[202:205], v171 offset:49152
	ds_read_b128 v[206:209], v171 offset:50176
	ds_read_b128 v[210:213], v171 offset:51200
	ds_read_b128 v[214:217], v171 offset:52224
	ds_read_b128 v[218:221], v171 offset:53248
	ds_read_b128 v[230:233], v171 offset:54272
	ds_read_b128 v[234:237], v171 offset:55296
	ds_read_b128 v[238:241], v171 offset:56320
	global_load_lds_dwordx4 v[78:79], off
	s_add_i32 m0, s66, 0x2000
	s_add_u32 s64, s64, 0x40080
	v_lshl_add_u64 v[78:79], v[226:227], 0, s[68:69]
	s_addc_u32 s65, s65, 0
	s_add_i32 s66, s83, s52
	global_load_lds_dwordx4 v[78:79], off
	v_lshl_add_u64 v[78:79], s[64:65], 0, v[164:165]
	s_mov_b32 m0, s66
	s_nop 0
	global_load_lds_dwordx4 v[78:79], off
	v_lshl_add_u64 v[78:79], s[64:65], 0, v[168:169]
	s_add_i32 m0, s66, 0x2000
	s_nop 0
	global_load_lds_dwordx4 v[78:79], off
	v_lshl_add_u64 v[78:79], v[242:243], 0, s[68:69]
	s_mov_b32 m0, s61
	s_nop 0
	global_load_lds_dwordx4 v[78:79], off
	v_lshl_add_u64 v[78:79], v[244:245], 0, s[68:69]
	s_mov_b32 m0, s70
	s_nop 0
	global_load_lds_dwordx4 v[78:79], off
	s_waitcnt vmcnt(8)
	s_waitcnt lgkmcnt(0)
	s_barrier
	s_waitcnt lgkmcnt(0)
	v_mfma_f32_16x16x32_bf16 v[60:63], v[70:73], v[202:205], v[60:63]
	v_mfma_f32_16x16x32_bf16 v[56:59], v[172:175], v[202:205], v[56:59]
	v_mfma_f32_16x16x32_bf16 v[52:55], v[70:73], v[210:213], v[52:55]
	v_mfma_f32_16x16x32_bf16 v[44:47], v[172:175], v[210:213], v[44:47]
	v_mfma_f32_16x16x32_bf16 v[28:31], v[70:73], v[218:221], v[28:31]
	v_mfma_f32_16x16x32_bf16 v[24:27], v[172:175], v[218:221], v[24:27]
	v_mfma_f32_16x16x32_bf16 v[16:19], v[70:73], v[234:237], v[16:19]
	v_mfma_f32_16x16x32_bf16 v[8:11], v[172:175], v[234:237], v[8:11]
	v_mfma_f32_16x16x32_bf16 v[60:63], v[74:77], v[206:209], v[60:63]
	v_mfma_f32_16x16x32_bf16 v[56:59], v[176:179], v[206:209], v[56:59]
	v_mfma_f32_16x16x32_bf16 v[52:55], v[74:77], v[214:217], v[52:55]
	v_mfma_f32_16x16x32_bf16 v[44:47], v[176:179], v[214:217], v[44:47]
	v_mfma_f32_16x16x32_bf16 v[28:31], v[74:77], v[230:233], v[28:31]
	v_mfma_f32_16x16x32_bf16 v[24:27], v[176:179], v[230:233], v[24:27]
	v_mfma_f32_16x16x32_bf16 v[16:19], v[74:77], v[238:241], v[16:19]
	v_mfma_f32_16x16x32_bf16 v[8:11], v[176:179], v[238:241], v[8:11]
	v_mfma_f32_16x16x32_bf16 v[48:51], v[180:183], v[202:205], v[48:51]
	v_mfma_f32_16x16x32_bf16 v[40:43], v[188:191], v[202:205], v[40:43]
	v_mfma_f32_16x16x32_bf16 v[36:39], v[180:183], v[210:213], v[36:39]
	v_mfma_f32_16x16x32_bf16 v[32:35], v[188:191], v[210:213], v[32:35]
	v_mfma_f32_16x16x32_bf16 v[20:23], v[180:183], v[218:221], v[20:23]
	v_mfma_f32_16x16x32_bf16 v[12:15], v[188:191], v[218:221], v[12:15]
	v_mfma_f32_16x16x32_bf16 v[4:7], v[180:183], v[234:237], v[4:7]
	v_mfma_f32_16x16x32_bf16 v[0:3], v[188:191], v[234:237], v[0:3]
	v_mfma_f32_16x16x32_bf16 v[48:51], v[184:187], v[206:209], v[48:51]
	v_mfma_f32_16x16x32_bf16 v[40:43], v[198:201], v[206:209], v[40:43]
	v_mfma_f32_16x16x32_bf16 v[36:39], v[184:187], v[214:217], v[36:39]
	v_mfma_f32_16x16x32_bf16 v[32:35], v[198:201], v[214:217], v[32:35]
	v_mfma_f32_16x16x32_bf16 v[20:23], v[184:187], v[230:233], v[20:23]
	v_mfma_f32_16x16x32_bf16 v[12:15], v[198:201], v[230:233], v[12:15]
	v_mfma_f32_16x16x32_bf16 v[4:7], v[184:187], v[238:241], v[4:7]
	v_mfma_f32_16x16x32_bf16 v[0:3], v[198:201], v[238:241], v[0:3]
	s_barrier
	s_add_i32 s81, s81, 2
	s_add_u32 s62, s62, 0x100
	s_addc_u32 s63, s63, 0
	s_add_u32 s78, s78, 0x100
	s_addc_u32 s79, s79, 0
	s_cmp_gt_u32 s81, 13
.LBB0_326:
	s_add_u32 s64, s62, 0xfffc0080
	s_addc_u32 s65, s63, -1
	s_add_i32 s82, 0, 0x10000
	s_cmp_eq_u32 s81, 12
	s_cselect_b32 s67, s39, s65
	s_cselect_b32 s66, s74, s64
	v_add_u32_e32 v69, s82, v154
	s_cselect_b32 s65, s23, s79
	s_cselect_b32 s64, s75, s78
	s_add_i32 s90, 0, 0x14000
	ds_read_b128 v[70:73], v69
	ds_read_b128 v[74:77], v69 offset:1024
	ds_read_b128 v[172:175], v69 offset:2048
	ds_read_b128 v[176:179], v69 offset:3072
	v_add_u32_e32 v69, s90, v154
	ds_read_b128 v[180:183], v69
	ds_read_b128 v[184:187], v69 offset:1024
	ds_read_b128 v[188:191], v69 offset:2048
	ds_read_b128 v[198:201], v69 offset:3072
	v_lshl_add_u64 v[78:79], s[62:63], 0, v[144:145]
	s_add_i32 m0, s53, 0xc000
	ds_read_b128 v[202:205], v171
	ds_read_b128 v[206:209], v171 offset:1024
	ds_read_b128 v[210:213], v171 offset:2048
	ds_read_b128 v[214:217], v171 offset:3072
	ds_read_b128 v[218:221], v171 offset:4096
	ds_read_b128 v[230:233], v171 offset:5120
	ds_read_b128 v[234:237], v171 offset:6144
	ds_read_b128 v[238:241], v171 offset:7168
	global_load_lds_dwordx4 v[78:79], off
	v_lshl_add_u64 v[78:79], s[62:63], 0, v[146:147]
	s_add_i32 m0, s53, 0xe000
	s_nop 0
	global_load_lds_dwordx4 v[78:79], off
	s_waitcnt vmcnt(8)
	s_waitcnt lgkmcnt(0)
	s_barrier
; #define PG8_STAGE(bufoff, gbase, voff) do { _Pragma("unroll") for (int _i = 0; _i < 2; ++_i) \
;         __builtin_amdgcn_global_load_lds((const unsigned*)((const char*)(gbase) + (voff)[_i]), (LAS unsigned*)(lds + (bufoff) + ldsw + _i * 8192), 16, 0, 0); } while (0)
; #define PG8_LDA(dst, b, h) do { _Pragma("unroll") for (int m = 0; m < 4; ++m) _Pragma("unroll") for (int k = 0; k < 2; ++k) dst[m][k] = *(const LAS bf16x8*)(lds + PG8_SA(b, h) + aoff + m * 2048 + k * 1024); } while (0)
; #define PG8_LDB(dst, b, h) do { _Pragma("unroll") for (int n = 0; n < 2; ++n) _Pragma("unroll") for (int k = 0; k < 2; ++k) dst[n][k] = *(const LAS bf16x8*)(lds + PG8_SB(b, h) + boff + n * 2048 + k * 1024); } while (0)
; #define PG8_WAIT_V(n) asm volatile("s_waitcnt vmcnt(" #n ")" ::: "memory")
; #define PG8_BAR __builtin_amdgcn_s_barrier()
; template <class Epi, class Sched>
; __device__ __forceinline__ void gemm_phase(LAS unsigned char* lds, const Gemm g, const Sched& S, const Epi& E, const int tid) {
;     ...
;         for (int t = 0; t < nt; t += 2) {
;             const bool last = (t == nt - 2);
;             const char* a1 = cA + (size_t)(t + 1) * kstep;
;             const char* a2 = last ? nA : cA + (size_t)(t + 2) * kstep; const char* b2 = last ? nB : cB + (size_t)(t + 2) * kstep;
;             const char* a3 = a2 + kstep; const char* b3 = b2 + kstep;
;             PG8_LDB(B0, 0, 0); PG8_LDB(B1, 0, 1); PG8_SCHED; PG8_LDA(At, 0, 0); PG8_STAGE(PG8_SA(1, 1), a1 + hstep, voffA);
;             PG8_WAIT_V(8); PG8_WAIT_L(0); PG8_BAR; PG8_MMA(0, 0, At, B0); PG8_MMA(0, 1, At, B1); PG8_BAR; PG8_SCHED;
;             PG8_LDA(At, 0, 1); PG8_STAGE(PG8_SB(0, 0), b2, voffB); PG8_STAGE(PG8_SB(0, 1), b2 + hstep, voffB); PG8_STAGE(PG8_SA(0, 0), a2, voffA);
;             PG8_WAIT_V(8); PG8_WAIT_L(0); PG8_BAR; PG8_MMA(1, 0, At, B0); PG8_MMA(1, 1, At, B1); PG8_BAR; PG8_SCHED;
;             PG8_LDB(B0, 1, 0); PG8_LDB(B1, 1, 1); PG8_SCHED; PG8_LDA(At, 1, 0); PG8_STAGE(PG8_SA(0, 1), a2 + hstep, voffA);
;             PG8_WAIT_V(8); PG8_WAIT_L(0); PG8_BAR; PG8_MMA(0, 0, At, B0); PG8_MMA(0, 1, At, B1); PG8_BAR; PG8_SCHED;
;             PG8_LDA(At, 1, 1); PG8_STAGE(PG8_SB(1, 0), b3, voffB); PG8_STAGE(PG8_SB(1, 1), b3 + hstep, voffB); PG8_STAGE(PG8_SA(1, 0), a3, voffA);
;             PG8_WAIT_V(8); PG8_WAIT_L(0); PG8_BAR; PG8_MMA(1, 0, At, B0); PG8_MMA(1, 1, At, B1); PG8_BAR; PG8_SCHED;
;         }
	s_waitcnt lgkmcnt(0)
	v_mfma_f32_16x16x32_bf16 v[140:143], v[70:73], v[202:205], v[140:143]
	v_mfma_f32_16x16x32_bf16 v[136:139], v[172:175], v[202:205], v[136:139]
	v_mfma_f32_16x16x32_bf16 v[132:135], v[70:73], v[210:213], v[132:135]
	v_mfma_f32_16x16x32_bf16 v[128:131], v[172:175], v[210:213], v[128:131]
	v_mfma_f32_16x16x32_bf16 v[116:119], v[70:73], v[218:221], v[116:119]
	v_mfma_f32_16x16x32_bf16 v[112:115], v[172:175], v[218:221], v[112:115]
	v_mfma_f32_16x16x32_bf16 v[100:103], v[70:73], v[234:237], v[100:103]
	v_mfma_f32_16x16x32_bf16 v[96:99], v[172:175], v[234:237], v[96:99]
	v_mfma_f32_16x16x32_bf16 v[140:143], v[74:77], v[206:209], v[140:143]
	v_mfma_f32_16x16x32_bf16 v[136:139], v[176:179], v[206:209], v[136:139]
	v_mfma_f32_16x16x32_bf16 v[132:135], v[74:77], v[214:217], v[132:135]
	v_mfma_f32_16x16x32_bf16 v[128:131], v[176:179], v[214:217], v[128:131]
	v_mfma_f32_16x16x32_bf16 v[116:119], v[74:77], v[230:233], v[116:119]
	v_mfma_f32_16x16x32_bf16 v[112:115], v[176:179], v[230:233], v[112:115]
	v_mfma_f32_16x16x32_bf16 v[100:103], v[74:77], v[238:241], v[100:103]
	v_mfma_f32_16x16x32_bf16 v[96:99], v[176:179], v[238:241], v[96:99]
	v_mfma_f32_16x16x32_bf16 v[124:127], v[180:183], v[202:205], v[124:127]
	v_mfma_f32_16x16x32_bf16 v[120:123], v[188:191], v[202:205], v[120:123]
	v_mfma_f32_16x16x32_bf16 v[108:111], v[180:183], v[210:213], v[108:111]
	v_mfma_f32_16x16x32_bf16 v[104:107], v[188:191], v[210:213], v[104:107]
	v_mfma_f32_16x16x32_bf16 v[92:95], v[180:183], v[218:221], v[92:95]
	v_mfma_f32_16x16x32_bf16 v[88:91], v[188:191], v[218:221], v[88:91]
	v_mfma_f32_16x16x32_bf16 v[84:87], v[180:183], v[234:237], v[84:87]
	v_mfma_f32_16x16x32_bf16 v[78:81], v[188:191], v[234:237], v[80:83]
	v_mfma_f32_16x16x32_bf16 v[124:127], v[184:187], v[206:209], v[124:127]
	v_mfma_f32_16x16x32_bf16 v[120:123], v[198:201], v[206:209], v[120:123]
	v_mfma_f32_16x16x32_bf16 v[108:111], v[184:187], v[214:217], v[108:111]
	v_mfma_f32_16x16x32_bf16 v[104:107], v[198:201], v[214:217], v[104:107]
	v_mfma_f32_16x16x32_bf16 v[92:95], v[184:187], v[230:233], v[92:95]
	v_mfma_f32_16x16x32_bf16 v[88:91], v[198:201], v[230:233], v[88:91]
	v_mfma_f32_16x16x32_bf16 v[84:87], v[184:187], v[238:241], v[84:87]
	v_mfma_f32_16x16x32_bf16 v[78:81], v[198:201], v[238:241], v[78:81]
	s_barrier
	s_add_i32 s82, s82, s52
	v_lshl_add_u64 v[224:225], s[64:65], 0, v[164:165]
	s_mov_b32 m0, s82
	ds_read_b128 v[202:205], v171 offset:16384
	ds_read_b128 v[206:209], v171 offset:17408
	ds_read_b128 v[210:213], v171 offset:18432
	ds_read_b128 v[214:217], v171 offset:19456
	ds_read_b128 v[218:221], v171 offset:20480
	ds_read_b128 v[230:233], v171 offset:21504
	ds_read_b128 v[234:237], v171 offset:22528
	ds_read_b128 v[238:241], v171 offset:23552
	global_load_lds_dwordx4 v[224:225], off
	s_add_i32 m0, s82, 0x2000
	s_add_u32 s82, s64, 0x40000
	v_lshl_add_u64 v[226:227], s[64:65], 0, v[168:169]
	s_addc_u32 s83, s65, 0
	s_add_i32 s90, s90, s52
	global_load_lds_dwordx4 v[226:227], off
	v_lshl_add_u64 v[82:83], s[82:83], 0, v[164:165]
	s_mov_b32 m0, s90
	v_lshl_add_u64 v[242:243], s[66:67], 0, v[162:163]
	global_load_lds_dwordx4 v[82:83], off
	v_lshl_add_u64 v[82:83], s[82:83], 0, v[168:169]
	s_add_i32 m0, s90, 0x2000
	v_lshl_add_u64 v[244:245], s[66:67], 0, v[166:167]
	global_load_lds_dwordx4 v[82:83], off
	s_mov_b32 m0, s53
	s_nop 0
	global_load_lds_dwordx4 v[242:243], off
	s_mov_b32 m0, s56
	s_nop 0
	global_load_lds_dwordx4 v[244:245], off
	s_waitcnt vmcnt(8)
	s_waitcnt lgkmcnt(0)
	s_barrier
	s_waitcnt lgkmcnt(0)
	v_mfma_f32_16x16x32_bf16 v[60:63], v[70:73], v[202:205], v[60:63]
	v_mfma_f32_16x16x32_bf16 v[56:59], v[172:175], v[202:205], v[56:59]
	v_mfma_f32_16x16x32_bf16 v[52:55], v[70:73], v[210:213], v[52:55]
	v_mfma_f32_16x16x32_bf16 v[44:47], v[172:175], v[210:213], v[44:47]
	v_mfma_f32_16x16x32_bf16 v[28:31], v[70:73], v[218:221], v[28:31]
	v_mfma_f32_16x16x32_bf16 v[24:27], v[172:175], v[218:221], v[24:27]
	v_mfma_f32_16x16x32_bf16 v[16:19], v[70:73], v[234:237], v[16:19]
	v_mfma_f32_16x16x32_bf16 v[8:11], v[172:175], v[234:237], v[8:11]
	v_mfma_f32_16x16x32_bf16 v[60:63], v[74:77], v[206:209], v[60:63]
	v_mfma_f32_16x16x32_bf16 v[56:59], v[176:179], v[206:209], v[56:59]
	v_mfma_f32_16x16x32_bf16 v[52:55], v[74:77], v[214:217], v[52:55]
	v_mfma_f32_16x16x32_bf16 v[44:47], v[176:179], v[214:217], v[44:47]
	v_mfma_f32_16x16x32_bf16 v[28:31], v[74:77], v[230:233], v[28:31]
	v_mfma_f32_16x16x32_bf16 v[24:27], v[176:179], v[230:233], v[24:27]
	v_mfma_f32_16x16x32_bf16 v[16:19], v[74:77], v[238:241], v[16:19]
	v_mfma_f32_16x16x32_bf16 v[8:11], v[176:179], v[238:241], v[8:11]
	v_mfma_f32_16x16x32_bf16 v[48:51], v[180:183], v[202:205], v[48:51]
	v_mfma_f32_16x16x32_bf16 v[40:43], v[188:191], v[202:205], v[40:43]
	v_mfma_f32_16x16x32_bf16 v[36:39], v[180:183], v[210:213], v[36:39]
	v_mfma_f32_16x16x32_bf16 v[32:35], v[188:191], v[210:213], v[32:35]
	v_mfma_f32_16x16x32_bf16 v[20:23], v[180:183], v[218:221], v[20:23]
	v_mfma_f32_16x16x32_bf16 v[12:15], v[188:191], v[218:221], v[12:15]
	v_mfma_f32_16x16x32_bf16 v[4:7], v[180:183], v[234:237], v[4:7]
	v_mfma_f32_16x16x32_bf16 v[0:3], v[188:191], v[234:237], v[0:3]
	v_mfma_f32_16x16x32_bf16 v[48:51], v[184:187], v[206:209], v[48:51]
	v_mfma_f32_16x16x32_bf16 v[40:43], v[198:201], v[206:209], v[40:43]
	v_mfma_f32_16x16x32_bf16 v[36:39], v[184:187], v[214:217], v[36:39]
	v_mfma_f32_16x16x32_bf16 v[32:35], v[198:201], v[214:217], v[32:35]
	v_mfma_f32_16x16x32_bf16 v[20:23], v[184:187], v[230:233], v[20:23]
	v_mfma_f32_16x16x32_bf16 v[12:15], v[198:201], v[230:233], v[12:15]
	v_mfma_f32_16x16x32_bf16 v[4:7], v[184:187], v[238:241], v[4:7]
	v_mfma_f32_16x16x32_bf16 v[0:3], v[198:201], v[238:241], v[0:3]
	s_barrier
; #define PG8_STAGE(bufoff, gbase, voff) do { _Pragma("unroll") for (int _i = 0; _i < 2; ++_i) \
;         __builtin_amdgcn_global_load_lds((const unsigned*)((const char*)(gbase) + (voff)[_i]), (LAS unsigned*)(lds + (bufoff) + ldsw + _i * 8192), 16, 0, 0); } while (0)
; #define PG8_LDA(dst, b, h) do { _Pragma("unroll") for (int m = 0; m < 4; ++m) _Pragma("unroll") for (int k = 0; k < 2; ++k) dst[m][k] = *(const LAS bf16x8*)(lds + PG8_SA(b, h) + aoff + m * 2048 + k * 1024); } while (0)
; #define PG8_LDB(dst, b, h) do { _Pragma("unroll") for (int n = 0; n < 2; ++n) _Pragma("unroll") for (int k = 0; k < 2; ++k) dst[n][k] = *(const LAS bf16x8*)(lds + PG8_SB(b, h) + boff + n * 2048 + k * 1024); } while (0)
; #define PG8_WAIT_V(n) asm volatile("s_waitcnt vmcnt(" #n ")" ::: "memory")
; #define PG8_BAR __builtin_amdgcn_s_barrier()
; template <class Epi, class Sched>
; __device__ __forceinline__ void gemm_phase(LAS unsigned char* lds, const Gemm g, const Sched& S, const Epi& E, const int tid) {
;     ...
;         for (int t = 0; t < nt; t += 2) {
;             const bool last = (t == nt - 2);
;             const char* a1 = cA + (size_t)(t + 1) * kstep;
;             const char* a2 = last ? nA : cA + (size_t)(t + 2) * kstep; const char* b2 = last ? nB : cB + (size_t)(t + 2) * kstep;
;             const char* a3 = a2 + kstep; const char* b3 = b2 + kstep;
;             PG8_LDB(B0, 0, 0); PG8_LDB(B1, 0, 1); PG8_SCHED; PG8_LDA(At, 0, 0); PG8_STAGE(PG8_SA(1, 1), a1 + hstep, voffA);
;             PG8_WAIT_V(8); PG8_WAIT_L(0); PG8_BAR; PG8_MMA(0, 0, At, B0); PG8_MMA(0, 1, At, B1); PG8_BAR; PG8_SCHED;
;             PG8_LDA(At, 0, 1); PG8_STAGE(PG8_SB(0, 0), b2, voffB); PG8_STAGE(PG8_SB(0, 1), b2 + hstep, voffB); PG8_STAGE(PG8_SA(0, 0), a2, voffA);
;             PG8_WAIT_V(8); PG8_WAIT_L(0); PG8_BAR; PG8_MMA(1, 0, At, B0); PG8_MMA(1, 1, At, B1); PG8_BAR; PG8_SCHED;
;             PG8_LDB(B0, 1, 0); PG8_LDB(B1, 1, 1); PG8_SCHED; PG8_LDA(At, 1, 0); PG8_STAGE(PG8_SA(0, 1), a2 + hstep, voffA);
;             PG8_WAIT_V(8); PG8_WAIT_L(0); PG8_BAR; PG8_MMA(0, 0, At, B0); PG8_MMA(0, 1, At, B1); PG8_BAR; PG8_SCHED;
;             PG8_LDA(At, 1, 1); PG8_STAGE(PG8_SB(1, 0), b3, voffB); PG8_STAGE(PG8_SB(1, 1), b3 + hstep, voffB); PG8_STAGE(PG8_SA(1, 0), a3, voffA);
;             PG8_WAIT_V(8); PG8_WAIT_L(0); PG8_BAR; PG8_MMA(1, 0, At, B0); PG8_MMA(1, 1, At, B1); PG8_BAR; PG8_SCHED;
;         }
	s_add_i32 s82, 0, 0x18000
	v_add_u32_e32 v69, s82, v154
	s_add_i32 s83, 0, 0x1c000
	ds_read_b128 v[70:73], v69
	ds_read_b128 v[74:77], v69 offset:1024
	ds_read_b128 v[172:175], v69 offset:2048
	ds_read_b128 v[176:179], v69 offset:3072
	v_add_u32_e32 v69, s83, v154
	ds_read_b128 v[180:183], v69
	ds_read_b128 v[184:187], v69 offset:1024
	ds_read_b128 v[188:191], v69 offset:2048
	ds_read_b128 v[198:201], v69 offset:3072
	s_add_u32 s66, s66, 0x40000
	s_addc_u32 s67, s67, 0
	s_mov_b32 m0, s57
	v_lshl_add_u64 v[82:83], s[66:67], 0, v[162:163]
	ds_read_b128 v[202:205], v171 offset:32768
	ds_read_b128 v[206:209], v171 offset:33792
	ds_read_b128 v[210:213], v171 offset:34816
	ds_read_b128 v[214:217], v171 offset:35840
	ds_read_b128 v[218:221], v171 offset:36864
	ds_read_b128 v[230:233], v171 offset:37888
	ds_read_b128 v[234:237], v171 offset:38912
	ds_read_b128 v[238:241], v171 offset:39936
	global_load_lds_dwordx4 v[82:83], off
	v_lshl_add_u64 v[82:83], s[66:67], 0, v[166:167]
	s_mov_b32 m0, s58
	s_nop 0
	global_load_lds_dwordx4 v[82:83], off
	s_waitcnt vmcnt(8)
	s_waitcnt lgkmcnt(0)
	s_barrier
	s_waitcnt lgkmcnt(0)
	v_mfma_f32_16x16x32_bf16 v[140:143], v[70:73], v[202:205], v[140:143]
	v_mfma_f32_16x16x32_bf16 v[136:139], v[172:175], v[202:205], v[136:139]
	v_mfma_f32_16x16x32_bf16 v[132:135], v[70:73], v[210:213], v[132:135]
	v_mfma_f32_16x16x32_bf16 v[128:131], v[172:175], v[210:213], v[128:131]
	v_mfma_f32_16x16x32_bf16 v[116:119], v[70:73], v[218:221], v[116:119]
	v_mfma_f32_16x16x32_bf16 v[112:115], v[172:175], v[218:221], v[112:115]
	v_mfma_f32_16x16x32_bf16 v[100:103], v[70:73], v[234:237], v[100:103]
	v_mfma_f32_16x16x32_bf16 v[96:99], v[172:175], v[234:237], v[96:99]
	v_mfma_f32_16x16x32_bf16 v[140:143], v[74:77], v[206:209], v[140:143]
	v_mfma_f32_16x16x32_bf16 v[136:139], v[176:179], v[206:209], v[136:139]
	v_mfma_f32_16x16x32_bf16 v[132:135], v[74:77], v[214:217], v[132:135]
	v_mfma_f32_16x16x32_bf16 v[128:131], v[176:179], v[214:217], v[128:131]
	v_mfma_f32_16x16x32_bf16 v[116:119], v[74:77], v[230:233], v[116:119]
	v_mfma_f32_16x16x32_bf16 v[112:115], v[176:179], v[230:233], v[112:115]
	v_mfma_f32_16x16x32_bf16 v[100:103], v[74:77], v[238:241], v[100:103]
	v_mfma_f32_16x16x32_bf16 v[96:99], v[176:179], v[238:241], v[96:99]
	v_mfma_f32_16x16x32_bf16 v[124:127], v[180:183], v[202:205], v[124:127]
	v_mfma_f32_16x16x32_bf16 v[120:123], v[188:191], v[202:205], v[120:123]
	v_mfma_f32_16x16x32_bf16 v[108:111], v[180:183], v[210:213], v[108:111]
	v_mfma_f32_16x16x32_bf16 v[104:107], v[188:191], v[210:213], v[104:107]
	v_mfma_f32_16x16x32_bf16 v[92:95], v[180:183], v[218:221], v[92:95]
	v_mfma_f32_16x16x32_bf16 v[88:91], v[188:191], v[218:221], v[88:91]
	v_mfma_f32_16x16x32_bf16 v[82:85], v[180:183], v[234:237], v[84:87]
	v_mfma_f32_16x16x32_bf16 v[78:81], v[188:191], v[234:237], v[78:81]
	v_mfma_f32_16x16x32_bf16 v[124:127], v[184:187], v[206:209], v[124:127]
	v_mfma_f32_16x16x32_bf16 v[120:123], v[198:201], v[206:209], v[120:123]
	v_mfma_f32_16x16x32_bf16 v[108:111], v[184:187], v[214:217], v[108:111]
	v_mfma_f32_16x16x32_bf16 v[104:107], v[198:201], v[214:217], v[104:107]
	v_mfma_f32_16x16x32_bf16 v[92:95], v[184:187], v[230:233], v[92:95]
	v_mfma_f32_16x16x32_bf16 v[88:91], v[198:201], v[230:233], v[88:91]
	v_mfma_f32_16x16x32_bf16 v[84:87], v[184:187], v[238:241], v[82:85]
	v_mfma_f32_16x16x32_bf16 v[80:83], v[198:201], v[238:241], v[78:81]
	s_barrier
; #define PG8_STAGE(bufoff, gbase, voff) do { _Pragma("unroll") for (int _i = 0; _i < 2; ++_i) \
;         __builtin_amdgcn_global_load_lds((const unsigned*)((const char*)(gbase) + (voff)[_i]), (LAS unsigned*)(lds + (bufoff) + ldsw + _i * 8192), 16, 0, 0); } while (0)
; #define PG8_LDA(dst, b, h) do { _Pragma("unroll") for (int m = 0; m < 4; ++m) _Pragma("unroll") for (int k = 0; k < 2; ++k) dst[m][k] = *(const LAS bf16x8*)(lds + PG8_SA(b, h) + aoff + m * 2048 + k * 1024); } while (0)
; #define PG8_LDB(dst, b, h) do { _Pragma("unroll") for (int n = 0; n < 2; ++n) _Pragma("unroll") for (int k = 0; k < 2; ++k) dst[n][k] = *(const LAS bf16x8*)(lds + PG8_SB(b, h) + boff + n * 2048 + k * 1024); } while (0)
; #define PG8_WAIT_V(n) asm volatile("s_waitcnt vmcnt(" #n ")" ::: "memory")
; #define PG8_BAR __builtin_amdgcn_s_barrier()
; template <class Epi, class Sched>
; __device__ __forceinline__ void gemm_phase(LAS unsigned char* lds, const Gemm g, const Sched& S, const Epi& E, const int tid) {
;     ...
;         for (int t = 0; t < nt; t += 2) {
;             const bool last = (t == nt - 2);
;             const char* a1 = cA + (size_t)(t + 1) * kstep;
;             const char* a2 = last ? nA : cA + (size_t)(t + 2) * kstep; const char* b2 = last ? nB : cB + (size_t)(t + 2) * kstep;
;             const char* a3 = a2 + kstep; const char* b3 = b2 + kstep;
;             PG8_LDB(B0, 0, 0); PG8_LDB(B1, 0, 1); PG8_SCHED; PG8_LDA(At, 0, 0); PG8_STAGE(PG8_SA(1, 1), a1 + hstep, voffA);
;             PG8_WAIT_V(8); PG8_WAIT_L(0); PG8_BAR; PG8_MMA(0, 0, At, B0); PG8_MMA(0, 1, At, B1); PG8_BAR; PG8_SCHED;
;             PG8_LDA(At, 0, 1); PG8_STAGE(PG8_SB(0, 0), b2, voffB); PG8_STAGE(PG8_SB(0, 1), b2 + hstep, voffB); PG8_STAGE(PG8_SA(0, 0), a2, voffA);
;             PG8_WAIT_V(8); PG8_WAIT_L(0); PG8_BAR; PG8_MMA(1, 0, At, B0); PG8_MMA(1, 1, At, B1); PG8_BAR; PG8_SCHED;
;             PG8_LDB(B0, 1, 0); PG8_LDB(B1, 1, 1); PG8_SCHED; PG8_LDA(At, 1, 0); PG8_STAGE(PG8_SA(0, 1), a2 + hstep, voffA);
;             PG8_WAIT_V(8); PG8_WAIT_L(0); PG8_BAR; PG8_MMA(0, 0, At, B0); PG8_MMA(0, 1, At, B1); PG8_BAR; PG8_SCHED;
;             PG8_LDA(At, 1, 1); PG8_STAGE(PG8_SB(1, 0), b3, voffB); PG8_STAGE(PG8_SB(1, 1), b3 + hstep, voffB); PG8_STAGE(PG8_SA(1, 0), a3, voffA);
;             PG8_WAIT_V(8); PG8_WAIT_L(0); PG8_BAR; PG8_MMA(1, 0, At, B0); PG8_MMA(1, 1, At, B1); PG8_BAR; PG8_SCHED;
;         }
	s_add_i32 s66, s82, s52
	v_lshl_add_u64 v[78:79], v[224:225], 0, s[68:69]
	s_mov_b32 m0, s66
	ds_read_b128 v[202:205], v171 offset:49152
	ds_read_b128 v[206:209], v171 offset:50176
	ds_read_b128 v[210:213], v171 offset:51200
	ds_read_b128 v[214:217], v171 offset:52224
	ds_read_b128 v[218:221], v171 offset:53248
	ds_read_b128 v[230:233], v171 offset:54272
	ds_read_b128 v[234:237], v171 offset:55296
	ds_read_b128 v[238:241], v171 offset:56320
	global_load_lds_dwordx4 v[78:79], off
	s_add_i32 m0, s66, 0x2000
	s_add_u32 s64, s64, 0x40080
	v_lshl_add_u64 v[78:79], v[226:227], 0, s[68:69]
	s_addc_u32 s65, s65, 0
	s_add_i32 s66, s83, s52
	global_load_lds_dwordx4 v[78:79], off
	v_lshl_add_u64 v[78:79], s[64:65], 0, v[164:165]
	s_mov_b32 m0, s66
	s_nop 0
	global_load_lds_dwordx4 v[78:79], off
	v_lshl_add_u64 v[78:79], s[64:65], 0, v[168:169]
	s_add_i32 m0, s66, 0x2000
	s_nop 0
	global_load_lds_dwordx4 v[78:79], off
	v_lshl_add_u64 v[78:79], v[242:243], 0, s[68:69]
	s_mov_b32 m0, s61
	s_nop 0
	global_load_lds_dwordx4 v[78:79], off
	v_lshl_add_u64 v[78:79], v[244:245], 0, s[68:69]
	s_mov_b32 m0, s70
	s_nop 0
	global_load_lds_dwordx4 v[78:79], off
	s_waitcnt vmcnt(8)
	s_waitcnt lgkmcnt(0)
	s_barrier
	s_waitcnt lgkmcnt(0)
	v_mfma_f32_16x16x32_bf16 v[60:63], v[70:73], v[202:205], v[60:63]
	v_mfma_f32_16x16x32_bf16 v[56:59], v[172:175], v[202:205], v[56:59]
	v_mfma_f32_16x16x32_bf16 v[52:55], v[70:73], v[210:213], v[52:55]
	v_mfma_f32_16x16x32_bf16 v[44:47], v[172:175], v[210:213], v[44:47]
	v_mfma_f32_16x16x32_bf16 v[28:31], v[70:73], v[218:221], v[28:31]
	v_mfma_f32_16x16x32_bf16 v[24:27], v[172:175], v[218:221], v[24:27]
	v_mfma_f32_16x16x32_bf16 v[16:19], v[70:73], v[234:237], v[16:19]
	v_mfma_f32_16x16x32_bf16 v[8:11], v[172:175], v[234:237], v[8:11]
	v_mfma_f32_16x16x32_bf16 v[60:63], v[74:77], v[206:209], v[60:63]
	v_mfma_f32_16x16x32_bf16 v[56:59], v[176:179], v[206:209], v[56:59]
	v_mfma_f32_16x16x32_bf16 v[52:55], v[74:77], v[214:217], v[52:55]
	v_mfma_f32_16x16x32_bf16 v[44:47], v[176:179], v[214:217], v[44:47]
	v_mfma_f32_16x16x32_bf16 v[28:31], v[74:77], v[230:233], v[28:31]
	v_mfma_f32_16x16x32_bf16 v[24:27], v[176:179], v[230:233], v[24:27]
	v_mfma_f32_16x16x32_bf16 v[16:19], v[74:77], v[238:241], v[16:19]
	v_mfma_f32_16x16x32_bf16 v[8:11], v[176:179], v[238:241], v[8:11]
	v_mfma_f32_16x16x32_bf16 v[48:51], v[180:183], v[202:205], v[48:51]
	v_mfma_f32_16x16x32_bf16 v[40:43], v[188:191], v[202:205], v[40:43]
	v_mfma_f32_16x16x32_bf16 v[36:39], v[180:183], v[210:213], v[36:39]
	v_mfma_f32_16x16x32_bf16 v[32:35], v[188:191], v[210:213], v[32:35]
	v_mfma_f32_16x16x32_bf16 v[20:23], v[180:183], v[218:221], v[20:23]
	v_mfma_f32_16x16x32_bf16 v[12:15], v[188:191], v[218:221], v[12:15]
	v_mfma_f32_16x16x32_bf16 v[4:7], v[180:183], v[234:237], v[4:7]
	v_mfma_f32_16x16x32_bf16 v[0:3], v[188:191], v[234:237], v[0:3]
	v_mfma_f32_16x16x32_bf16 v[48:51], v[184:187], v[206:209], v[48:51]
	v_mfma_f32_16x16x32_bf16 v[40:43], v[198:201], v[206:209], v[40:43]
	v_mfma_f32_16x16x32_bf16 v[36:39], v[184:187], v[214:217], v[36:39]
	v_mfma_f32_16x16x32_bf16 v[32:35], v[198:201], v[214:217], v[32:35]
	v_mfma_f32_16x16x32_bf16 v[20:23], v[184:187], v[230:233], v[20:23]
	v_mfma_f32_16x16x32_bf16 v[12:15], v[198:201], v[230:233], v[12:15]
	v_mfma_f32_16x16x32_bf16 v[4:7], v[184:187], v[238:241], v[4:7]
	v_mfma_f32_16x16x32_bf16 v[0:3], v[198:201], v[238:241], v[0:3]
	s_barrier
	s_add_i32 s81, s81, 2
	s_add_u32 s62, s62, 0x100
	s_addc_u32 s63, s63, 0
	s_add_u32 s78, s78, 0x100
	s_addc_u32 s79, s79, 0
	s_cmp_gt_u32 s81, 13
	s_cbranch_scc0 .LBB0_326
	s_and_b64 vcc, exec, s[8:9]
	s_cbranch_vccz .LBB0_329
	s_barrier

; #define PG8_STAGE(bufoff, gbase, voff) do { _Pragma("unroll") for (int _i = 0; _i < 2; ++_i) \
;         __builtin_amdgcn_global_load_lds((const unsigned*)((const char*)(gbase) + (voff)[_i]), (LAS unsigned*)(lds + (bufoff) + ldsw + _i * 8192), 16, 0, 0); } while (0)
; #define PG8_WAIT_V(n) asm volatile("s_waitcnt vmcnt(" #n ")" ::: "memory")
; #define PG8_BAR __builtin_amdgcn_s_barrier()
; template <class Epi, class Sched>
; __device__ __forceinline__ void gemm_phase(LAS unsigned char* lds, const Gemm g, const Sched& S, const Epi& E, const int tid) {
;     ...
;     unsigned voffA[2], voffB[2];
; #pragma unroll
;     for (int i = 0; i < 2; ++i) { int R, C; stage_rc(tid * 16 + i * 8192, R, C); const int Rb = Epi::PERM ? ((R & ~31) + perm32(R & 31)) : R;
;         voffA[i] = (unsigned)(R * K + C) * 2u; voffB[i] = (unsigned)(Rb * K + C) * 2u; }
;     const size_t kstep = (size_t)(BK * 2);
;     const size_t hstep = (size_t)HALF * K * 2;
;     const size_t tstep = 2 * hstep;
;     const unsigned ldsw = (unsigned)wid * 1024u;
;     const int aoff = lds_byte(wr * 64 + fr, fq * 8), boff = lds_byte(wc * 32 + fr, fq * 8);
;     ...
;     Unit cur, nxt; int ui = 0;
;     if (!S.next(0, cur)) return;
;     f32x4 acc[2][2][4][2];
; #pragma unroll
;     for (int a = 0; a < 2; ++a)
; #pragma unroll
;         for (int b = 0; b < 2; ++b)
; #pragma unroll
;             for (int m = 0; m < 4; ++m)
; #pragma unroll
;                 for (int n = 0; n < 2; ++n) acc[a][b][m][n] = (f32x4){0.f, 0.f, 0.f, 0.f};
;     bf16x8 At[4][2], B0[2][2], B1[2][2];
;     const char* cA = (const char*)g.A + (size_t)cur.pm * tstep; const char* cB = (const char*)g.Bt + (size_t)cur.pn * tstep;
;     PG8_STAGE(PG8_SB(0, 0), cB, voffB); PG8_STAGE(PG8_SB(0, 1), cB + hstep, voffB); PG8_STAGE(PG8_SA(0, 0), cA, voffA); PG8_STAGE(PG8_SA(0, 1), cA + hstep, voffA);
;     if (wr == 1) PG8_BAR;
;     PG8_WAIT_V(2); PG8_BAR;
;     PG8_STAGE(PG8_SB(1, 0), cB + kstep, voffB); PG8_STAGE(PG8_SA(1, 0), cA + kstep, voffA); PG8_STAGE(PG8_SB(1, 1), cB + hstep + kstep, voffB);
;     PG8_WAIT_V(6); PG8_BAR;
.LBB0_546:
	v_readlane_b32 s6, v254, 13
	v_readlane_b32 s7, v254, 14
	s_andn2_b64 vcc, exec, s[6:7]
	v_readfirstlane_b32 s4, v229
	s_cbranch_vccnz .LBB0_676
	v_lshlrev_b32_e32 v230, 4, v229
	v_add_u32_e32 v0, 0x2000, v230
	s_waitcnt lgkmcnt(0)
	v_ashrrev_i32_e32 v1, 31, v0
	v_lshrrev_b32_e32 v1, 22, v1
	v_add_u32_e32 v1, v0, v1
	v_ashrrev_i32_e32 v1, 10, v1
	v_mul_i32_i24_e32 v2, 0x400, v1
	v_sub_u32_e32 v0, v0, v2
	v_lshrrev_b32_e32 v2, 4, v0
	v_bitop3_b32 v0, v2, v0, 32 bitop3:0x6c
	v_ashrrev_i32_e32 v2, 31, v0
	v_lshrrev_b32_e32 v2, 26, v2
	v_add_u32_e32 v2, v0, v2
	s_waitcnt vmcnt(0)
	v_lshlrev_b32_e32 v4, 3, v1
	v_ashrrev_i32_e32 v3, 6, v2
	v_and_b32_e32 v4, -16, v4
	v_lshlrev_b32_e32 v1, 5, v1
	v_add_u32_e32 v4, v3, v4
	v_and_b32_e32 v12, 32, v1
	v_and_b32_e32 v1, 0xc0, v2
	v_and_b32_e32 v3, 3, v3
	s_mov_b32 s3, 0x7fffffe0
	v_lshrrev_b32_e32 v5, 2, v4
	v_lshlrev_b32_e32 v6, 1, v4
	v_sub_u32_e32 v0, v0, v1
	v_mov_b32_e32 v7, 1
	v_and_or_b32 v3, v4, s3, v3
	v_and_b32_e32 v5, 4, v5
	v_and_b32_e32 v6, 24, v6
	v_ashrrev_i16_sdwa v0, v7, sext(v0) dst_sel:DWORD dst_unused:UNUSED_PAD src0_sel:DWORD src1_sel:BYTE_0
	v_or3_b32 v3, v3, v5, v6
	v_bfe_i32 v13, v0, 0, 16
	v_mul_lo_u32 v3, s5, v3
	v_add_u32_e32 v0, v12, v13
	v_mul_lo_u32 v14, s5, v4
	s_waitcnt lgkmcnt(6)
	v_add_lshl_u32 v198, v3, v0, 1
	s_waitcnt lgkmcnt(5)
	v_add_lshl_u32 v200, v14, v0, 1
	v_bfe_i32 v0, v229, 27, 1
	v_lshrrev_b32_e32 v0, 22, v0
	v_add_u32_e32 v0, v230, v0
	v_and_b32_e32 v0, 0xfffffc00, v0
	v_sub_u32_e32 v0, v230, v0
	v_lshrrev_b32_e32 v1, 4, v0
	v_ashrrev_i32_e32 v3, 31, v229
	v_bitop3_b32 v0, v1, v0, 32 bitop3:0x6c
	v_lshrrev_b32_e32 v3, 26, v3
	v_ashrrev_i32_e32 v1, 31, v0
	v_add_u32_e32 v3, v229, v3
	s_ashr_i32 s7, s4, 6
	v_lshrrev_b32_e32 v1, 26, v1
	v_ashrrev_i32_e32 v3, 6, v3
	s_ashr_i32 s6, s4, 8
	s_lshl_b32 s12, s5, 8
	s_lshl_b32 s93, s5, 9
	s_lshl_b32 s94, s7, 10
	v_add_u32_e32 v1, v0, v1
	v_lshlrev_b32_e32 v4, 3, v3
	s_and_b64 s[8:9], exec, s[10:11]
	v_ashrrev_i32_e32 v2, 6, v1
	v_and_b32_e32 v4, -16, v4
	v_add_u32_e32 v4, v2, v4
	v_and_b32_e32 v1, 0xc0, v1
	v_readlane_b32 s8, v254, 26
	v_and_b32_e32 v2, 3, v2
	v_lshrrev_b32_e32 v5, 2, v4
	v_lshlrev_b32_e32 v6, 1, v4
	v_sub_u32_e32 v0, v0, v1
	v_readlane_b32 s9, v254, 27
	s_mov_b32 s22, s8
	v_and_or_b32 v2, v4, s3, v2
	v_and_b32_e32 v5, 4, v5
	v_and_b32_e32 v6, 24, v6
	v_lshlrev_b32_e32 v3, 5, v3
	v_ashrrev_i16_sdwa v0, v7, sext(v0) dst_sel:DWORD dst_unused:UNUSED_PAD src0_sel:DWORD src1_sel:BYTE_0
	s_mul_i32 s9, s93, s22
	s_cselect_b32 s95, s65, s17
	s_cselect_b32 s96, s64, s16
	v_or3_b32 v2, v2, v5, v6
	v_and_b32_e32 v15, 32, v3
	v_bfe_i32 v16, v0, 0, 16
	s_mul_hi_i32 s8, s93, s8
	s_add_u32 s74, s38, s9
	v_mul_lo_u32 v2, s5, v2
	v_add_u32_e32 v0, v15, v16
	s_addc_u32 s75, s39, s8
	s_add_i32 s97, s94, 0
	v_add_lshl_u32 v192, v2, v0, 1
	s_add_i32 m0, s97, 0x10000
	v_readlane_b32 s3, v254, 16
	global_load_lds_dwordx4 v192, s[74:75]
	s_add_i32 m0, s97, 0x12000
	s_add_u32 s8, s74, s12
	global_load_lds_dwordx4 v198, s[74:75]
	s_addc_u32 s9, s75, 0
	s_add_i32 m0, s97, 0x14000
	s_mul_i32 s11, s93, s3
	global_load_lds_dwordx4 v192, s[8:9]
	s_add_i32 m0, s97, 0x16000
	s_mul_hi_i32 s10, s93, s3
	s_add_u32 s80, s96, s11
	v_mul_lo_u32 v17, s5, v4
	v_mov_b32_e32 v199, v193
	s_addc_u32 s81, s95, s10
	s_add_i32 s98, s97, 0x2000
	s_waitcnt lgkmcnt(0)
	v_add_lshl_u32 v202, v17, v0, 1
	v_lshl_add_u64 v[4:5], s[8:9], 0, v[192:193]
	v_lshl_add_u64 v[6:7], s[8:9], 0, v[198:199]
	global_load_lds_dwordx4 v198, s[8:9]
	s_mov_b32 m0, s97
	s_add_u32 s8, s80, s12
	global_load_lds_dwordx4 v202, s[80:81]
	s_mov_b32 m0, s98
	s_addc_u32 s9, s81, 0
	s_add_i32 s99, s97, 0x4000
	global_load_lds_dwordx4 v200, s[80:81]
	s_mov_b32 m0, s99
	s_add_i32 s78, s97, 0x6000
	global_load_lds_dwordx4 v202, s[8:9]
	s_mov_b32 m0, s78
	v_mov_b32_e32 v203, v193
	global_load_lds_dwordx4 v200, s[8:9]
	v_mov_b32_e32 v201, v193
	s_cmp_eq_u32 s6, 1
	v_lshl_add_u64 v[0:1], s[74:75], 0, v[192:193]
	v_lshl_add_u64 v[2:3], s[74:75], 0, v[198:199]
	v_lshl_add_u64 v[8:9], s[80:81], 0, v[202:203]
	v_lshl_add_u64 v[10:11], s[80:81], 0, v[200:201]
	s_cselect_b64 s[22:23], -1, 0
	s_cmp_lg_u32 s6, 1
	s_cbranch_scc1 .LBB0_549
	s_barrier
	s_setprio 1

;     __device__ __forceinline__ Pre prefetch(const Unit& u, int tid) const { return prenorm_load(stats, u.pn * BM, sW + (size_t)(u.pn >> 4) * SW_ROWS + u.pm * BM, tid); }
;     __device__ __forceinline__ Pre prefetch(const Unit& u, int tid) const { return prenorm_load(stats, u.pm * BM, sW + (size_t)(u.pm >> 4) * SW_ROWS + u.pn * BM, tid); }
;     __device__ __forceinline__ Pre prefetch(const Unit& u, int tid) const { return prenorm_load(stats, u.pm * BM, sW + (size_t)(u.pm >> 4) * SW_ROWS + u.pn * BM, tid); }
; template <class Epi, class Sched>
; __device__ __forceinline__ void gemm_phase(LAS unsigned char* lds, const Gemm g, const Sched& S, const Epi& E, const int tid) {
;     ...
;         const bool has_next = S.next(ui + 1, nxt);
;         const char* nA = has_next ? (const char*)g.A + (size_t)nxt.pm * tstep : cA; const char* nB = has_next ? (const char*)g.Bt + (size_t)nxt.pn * tstep : cB;
;         const typename Epi::Pre pre = E.prefetch(cur, tid);
;         for (int t = 0; t < nt; t += 2) {
;             const bool last = (t == nt - 2);
;             const char* a1 = cA + (size_t)(t + 1) * kstep;
;             const char* a2 = last ? nA : cA + (size_t)(t + 2) * kstep; const char* b2 = last ? nB : cB + (size_t)(t + 2) * kstep;
;             const char* a3 = a2 + kstep; const char* b3 = b2 + kstep;
;             PG8_LDB(B0, 0, 0); PG8_LDB(B1, 0, 1); PG8_SCHED; PG8_LDA(At, 0, 0); PG8_STAGE(PG8_SA(1, 1), a1 + hstep, voffA);
;             PG8_WAIT_V(8); PG8_WAIT_L(0); PG8_BAR; PG8_MMA(0, 0, At, B0); PG8_MMA(0, 1, At, B1); PG8_BAR; PG8_SCHED;
;             PG8_LDA(At, 0, 1); PG8_STAGE(PG8_SB(0, 0), b2, voffB); PG8_STAGE(PG8_SB(0, 1), b2 + hstep, voffB); PG8_STAGE(PG8_SA(0, 0), a2, voffA);
;             PG8_WAIT_V(8); PG8_WAIT_L(0); PG8_BAR; PG8_MMA(1, 0, At, B0); PG8_MMA(1, 1, At, B1); PG8_BAR; PG8_SCHED;
;             PG8_LDB(B0, 1, 0); PG8_LDB(B1, 1, 1); PG8_SCHED; PG8_LDA(At, 1, 0); PG8_STAGE(PG8_SA(0, 1), a2 + hstep, voffA);
;             PG8_WAIT_V(8); PG8_WAIT_L(0); PG8_BAR; PG8_MMA(0, 0, At, B0); PG8_MMA(0, 1, At, B1); PG8_BAR; PG8_SCHED;
;             PG8_LDA(At, 1, 1); PG8_STAGE(PG8_SB(1, 0), b3, voffB); PG8_STAGE(PG8_SB(1, 1), b3 + hstep, voffB); PG8_STAGE(PG8_SA(1, 0), a3, voffA);
;             PG8_WAIT_V(8); PG8_WAIT_L(0); PG8_BAR; PG8_MMA(1, 0, At, B0); PG8_MMA(1, 1, At, B1); PG8_BAR; PG8_SCHED;
;         }
.LBB0_565:
.LBB0_566:
	s_or_b64 exec, exec, s[82:83]
	s_add_u32 vcc_lo, s80, 0x80
	s_addc_u32 vcc_hi, s81, 0
	s_add_u32 s61, s74, 0x100
	s_addc_u32 s67, s75, 0
	s_mov_b32 s74, 0
	s_add_i32 s80, s74, 2
	s_add_u32 s81, vcc_lo, 0x80
	s_addc_u32 s75, vcc_hi, 0
	s_add_i32 s3, 0, 0x10000
	s_cmp_eq_u32 s57, s74
	s_cselect_b32 s75, s71, s75
	s_cselect_b32 s74, s70, s81
	v_add_u32_e32 v70, s3, v232
	s_cselect_b32 s83, s73, s67
	s_cselect_b32 s82, s72, s61
	s_add_i32 s81, 0, 0x14000
	ds_read_b128 v[58:61], v70
	ds_read_b128 v[62:65], v70 offset:1024
	ds_read_b128 v[66:69], v70 offset:2048
	ds_read_b128 v[80:83], v70 offset:3072
	v_add_u32_e32 v70, s81, v232
	ds_read_b128 v[84:87], v70
	ds_read_b128 v[88:91], v70 offset:1024
	ds_read_b128 v[92:95], v70 offset:2048
	ds_read_b128 v[152:155], v70 offset:3072
	v_lshl_add_u64 v[70:71], vcc, 0, v[204:205]
	s_add_i32 m0, s97, 0xc000
	ds_read_b128 v[164:167], v240
	ds_read_b128 v[168:171], v240 offset:1024
	ds_read_b128 v[172:175], v240 offset:2048
	ds_read_b128 v[176:179], v240 offset:3072
	ds_read_b128 v[180:183], v240 offset:4096
	ds_read_b128 v[184:187], v240 offset:5120
	ds_read_b128 v[188:191], v240 offset:6144
	ds_read_b128 v[208:211], v240 offset:7168
	global_load_lds_dwordx4 v[70:71], off
	v_lshl_add_u64 v[70:71], vcc, 0, v[206:207]
	s_add_i32 m0, s97, 0xe000
	s_nop 0
	global_load_lds_dwordx4 v[70:71], off
	s_waitcnt vmcnt(8)
	s_waitcnt lgkmcnt(0)
	s_barrier
	s_waitcnt lgkmcnt(0)
	v_mfma_f32_16x16x32_bf16 v[160:163], v[58:61], v[164:167], 0
	v_mfma_f32_16x16x32_bf16 v[156:159], v[66:69], v[164:167], 0
	v_mfma_f32_16x16x32_bf16 v[140:143], v[58:61], v[172:175], 0
	v_mfma_f32_16x16x32_bf16 v[136:139], v[66:69], v[172:175], 0
	v_mfma_f32_16x16x32_bf16 v[124:127], v[58:61], v[180:183], 0
	v_mfma_f32_16x16x32_bf16 v[120:123], v[66:69], v[180:183], 0
	v_mfma_f32_16x16x32_bf16 v[108:111], v[58:61], v[188:191], 0
	v_mfma_f32_16x16x32_bf16 v[104:107], v[66:69], v[188:191], 0
	v_mfma_f32_16x16x32_bf16 v[160:163], v[62:65], v[168:171], v[160:163]
	v_mfma_f32_16x16x32_bf16 v[156:159], v[80:83], v[168:171], v[156:159]
	v_mfma_f32_16x16x32_bf16 v[140:143], v[62:65], v[176:179], v[140:143]
	v_mfma_f32_16x16x32_bf16 v[136:139], v[80:83], v[176:179], v[136:139]
	v_mfma_f32_16x16x32_bf16 v[124:127], v[62:65], v[184:187], v[124:127]
	v_mfma_f32_16x16x32_bf16 v[120:123], v[80:83], v[184:187], v[120:123]
	v_mfma_f32_16x16x32_bf16 v[108:111], v[62:65], v[208:211], v[108:111]
	v_mfma_f32_16x16x32_bf16 v[104:107], v[80:83], v[208:211], v[104:107]
	v_mfma_f32_16x16x32_bf16 v[148:151], v[84:87], v[164:167], 0
	v_mfma_f32_16x16x32_bf16 v[144:147], v[92:95], v[164:167], 0
	v_mfma_f32_16x16x32_bf16 v[132:135], v[84:87], v[172:175], 0
	v_mfma_f32_16x16x32_bf16 v[128:131], v[92:95], v[172:175], 0
	v_mfma_f32_16x16x32_bf16 v[116:119], v[84:87], v[180:183], 0
	v_mfma_f32_16x16x32_bf16 v[112:115], v[92:95], v[180:183], 0
	v_mfma_f32_16x16x32_bf16 v[100:103], v[84:87], v[188:191], 0
	v_mfma_f32_16x16x32_bf16 v[96:99], v[92:95], v[188:191], 0
	v_mfma_f32_16x16x32_bf16 v[148:151], v[88:91], v[168:171], v[148:151]
	v_mfma_f32_16x16x32_bf16 v[144:147], v[152:155], v[168:171], v[144:147]
	v_mfma_f32_16x16x32_bf16 v[132:135], v[88:91], v[176:179], v[132:135]
	v_mfma_f32_16x16x32_bf16 v[128:131], v[152:155], v[176:179], v[128:131]
	v_mfma_f32_16x16x32_bf16 v[116:119], v[88:91], v[184:187], v[116:119]
	v_mfma_f32_16x16x32_bf16 v[112:115], v[152:155], v[184:187], v[112:115]
	v_mfma_f32_16x16x32_bf16 v[100:103], v[88:91], v[208:211], v[100:103]
	v_mfma_f32_16x16x32_bf16 v[96:99], v[152:155], v[208:211], v[96:99]
	s_barrier
	s_add_i32 s3, s3, s94
	v_lshl_add_u64 v[212:213], s[82:83], 0, v[192:193]
	s_mov_b32 m0, s3
	ds_read_b128 v[164:167], v240 offset:16384
	ds_read_b128 v[168:171], v240 offset:17408
	ds_read_b128 v[172:175], v240 offset:18432
	ds_read_b128 v[176:179], v240 offset:19456
	ds_read_b128 v[180:183], v240 offset:20480
	ds_read_b128 v[184:187], v240 offset:21504
	ds_read_b128 v[188:191], v240 offset:22528
	ds_read_b128 v[208:211], v240 offset:23552
	global_load_lds_dwordx4 v[212:213], off
	s_add_i32 m0, s3, 0x2000
	v_lshl_add_u64 v[214:215], s[82:83], 0, v[198:199]
	s_add_u32 s82, s82, s12
	s_addc_u32 s83, s83, 0
	s_add_i32 s3, s81, s94
	global_load_lds_dwordx4 v[214:215], off
	v_lshl_add_u64 v[216:217], s[82:83], 0, v[192:193]
	s_mov_b32 m0, s3
	v_lshl_add_u64 v[218:219], s[82:83], 0, v[198:199]
	global_load_lds_dwordx4 v[216:217], off
	s_add_i32 m0, s3, 0x2000
	v_lshl_add_u64 v[220:221], s[74:75], 0, v[202:203]
	global_load_lds_dwordx4 v[218:219], off
	s_mov_b32 m0, s97
	v_lshl_add_u64 v[224:225], s[74:75], 0, v[200:201]
	global_load_lds_dwordx4 v[220:221], off
	s_mov_b32 m0, s98
	s_nop 0
	global_load_lds_dwordx4 v[224:225], off
	s_waitcnt vmcnt(8)
	s_waitcnt lgkmcnt(0)
	s_barrier
; #define PG8_STAGE(bufoff, gbase, voff) do { _Pragma("unroll") for (int _i = 0; _i < 2; ++_i) \
;         __builtin_amdgcn_global_load_lds((const unsigned*)((const char*)(gbase) + (voff)[_i]), (LAS unsigned*)(lds + (bufoff) + ldsw + _i * 8192), 16, 0, 0); } while (0)
; #define PG8_LDA(dst, b, h) do { _Pragma("unroll") for (int m = 0; m < 4; ++m) _Pragma("unroll") for (int k = 0; k < 2; ++k) dst[m][k] = *(const LAS bf16x8*)(lds + PG8_SA(b, h) + aoff + m * 2048 + k * 1024); } while (0)
; #define PG8_LDB(dst, b, h) do { _Pragma("unroll") for (int n = 0; n < 2; ++n) _Pragma("unroll") for (int k = 0; k < 2; ++k) dst[n][k] = *(const LAS bf16x8*)(lds + PG8_SB(b, h) + boff + n * 2048 + k * 1024); } while (0)
; #define PG8_WAIT_V(n) asm volatile("s_waitcnt vmcnt(" #n ")" ::: "memory")
; #define PG8_BAR __builtin_amdgcn_s_barrier()
; template <class Epi, class Sched>
; __device__ __forceinline__ void gemm_phase(LAS unsigned char* lds, const Gemm g, const Sched& S, const Epi& E, const int tid) {
;     ...
;         for (int t = 0; t < nt; t += 2) {
;             const bool last = (t == nt - 2);
;             const char* a1 = cA + (size_t)(t + 1) * kstep;
;             const char* a2 = last ? nA : cA + (size_t)(t + 2) * kstep; const char* b2 = last ? nB : cB + (size_t)(t + 2) * kstep;
;             const char* a3 = a2 + kstep; const char* b3 = b2 + kstep;
;             PG8_LDB(B0, 0, 0); PG8_LDB(B1, 0, 1); PG8_SCHED; PG8_LDA(At, 0, 0); PG8_STAGE(PG8_SA(1, 1), a1 + hstep, voffA);
;             PG8_WAIT_V(8); PG8_WAIT_L(0); PG8_BAR; PG8_MMA(0, 0, At, B0); PG8_MMA(0, 1, At, B1); PG8_BAR; PG8_SCHED;
;             PG8_LDA(At, 0, 1); PG8_STAGE(PG8_SB(0, 0), b2, voffB); PG8_STAGE(PG8_SB(0, 1), b2 + hstep, voffB); PG8_STAGE(PG8_SA(0, 0), a2, voffA);
;             PG8_WAIT_V(8); PG8_WAIT_L(0); PG8_BAR; PG8_MMA(1, 0, At, B0); PG8_MMA(1, 1, At, B1); PG8_BAR; PG8_SCHED;
;             PG8_LDB(B0, 1, 0); PG8_LDB(B1, 1, 1); PG8_SCHED; PG8_LDA(At, 1, 0); PG8_STAGE(PG8_SA(0, 1), a2 + hstep, voffA);
;             PG8_WAIT_V(8); PG8_WAIT_L(0); PG8_BAR; PG8_MMA(0, 0, At, B0); PG8_MMA(0, 1, At, B1); PG8_BAR; PG8_SCHED;
;             PG8_LDA(At, 1, 1); PG8_STAGE(PG8_SB(1, 0), b3, voffB); PG8_STAGE(PG8_SB(1, 1), b3 + hstep, voffB); PG8_STAGE(PG8_SA(1, 0), a3, voffA);
;             PG8_WAIT_V(8); PG8_WAIT_L(0); PG8_BAR; PG8_MMA(1, 0, At, B0); PG8_MMA(1, 1, At, B1); PG8_BAR; PG8_SCHED;
;         }
	s_waitcnt lgkmcnt(0)
	v_mfma_f32_16x16x32_bf16 v[76:79], v[58:61], v[164:167], 0
	v_mfma_f32_16x16x32_bf16 v[70:73], v[66:69], v[164:167], 0
	v_mfma_f32_16x16x32_bf16 v[44:47], v[58:61], v[172:175], 0
	v_mfma_f32_16x16x32_bf16 v[40:43], v[66:69], v[172:175], 0
	v_mfma_f32_16x16x32_bf16 v[28:31], v[58:61], v[180:183], 0
	v_mfma_f32_16x16x32_bf16 v[24:27], v[66:69], v[180:183], 0
	v_mfma_f32_16x16x32_bf16 v[12:15], v[58:61], v[188:191], 0
	v_mfma_f32_16x16x32_bf16 v[8:11], v[66:69], v[188:191], 0
	v_mfma_f32_16x16x32_bf16 v[76:79], v[62:65], v[168:171], v[76:79]
	v_mfma_f32_16x16x32_bf16 v[70:73], v[80:83], v[168:171], v[70:73]
	v_mfma_f32_16x16x32_bf16 v[44:47], v[62:65], v[176:179], v[44:47]
	v_mfma_f32_16x16x32_bf16 v[40:43], v[80:83], v[176:179], v[40:43]
	v_mfma_f32_16x16x32_bf16 v[28:31], v[62:65], v[184:187], v[28:31]
	v_mfma_f32_16x16x32_bf16 v[24:27], v[80:83], v[184:187], v[24:27]
	v_mfma_f32_16x16x32_bf16 v[12:15], v[62:65], v[208:211], v[12:15]
	v_mfma_f32_16x16x32_bf16 v[8:11], v[80:83], v[208:211], v[8:11]
	v_mfma_f32_16x16x32_bf16 v[52:55], v[84:87], v[164:167], 0
	v_mfma_f32_16x16x32_bf16 v[48:51], v[92:95], v[164:167], 0
	v_mfma_f32_16x16x32_bf16 v[36:39], v[84:87], v[172:175], 0
	v_mfma_f32_16x16x32_bf16 v[32:35], v[92:95], v[172:175], 0
	v_mfma_f32_16x16x32_bf16 v[20:23], v[84:87], v[180:183], 0
	v_mfma_f32_16x16x32_bf16 v[16:19], v[92:95], v[180:183], 0
	v_mfma_f32_16x16x32_bf16 v[4:7], v[84:87], v[188:191], 0
	v_mfma_f32_16x16x32_bf16 v[0:3], v[92:95], v[188:191], 0
	v_mfma_f32_16x16x32_bf16 v[52:55], v[88:91], v[168:171], v[52:55]
	v_mfma_f32_16x16x32_bf16 v[48:51], v[152:155], v[168:171], v[48:51]
	v_mfma_f32_16x16x32_bf16 v[36:39], v[88:91], v[176:179], v[36:39]
	v_mfma_f32_16x16x32_bf16 v[32:35], v[152:155], v[176:179], v[32:35]
	v_mfma_f32_16x16x32_bf16 v[20:23], v[88:91], v[184:187], v[20:23]
	v_mfma_f32_16x16x32_bf16 v[16:19], v[152:155], v[184:187], v[16:19]
	v_mfma_f32_16x16x32_bf16 v[4:7], v[88:91], v[208:211], v[4:7]
	v_mfma_f32_16x16x32_bf16 v[0:3], v[152:155], v[208:211], v[0:3]
	s_barrier
	s_add_i32 s3, 0, 0x18000
	v_add_u32_e32 v74, s3, v232
	s_add_i32 s81, 0, 0x1c000
	ds_read_b128 v[58:61], v74
	ds_read_b128 v[62:65], v74 offset:1024
	ds_read_b128 v[66:69], v74 offset:2048
	ds_read_b128 v[80:83], v74 offset:3072
	v_add_u32_e32 v74, s81, v232
	ds_read_b128 v[84:87], v74
	ds_read_b128 v[88:91], v74 offset:1024
	ds_read_b128 v[92:95], v74 offset:2048
	ds_read_b128 v[152:155], v74 offset:3072
	s_add_u32 s74, s74, s12
	s_addc_u32 s75, s75, 0
	s_mov_b32 m0, s99
	v_lshl_add_u64 v[74:75], s[74:75], 0, v[202:203]
	ds_read_b128 v[164:167], v240 offset:32768
	ds_read_b128 v[168:171], v240 offset:33792
	ds_read_b128 v[172:175], v240 offset:34816
	ds_read_b128 v[176:179], v240 offset:35840
	ds_read_b128 v[180:183], v240 offset:36864
	ds_read_b128 v[184:187], v240 offset:37888
	ds_read_b128 v[188:191], v240 offset:38912
	ds_read_b128 v[208:211], v240 offset:39936
	global_load_lds_dwordx4 v[74:75], off
	v_lshl_add_u64 v[74:75], s[74:75], 0, v[200:201]
	s_mov_b32 m0, s78
	s_nop 0
	global_load_lds_dwordx4 v[74:75], off
	s_waitcnt vmcnt(8)
	s_waitcnt lgkmcnt(0)
	s_barrier
	s_waitcnt lgkmcnt(0)
	v_mfma_f32_16x16x32_bf16 v[160:163], v[58:61], v[164:167], v[160:163]
	v_mfma_f32_16x16x32_bf16 v[156:159], v[66:69], v[164:167], v[156:159]
	v_mfma_f32_16x16x32_bf16 v[140:143], v[58:61], v[172:175], v[140:143]
	v_mfma_f32_16x16x32_bf16 v[136:139], v[66:69], v[172:175], v[136:139]
	v_mfma_f32_16x16x32_bf16 v[124:127], v[58:61], v[180:183], v[124:127]
	v_mfma_f32_16x16x32_bf16 v[120:123], v[66:69], v[180:183], v[120:123]
	v_mfma_f32_16x16x32_bf16 v[108:111], v[58:61], v[188:191], v[108:111]
	v_mfma_f32_16x16x32_bf16 v[104:107], v[66:69], v[188:191], v[104:107]
	v_mfma_f32_16x16x32_bf16 v[160:163], v[62:65], v[168:171], v[160:163]
	v_mfma_f32_16x16x32_bf16 v[156:159], v[80:83], v[168:171], v[156:159]
	v_mfma_f32_16x16x32_bf16 v[140:143], v[62:65], v[176:179], v[140:143]
	v_mfma_f32_16x16x32_bf16 v[136:139], v[80:83], v[176:179], v[136:139]
	v_mfma_f32_16x16x32_bf16 v[124:127], v[62:65], v[184:187], v[124:127]
	v_mfma_f32_16x16x32_bf16 v[120:123], v[80:83], v[184:187], v[120:123]
	v_mfma_f32_16x16x32_bf16 v[108:111], v[62:65], v[208:211], v[108:111]
	v_mfma_f32_16x16x32_bf16 v[104:107], v[80:83], v[208:211], v[104:107]
	v_mfma_f32_16x16x32_bf16 v[148:151], v[84:87], v[164:167], v[148:151]
	v_mfma_f32_16x16x32_bf16 v[144:147], v[92:95], v[164:167], v[144:147]
	v_mfma_f32_16x16x32_bf16 v[132:135], v[84:87], v[172:175], v[132:135]
	v_mfma_f32_16x16x32_bf16 v[128:131], v[92:95], v[172:175], v[128:131]
	v_mfma_f32_16x16x32_bf16 v[116:119], v[84:87], v[180:183], v[116:119]
	v_mfma_f32_16x16x32_bf16 v[112:115], v[92:95], v[180:183], v[112:115]
	v_mfma_f32_16x16x32_bf16 v[100:103], v[84:87], v[188:191], v[100:103]
	v_mfma_f32_16x16x32_bf16 v[96:99], v[92:95], v[188:191], v[96:99]
	v_mfma_f32_16x16x32_bf16 v[148:151], v[88:91], v[168:171], v[148:151]
	v_mfma_f32_16x16x32_bf16 v[144:147], v[152:155], v[168:171], v[144:147]
	v_mfma_f32_16x16x32_bf16 v[132:135], v[88:91], v[176:179], v[132:135]
	v_mfma_f32_16x16x32_bf16 v[128:131], v[152:155], v[176:179], v[128:131]
	v_mfma_f32_16x16x32_bf16 v[116:119], v[88:91], v[184:187], v[116:119]
	v_mfma_f32_16x16x32_bf16 v[112:115], v[152:155], v[184:187], v[112:115]
	v_mfma_f32_16x16x32_bf16 v[100:103], v[88:91], v[208:211], v[100:103]
	v_mfma_f32_16x16x32_bf16 v[96:99], v[152:155], v[208:211], v[96:99]
	s_barrier
; #define PG8_STAGE(bufoff, gbase, voff) do { _Pragma("unroll") for (int _i = 0; _i < 2; ++_i) \
;         __builtin_amdgcn_global_load_lds((const unsigned*)((const char*)(gbase) + (voff)[_i]), (LAS unsigned*)(lds + (bufoff) + ldsw + _i * 8192), 16, 0, 0); } while (0)
; #define PG8_LDA(dst, b, h) do { _Pragma("unroll") for (int m = 0; m < 4; ++m) _Pragma("unroll") for (int k = 0; k < 2; ++k) dst[m][k] = *(const LAS bf16x8*)(lds + PG8_SA(b, h) + aoff + m * 2048 + k * 1024); } while (0)
; #define PG8_LDB(dst, b, h) do { _Pragma("unroll") for (int n = 0; n < 2; ++n) _Pragma("unroll") for (int k = 0; k < 2; ++k) dst[n][k] = *(const LAS bf16x8*)(lds + PG8_SB(b, h) + boff + n * 2048 + k * 1024); } while (0)
; #define PG8_WAIT_V(n) asm volatile("s_waitcnt vmcnt(" #n ")" ::: "memory")
; #define PG8_BAR __builtin_amdgcn_s_barrier()
; template <class Epi, class Sched>
; __device__ __forceinline__ void gemm_phase(LAS unsigned char* lds, const Gemm g, const Sched& S, const Epi& E, const int tid) {
;     ...
;         for (int t = 0; t < nt; t += 2) {
;             const bool last = (t == nt - 2);
;             const char* a1 = cA + (size_t)(t + 1) * kstep;
;             const char* a2 = last ? nA : cA + (size_t)(t + 2) * kstep; const char* b2 = last ? nB : cB + (size_t)(t + 2) * kstep;
;             const char* a3 = a2 + kstep; const char* b3 = b2 + kstep;
;             PG8_LDB(B0, 0, 0); PG8_LDB(B1, 0, 1); PG8_SCHED; PG8_LDA(At, 0, 0); PG8_STAGE(PG8_SA(1, 1), a1 + hstep, voffA);
;             PG8_WAIT_V(8); PG8_WAIT_L(0); PG8_BAR; PG8_MMA(0, 0, At, B0); PG8_MMA(0, 1, At, B1); PG8_BAR; PG8_SCHED;
;             PG8_LDA(At, 0, 1); PG8_STAGE(PG8_SB(0, 0), b2, voffB); PG8_STAGE(PG8_SB(0, 1), b2 + hstep, voffB); PG8_STAGE(PG8_SA(0, 0), a2, voffA);
;             PG8_WAIT_V(8); PG8_WAIT_L(0); PG8_BAR; PG8_MMA(1, 0, At, B0); PG8_MMA(1, 1, At, B1); PG8_BAR; PG8_SCHED;
;             PG8_LDB(B0, 1, 0); PG8_LDB(B1, 1, 1); PG8_SCHED; PG8_LDA(At, 1, 0); PG8_STAGE(PG8_SA(0, 1), a2 + hstep, voffA);
;             PG8_WAIT_V(8); PG8_WAIT_L(0); PG8_BAR; PG8_MMA(0, 0, At, B0); PG8_MMA(0, 1, At, B1); PG8_BAR; PG8_SCHED;
;             PG8_LDA(At, 1, 1); PG8_STAGE(PG8_SB(1, 0), b3, voffB); PG8_STAGE(PG8_SB(1, 1), b3 + hstep, voffB); PG8_STAGE(PG8_SA(1, 0), a3, voffA);
;             PG8_WAIT_V(8); PG8_WAIT_L(0); PG8_BAR; PG8_MMA(1, 0, At, B0); PG8_MMA(1, 1, At, B1); PG8_BAR; PG8_SCHED;
;         }
	s_add_i32 s3, s3, s94
	v_lshl_add_u64 v[74:75], v[212:213], 0, s[68:69]
	s_mov_b32 m0, s3
	ds_read_b128 v[164:167], v240 offset:49152
	ds_read_b128 v[168:171], v240 offset:50176
	ds_read_b128 v[172:175], v240 offset:51200
	ds_read_b128 v[176:179], v240 offset:52224
	ds_read_b128 v[180:183], v240 offset:53248
	ds_read_b128 v[184:187], v240 offset:54272
	ds_read_b128 v[188:191], v240 offset:55296
	ds_read_b128 v[208:211], v240 offset:56320
	global_load_lds_dwordx4 v[74:75], off
	v_lshl_add_u64 v[74:75], v[214:215], 0, s[68:69]
	s_add_i32 m0, s3, 0x2000
	s_add_i32 s3, s81, s94
	global_load_lds_dwordx4 v[74:75], off
	v_lshl_add_u64 v[74:75], v[216:217], 0, s[68:69]
	s_mov_b32 m0, s3
	s_nop 0
	global_load_lds_dwordx4 v[74:75], off
	v_lshl_add_u64 v[74:75], v[218:219], 0, s[68:69]
	s_add_i32 m0, s3, 0x2000
	s_nop 0
	global_load_lds_dwordx4 v[74:75], off
	v_lshl_add_u64 v[74:75], v[220:221], 0, s[68:69]
	s_mov_b32 m0, s53
	s_nop 0
	global_load_lds_dwordx4 v[74:75], off
	v_lshl_add_u64 v[74:75], v[224:225], 0, s[68:69]
	s_mov_b32 m0, s56
	s_nop 0
	global_load_lds_dwordx4 v[74:75], off
	s_waitcnt vmcnt(8)
	s_waitcnt lgkmcnt(0)
	s_barrier
	s_waitcnt lgkmcnt(0)
	v_mfma_f32_16x16x32_bf16 v[74:77], v[58:61], v[164:167], v[76:79]
	v_mfma_f32_16x16x32_bf16 v[70:73], v[66:69], v[164:167], v[70:73]
	v_mfma_f32_16x16x32_bf16 v[44:47], v[58:61], v[172:175], v[44:47]
	v_mfma_f32_16x16x32_bf16 v[40:43], v[66:69], v[172:175], v[40:43]
	v_mfma_f32_16x16x32_bf16 v[28:31], v[58:61], v[180:183], v[28:31]
	v_mfma_f32_16x16x32_bf16 v[24:27], v[66:69], v[180:183], v[24:27]
	v_mfma_f32_16x16x32_bf16 v[12:15], v[58:61], v[188:191], v[12:15]
	v_mfma_f32_16x16x32_bf16 v[8:11], v[66:69], v[188:191], v[8:11]
	v_mfma_f32_16x16x32_bf16 v[76:79], v[62:65], v[168:171], v[74:77]
	v_mfma_f32_16x16x32_bf16 v[72:75], v[80:83], v[168:171], v[70:73]
	v_mfma_f32_16x16x32_bf16 v[44:47], v[62:65], v[176:179], v[44:47]
	v_mfma_f32_16x16x32_bf16 v[40:43], v[80:83], v[176:179], v[40:43]
	v_mfma_f32_16x16x32_bf16 v[28:31], v[62:65], v[184:187], v[28:31]
	v_mfma_f32_16x16x32_bf16 v[24:27], v[80:83], v[184:187], v[24:27]
	v_mfma_f32_16x16x32_bf16 v[12:15], v[62:65], v[208:211], v[12:15]
	v_mfma_f32_16x16x32_bf16 v[8:11], v[80:83], v[208:211], v[8:11]
	v_mfma_f32_16x16x32_bf16 v[52:55], v[84:87], v[164:167], v[52:55]
	v_mfma_f32_16x16x32_bf16 v[48:51], v[92:95], v[164:167], v[48:51]
	v_mfma_f32_16x16x32_bf16 v[36:39], v[84:87], v[172:175], v[36:39]
	v_mfma_f32_16x16x32_bf16 v[32:35], v[92:95], v[172:175], v[32:35]
	v_mfma_f32_16x16x32_bf16 v[20:23], v[84:87], v[180:183], v[20:23]
	v_mfma_f32_16x16x32_bf16 v[16:19], v[92:95], v[180:183], v[16:19]
	v_mfma_f32_16x16x32_bf16 v[4:7], v[84:87], v[188:191], v[4:7]
	v_mfma_f32_16x16x32_bf16 v[0:3], v[92:95], v[188:191], v[0:3]
	v_mfma_f32_16x16x32_bf16 v[52:55], v[88:91], v[168:171], v[52:55]
	v_mfma_f32_16x16x32_bf16 v[48:51], v[152:155], v[168:171], v[48:51]
	v_mfma_f32_16x16x32_bf16 v[36:39], v[88:91], v[176:179], v[36:39]
	v_mfma_f32_16x16x32_bf16 v[32:35], v[152:155], v[176:179], v[32:35]
	v_mfma_f32_16x16x32_bf16 v[20:23], v[88:91], v[184:187], v[20:23]
	v_mfma_f32_16x16x32_bf16 v[16:19], v[152:155], v[184:187], v[16:19]
	v_mfma_f32_16x16x32_bf16 v[4:7], v[88:91], v[208:211], v[4:7]
	v_mfma_f32_16x16x32_bf16 v[0:3], v[152:155], v[208:211], v[0:3]
	s_barrier
	s_add_u32 vcc_lo, vcc_lo, 0x100
	s_addc_u32 vcc_hi, vcc_hi, 0
	s_add_u32 s61, s61, 0x100
	s_addc_u32 s67, s67, 0
	s_cmp_ge_u32 s80, s52
	s_mov_b32 s74, s80
.LBB0_567:
	s_add_i32 s80, s74, 2
	s_add_u32 s81, vcc_lo, 0x80
	s_addc_u32 s75, vcc_hi, 0
	s_add_i32 s3, 0, 0x10000
	s_cmp_eq_u32 s57, s74
	s_cselect_b32 s75, s71, s75
	s_cselect_b32 s74, s70, s81
	v_add_u32_e32 v70, s3, v232
	s_cselect_b32 s83, s73, s67
	s_cselect_b32 s82, s72, s61
	s_add_i32 s81, 0, 0x14000
	ds_read_b128 v[58:61], v70
	ds_read_b128 v[62:65], v70 offset:1024
	ds_read_b128 v[66:69], v70 offset:2048
	ds_read_b128 v[80:83], v70 offset:3072
	v_add_u32_e32 v70, s81, v232
	ds_read_b128 v[84:87], v70
	ds_read_b128 v[88:91], v70 offset:1024
	ds_read_b128 v[92:95], v70 offset:2048
	ds_read_b128 v[152:155], v70 offset:3072
	v_lshl_add_u64 v[70:71], vcc, 0, v[204:205]
	s_add_i32 m0, s97, 0xc000
	ds_read_b128 v[164:167], v240
	ds_read_b128 v[168:171], v240 offset:1024
	ds_read_b128 v[172:175], v240 offset:2048
	ds_read_b128 v[176:179], v240 offset:3072
	ds_read_b128 v[180:183], v240 offset:4096
	ds_read_b128 v[184:187], v240 offset:5120
	ds_read_b128 v[188:191], v240 offset:6144
	ds_read_b128 v[208:211], v240 offset:7168
	global_load_lds_dwordx4 v[70:71], off
	v_lshl_add_u64 v[70:71], vcc, 0, v[206:207]
	s_add_i32 m0, s97, 0xe000
	s_nop 0
	global_load_lds_dwordx4 v[70:71], off
	s_waitcnt vmcnt(8)
	s_waitcnt lgkmcnt(0)
	s_barrier
; #define PG8_STAGE(bufoff, gbase, voff) do { _Pragma("unroll") for (int _i = 0; _i < 2; ++_i) \
;         __builtin_amdgcn_global_load_lds((const unsigned*)((const char*)(gbase) + (voff)[_i]), (LAS unsigned*)(lds + (bufoff) + ldsw + _i * 8192), 16, 0, 0); } while (0)
; #define PG8_LDA(dst, b, h) do { _Pragma("unroll") for (int m = 0; m < 4; ++m) _Pragma("unroll") for (int k = 0; k < 2; ++k) dst[m][k] = *(const LAS bf16x8*)(lds + PG8_SA(b, h) + aoff + m * 2048 + k * 1024); } while (0)
; #define PG8_LDB(dst, b, h) do { _Pragma("unroll") for (int n = 0; n < 2; ++n) _Pragma("unroll") for (int k = 0; k < 2; ++k) dst[n][k] = *(const LAS bf16x8*)(lds + PG8_SB(b, h) + boff + n * 2048 + k * 1024); } while (0)
; #define PG8_WAIT_V(n) asm volatile("s_waitcnt vmcnt(" #n ")" ::: "memory")
; #define PG8_BAR __builtin_amdgcn_s_barrier()
; template <class Epi, class Sched>
; __device__ __forceinline__ void gemm_phase(LAS unsigned char* lds, const Gemm g, const Sched& S, const Epi& E, const int tid) {
;     ...
;         for (int t = 0; t < nt; t += 2) {
;             const bool last = (t == nt - 2);
;             const char* a1 = cA + (size_t)(t + 1) * kstep;
;             const char* a2 = last ? nA : cA + (size_t)(t + 2) * kstep; const char* b2 = last ? nB : cB + (size_t)(t + 2) * kstep;
;             const char* a3 = a2 + kstep; const char* b3 = b2 + kstep;
;             PG8_LDB(B0, 0, 0); PG8_LDB(B1, 0, 1); PG8_SCHED; PG8_LDA(At, 0, 0); PG8_STAGE(PG8_SA(1, 1), a1 + hstep, voffA);
;             PG8_WAIT_V(8); PG8_WAIT_L(0); PG8_BAR; PG8_MMA(0, 0, At, B0); PG8_MMA(0, 1, At, B1); PG8_BAR; PG8_SCHED;
;             PG8_LDA(At, 0, 1); PG8_STAGE(PG8_SB(0, 0), b2, voffB); PG8_STAGE(PG8_SB(0, 1), b2 + hstep, voffB); PG8_STAGE(PG8_SA(0, 0), a2, voffA);
;             PG8_WAIT_V(8); PG8_WAIT_L(0); PG8_BAR; PG8_MMA(1, 0, At, B0); PG8_MMA(1, 1, At, B1); PG8_BAR; PG8_SCHED;
;             PG8_LDB(B0, 1, 0); PG8_LDB(B1, 1, 1); PG8_SCHED; PG8_LDA(At, 1, 0); PG8_STAGE(PG8_SA(0, 1), a2 + hstep, voffA);
;             PG8_WAIT_V(8); PG8_WAIT_L(0); PG8_BAR; PG8_MMA(0, 0, At, B0); PG8_MMA(0, 1, At, B1); PG8_BAR; PG8_SCHED;
;             PG8_LDA(At, 1, 1); PG8_STAGE(PG8_SB(1, 0), b3, voffB); PG8_STAGE(PG8_SB(1, 1), b3 + hstep, voffB); PG8_STAGE(PG8_SA(1, 0), a3, voffA);
;             PG8_WAIT_V(8); PG8_WAIT_L(0); PG8_BAR; PG8_MMA(1, 0, At, B0); PG8_MMA(1, 1, At, B1); PG8_BAR; PG8_SCHED;
;         }
	s_waitcnt lgkmcnt(0)
	v_mfma_f32_16x16x32_bf16 v[160:163], v[58:61], v[164:167], v[160:163]
	v_mfma_f32_16x16x32_bf16 v[156:159], v[66:69], v[164:167], v[156:159]
	v_mfma_f32_16x16x32_bf16 v[140:143], v[58:61], v[172:175], v[140:143]
	v_mfma_f32_16x16x32_bf16 v[136:139], v[66:69], v[172:175], v[136:139]
	v_mfma_f32_16x16x32_bf16 v[124:127], v[58:61], v[180:183], v[124:127]
	v_mfma_f32_16x16x32_bf16 v[120:123], v[66:69], v[180:183], v[120:123]
	v_mfma_f32_16x16x32_bf16 v[108:111], v[58:61], v[188:191], v[108:111]
	v_mfma_f32_16x16x32_bf16 v[104:107], v[66:69], v[188:191], v[104:107]
	v_mfma_f32_16x16x32_bf16 v[160:163], v[62:65], v[168:171], v[160:163]
	v_mfma_f32_16x16x32_bf16 v[156:159], v[80:83], v[168:171], v[156:159]
	v_mfma_f32_16x16x32_bf16 v[140:143], v[62:65], v[176:179], v[140:143]
	v_mfma_f32_16x16x32_bf16 v[136:139], v[80:83], v[176:179], v[136:139]
	v_mfma_f32_16x16x32_bf16 v[124:127], v[62:65], v[184:187], v[124:127]
	v_mfma_f32_16x16x32_bf16 v[120:123], v[80:83], v[184:187], v[120:123]
	v_mfma_f32_16x16x32_bf16 v[108:111], v[62:65], v[208:211], v[108:111]
	v_mfma_f32_16x16x32_bf16 v[104:107], v[80:83], v[208:211], v[104:107]
	v_mfma_f32_16x16x32_bf16 v[148:151], v[84:87], v[164:167], v[148:151]
	v_mfma_f32_16x16x32_bf16 v[144:147], v[92:95], v[164:167], v[144:147]
	v_mfma_f32_16x16x32_bf16 v[132:135], v[84:87], v[172:175], v[132:135]
	v_mfma_f32_16x16x32_bf16 v[128:131], v[92:95], v[172:175], v[128:131]
	v_mfma_f32_16x16x32_bf16 v[116:119], v[84:87], v[180:183], v[116:119]
	v_mfma_f32_16x16x32_bf16 v[112:115], v[92:95], v[180:183], v[112:115]
	v_mfma_f32_16x16x32_bf16 v[100:103], v[84:87], v[188:191], v[100:103]
	v_mfma_f32_16x16x32_bf16 v[96:99], v[92:95], v[188:191], v[96:99]
	v_mfma_f32_16x16x32_bf16 v[148:151], v[88:91], v[168:171], v[148:151]
	v_mfma_f32_16x16x32_bf16 v[144:147], v[152:155], v[168:171], v[144:147]
	v_mfma_f32_16x16x32_bf16 v[132:135], v[88:91], v[176:179], v[132:135]
	v_mfma_f32_16x16x32_bf16 v[128:131], v[152:155], v[176:179], v[128:131]
	v_mfma_f32_16x16x32_bf16 v[116:119], v[88:91], v[184:187], v[116:119]
	v_mfma_f32_16x16x32_bf16 v[112:115], v[152:155], v[184:187], v[112:115]
	v_mfma_f32_16x16x32_bf16 v[100:103], v[88:91], v[208:211], v[100:103]
	v_mfma_f32_16x16x32_bf16 v[96:99], v[152:155], v[208:211], v[96:99]
	s_barrier
	s_add_i32 s3, s3, s94
	v_lshl_add_u64 v[212:213], s[82:83], 0, v[192:193]
	s_mov_b32 m0, s3
	ds_read_b128 v[164:167], v240 offset:16384
	ds_read_b128 v[168:171], v240 offset:17408
	ds_read_b128 v[172:175], v240 offset:18432
	ds_read_b128 v[176:179], v240 offset:19456
	ds_read_b128 v[180:183], v240 offset:20480
	ds_read_b128 v[184:187], v240 offset:21504
	ds_read_b128 v[188:191], v240 offset:22528
	ds_read_b128 v[208:211], v240 offset:23552
	global_load_lds_dwordx4 v[212:213], off
	s_add_i32 m0, s3, 0x2000
	v_lshl_add_u64 v[214:215], s[82:83], 0, v[198:199]
	s_add_u32 s82, s82, s12
	s_addc_u32 s83, s83, 0
	s_add_i32 s3, s81, s94
	global_load_lds_dwordx4 v[214:215], off
	v_lshl_add_u64 v[216:217], s[82:83], 0, v[192:193]
	s_mov_b32 m0, s3
	v_lshl_add_u64 v[218:219], s[82:83], 0, v[198:199]
	global_load_lds_dwordx4 v[216:217], off
	s_add_i32 m0, s3, 0x2000
	v_lshl_add_u64 v[220:221], s[74:75], 0, v[202:203]
	global_load_lds_dwordx4 v[218:219], off
	s_mov_b32 m0, s97
	v_lshl_add_u64 v[224:225], s[74:75], 0, v[200:201]
	global_load_lds_dwordx4 v[220:221], off
	s_mov_b32 m0, s98
	s_nop 0
	global_load_lds_dwordx4 v[224:225], off
	s_waitcnt vmcnt(8)
	s_waitcnt lgkmcnt(0)
	s_barrier
	s_waitcnt lgkmcnt(0)
	v_mfma_f32_16x16x32_bf16 v[76:79], v[58:61], v[164:167], v[76:79]
	v_mfma_f32_16x16x32_bf16 v[70:73], v[66:69], v[164:167], v[72:75]
	v_mfma_f32_16x16x32_bf16 v[44:47], v[58:61], v[172:175], v[44:47]
	v_mfma_f32_16x16x32_bf16 v[40:43], v[66:69], v[172:175], v[40:43]
	v_mfma_f32_16x16x32_bf16 v[28:31], v[58:61], v[180:183], v[28:31]
	v_mfma_f32_16x16x32_bf16 v[24:27], v[66:69], v[180:183], v[24:27]
	v_mfma_f32_16x16x32_bf16 v[12:15], v[58:61], v[188:191], v[12:15]
	v_mfma_f32_16x16x32_bf16 v[8:11], v[66:69], v[188:191], v[8:11]
	v_mfma_f32_16x16x32_bf16 v[76:79], v[62:65], v[168:171], v[76:79]
	v_mfma_f32_16x16x32_bf16 v[70:73], v[80:83], v[168:171], v[70:73]
	v_mfma_f32_16x16x32_bf16 v[44:47], v[62:65], v[176:179], v[44:47]
	v_mfma_f32_16x16x32_bf16 v[40:43], v[80:83], v[176:179], v[40:43]
	v_mfma_f32_16x16x32_bf16 v[28:31], v[62:65], v[184:187], v[28:31]
	v_mfma_f32_16x16x32_bf16 v[24:27], v[80:83], v[184:187], v[24:27]
	v_mfma_f32_16x16x32_bf16 v[12:15], v[62:65], v[208:211], v[12:15]
	v_mfma_f32_16x16x32_bf16 v[8:11], v[80:83], v[208:211], v[8:11]
	v_mfma_f32_16x16x32_bf16 v[52:55], v[84:87], v[164:167], v[52:55]
	v_mfma_f32_16x16x32_bf16 v[48:51], v[92:95], v[164:167], v[48:51]
	v_mfma_f32_16x16x32_bf16 v[36:39], v[84:87], v[172:175], v[36:39]
	v_mfma_f32_16x16x32_bf16 v[32:35], v[92:95], v[172:175], v[32:35]
	v_mfma_f32_16x16x32_bf16 v[20:23], v[84:87], v[180:183], v[20:23]
	v_mfma_f32_16x16x32_bf16 v[16:19], v[92:95], v[180:183], v[16:19]
	v_mfma_f32_16x16x32_bf16 v[4:7], v[84:87], v[188:191], v[4:7]
	v_mfma_f32_16x16x32_bf16 v[0:3], v[92:95], v[188:191], v[0:3]
	v_mfma_f32_16x16x32_bf16 v[52:55], v[88:91], v[168:171], v[52:55]
	v_mfma_f32_16x16x32_bf16 v[48:51], v[152:155], v[168:171], v[48:51]
	v_mfma_f32_16x16x32_bf16 v[36:39], v[88:91], v[176:179], v[36:39]
	v_mfma_f32_16x16x32_bf16 v[32:35], v[152:155], v[176:179], v[32:35]
	v_mfma_f32_16x16x32_bf16 v[20:23], v[88:91], v[184:187], v[20:23]
	v_mfma_f32_16x16x32_bf16 v[16:19], v[152:155], v[184:187], v[16:19]
	v_mfma_f32_16x16x32_bf16 v[4:7], v[88:91], v[208:211], v[4:7]
	v_mfma_f32_16x16x32_bf16 v[0:3], v[152:155], v[208:211], v[0:3]
	s_barrier
; #define PG8_STAGE(bufoff, gbase, voff) do { _Pragma("unroll") for (int _i = 0; _i < 2; ++_i) \
;         __builtin_amdgcn_global_load_lds((const unsigned*)((const char*)(gbase) + (voff)[_i]), (LAS unsigned*)(lds + (bufoff) + ldsw + _i * 8192), 16, 0, 0); } while (0)
; #define PG8_LDA(dst, b, h) do { _Pragma("unroll") for (int m = 0; m < 4; ++m) _Pragma("unroll") for (int k = 0; k < 2; ++k) dst[m][k] = *(const LAS bf16x8*)(lds + PG8_SA(b, h) + aoff + m * 2048 + k * 1024); } while (0)
; #define PG8_LDB(dst, b, h) do { _Pragma("unroll") for (int n = 0; n < 2; ++n) _Pragma("unroll") for (int k = 0; k < 2; ++k) dst[n][k] = *(const LAS bf16x8*)(lds + PG8_SB(b, h) + boff + n * 2048 + k * 1024); } while (0)
; #define PG8_WAIT_V(n) asm volatile("s_waitcnt vmcnt(" #n ")" ::: "memory")
; #define PG8_BAR __builtin_amdgcn_s_barrier()
; template <class Epi, class Sched>
; __device__ __forceinline__ void gemm_phase(LAS unsigned char* lds, const Gemm g, const Sched& S, const Epi& E, const int tid) {
;     ...
;         for (int t = 0; t < nt; t += 2) {
;             const bool last = (t == nt - 2);
;             const char* a1 = cA + (size_t)(t + 1) * kstep;
;             const char* a2 = last ? nA : cA + (size_t)(t + 2) * kstep; const char* b2 = last ? nB : cB + (size_t)(t + 2) * kstep;
;             const char* a3 = a2 + kstep; const char* b3 = b2 + kstep;
;             PG8_LDB(B0, 0, 0); PG8_LDB(B1, 0, 1); PG8_SCHED; PG8_LDA(At, 0, 0); PG8_STAGE(PG8_SA(1, 1), a1 + hstep, voffA);
;             PG8_WAIT_V(8); PG8_WAIT_L(0); PG8_BAR; PG8_MMA(0, 0, At, B0); PG8_MMA(0, 1, At, B1); PG8_BAR; PG8_SCHED;
;             PG8_LDA(At, 0, 1); PG8_STAGE(PG8_SB(0, 0), b2, voffB); PG8_STAGE(PG8_SB(0, 1), b2 + hstep, voffB); PG8_STAGE(PG8_SA(0, 0), a2, voffA);
;             PG8_WAIT_V(8); PG8_WAIT_L(0); PG8_BAR; PG8_MMA(1, 0, At, B0); PG8_MMA(1, 1, At, B1); PG8_BAR; PG8_SCHED;
;             PG8_LDB(B0, 1, 0); PG8_LDB(B1, 1, 1); PG8_SCHED; PG8_LDA(At, 1, 0); PG8_STAGE(PG8_SA(0, 1), a2 + hstep, voffA);
;             PG8_WAIT_V(8); PG8_WAIT_L(0); PG8_BAR; PG8_MMA(0, 0, At, B0); PG8_MMA(0, 1, At, B1); PG8_BAR; PG8_SCHED;
;             PG8_LDA(At, 1, 1); PG8_STAGE(PG8_SB(1, 0), b3, voffB); PG8_STAGE(PG8_SB(1, 1), b3 + hstep, voffB); PG8_STAGE(PG8_SA(1, 0), a3, voffA);
;             PG8_WAIT_V(8); PG8_WAIT_L(0); PG8_BAR; PG8_MMA(1, 0, At, B0); PG8_MMA(1, 1, At, B1); PG8_BAR; PG8_SCHED;
;         }
	s_add_i32 s3, 0, 0x18000
	v_add_u32_e32 v74, s3, v232
	s_add_i32 s81, 0, 0x1c000
	ds_read_b128 v[58:61], v74
	ds_read_b128 v[62:65], v74 offset:1024
	ds_read_b128 v[66:69], v74 offset:2048
	ds_read_b128 v[80:83], v74 offset:3072
	v_add_u32_e32 v74, s81, v232
	ds_read_b128 v[84:87], v74
	ds_read_b128 v[88:91], v74 offset:1024
	ds_read_b128 v[92:95], v74 offset:2048
	ds_read_b128 v[152:155], v74 offset:3072
	s_add_u32 s74, s74, s12
	s_addc_u32 s75, s75, 0
	s_mov_b32 m0, s99
	v_lshl_add_u64 v[74:75], s[74:75], 0, v[202:203]
	ds_read_b128 v[164:167], v240 offset:32768
	ds_read_b128 v[168:171], v240 offset:33792
	ds_read_b128 v[172:175], v240 offset:34816
	ds_read_b128 v[176:179], v240 offset:35840
	ds_read_b128 v[180:183], v240 offset:36864
	ds_read_b128 v[184:187], v240 offset:37888
	ds_read_b128 v[188:191], v240 offset:38912
	ds_read_b128 v[208:211], v240 offset:39936
	global_load_lds_dwordx4 v[74:75], off
	v_lshl_add_u64 v[74:75], s[74:75], 0, v[200:201]
	s_mov_b32 m0, s78
	s_nop 0
	global_load_lds_dwordx4 v[74:75], off
	s_waitcnt vmcnt(8)
	s_waitcnt lgkmcnt(0)
	s_barrier
	s_waitcnt lgkmcnt(0)
	v_mfma_f32_16x16x32_bf16 v[160:163], v[58:61], v[164:167], v[160:163]
	v_mfma_f32_16x16x32_bf16 v[156:159], v[66:69], v[164:167], v[156:159]
	v_mfma_f32_16x16x32_bf16 v[140:143], v[58:61], v[172:175], v[140:143]
	v_mfma_f32_16x16x32_bf16 v[136:139], v[66:69], v[172:175], v[136:139]
	v_mfma_f32_16x16x32_bf16 v[124:127], v[58:61], v[180:183], v[124:127]
	v_mfma_f32_16x16x32_bf16 v[120:123], v[66:69], v[180:183], v[120:123]
	v_mfma_f32_16x16x32_bf16 v[108:111], v[58:61], v[188:191], v[108:111]
	v_mfma_f32_16x16x32_bf16 v[104:107], v[66:69], v[188:191], v[104:107]
	v_mfma_f32_16x16x32_bf16 v[160:163], v[62:65], v[168:171], v[160:163]
	v_mfma_f32_16x16x32_bf16 v[156:159], v[80:83], v[168:171], v[156:159]
	v_mfma_f32_16x16x32_bf16 v[140:143], v[62:65], v[176:179], v[140:143]
	v_mfma_f32_16x16x32_bf16 v[136:139], v[80:83], v[176:179], v[136:139]
	v_mfma_f32_16x16x32_bf16 v[124:127], v[62:65], v[184:187], v[124:127]
	v_mfma_f32_16x16x32_bf16 v[120:123], v[80:83], v[184:187], v[120:123]
	v_mfma_f32_16x16x32_bf16 v[108:111], v[62:65], v[208:211], v[108:111]
	v_mfma_f32_16x16x32_bf16 v[104:107], v[80:83], v[208:211], v[104:107]
	v_mfma_f32_16x16x32_bf16 v[148:151], v[84:87], v[164:167], v[148:151]
	v_mfma_f32_16x16x32_bf16 v[144:147], v[92:95], v[164:167], v[144:147]
	v_mfma_f32_16x16x32_bf16 v[132:135], v[84:87], v[172:175], v[132:135]
	v_mfma_f32_16x16x32_bf16 v[128:131], v[92:95], v[172:175], v[128:131]
	v_mfma_f32_16x16x32_bf16 v[116:119], v[84:87], v[180:183], v[116:119]
	v_mfma_f32_16x16x32_bf16 v[112:115], v[92:95], v[180:183], v[112:115]
	v_mfma_f32_16x16x32_bf16 v[100:103], v[84:87], v[188:191], v[100:103]
	v_mfma_f32_16x16x32_bf16 v[96:99], v[92:95], v[188:191], v[96:99]
	v_mfma_f32_16x16x32_bf16 v[148:151], v[88:91], v[168:171], v[148:151]
	v_mfma_f32_16x16x32_bf16 v[144:147], v[152:155], v[168:171], v[144:147]
	v_mfma_f32_16x16x32_bf16 v[132:135], v[88:91], v[176:179], v[132:135]
	v_mfma_f32_16x16x32_bf16 v[128:131], v[152:155], v[176:179], v[128:131]
	v_mfma_f32_16x16x32_bf16 v[116:119], v[88:91], v[184:187], v[116:119]
	v_mfma_f32_16x16x32_bf16 v[112:115], v[152:155], v[184:187], v[112:115]
	v_mfma_f32_16x16x32_bf16 v[100:103], v[88:91], v[208:211], v[100:103]
	v_mfma_f32_16x16x32_bf16 v[96:99], v[152:155], v[208:211], v[96:99]
	s_barrier
	s_add_i32 s3, s3, s94
	v_lshl_add_u64 v[74:75], v[212:213], 0, s[68:69]
	s_mov_b32 m0, s3
	ds_read_b128 v[164:167], v240 offset:49152
	ds_read_b128 v[168:171], v240 offset:50176
	ds_read_b128 v[172:175], v240 offset:51200
	ds_read_b128 v[176:179], v240 offset:52224
	ds_read_b128 v[180:183], v240 offset:53248
	ds_read_b128 v[184:187], v240 offset:54272
	ds_read_b128 v[188:191], v240 offset:55296
	ds_read_b128 v[208:211], v240 offset:56320
	global_load_lds_dwordx4 v[74:75], off
	v_lshl_add_u64 v[74:75], v[214:215], 0, s[68:69]
	s_add_i32 m0, s3, 0x2000
	s_add_i32 s3, s81, s94
	global_load_lds_dwordx4 v[74:75], off
	v_lshl_add_u64 v[74:75], v[216:217], 0, s[68:69]
	s_mov_b32 m0, s3
	s_nop 0
	global_load_lds_dwordx4 v[74:75], off
	v_lshl_add_u64 v[74:75], v[218:219], 0, s[68:69]
	s_add_i32 m0, s3, 0x2000
	s_nop 0
	global_load_lds_dwordx4 v[74:75], off
	v_lshl_add_u64 v[74:75], v[220:221], 0, s[68:69]
	s_mov_b32 m0, s53
	s_nop 0
	global_load_lds_dwordx4 v[74:75], off
	v_lshl_add_u64 v[74:75], v[224:225], 0, s[68:69]
	s_mov_b32 m0, s56
	s_nop 0
	global_load_lds_dwordx4 v[74:75], off
	s_waitcnt vmcnt(8)
	s_waitcnt lgkmcnt(0)
	s_barrier
	s_waitcnt lgkmcnt(0)
	v_mfma_f32_16x16x32_bf16 v[74:77], v[58:61], v[164:167], v[76:79]
	v_mfma_f32_16x16x32_bf16 v[70:73], v[66:69], v[164:167], v[70:73]
	v_mfma_f32_16x16x32_bf16 v[44:47], v[58:61], v[172:175], v[44:47]
	v_mfma_f32_16x16x32_bf16 v[40:43], v[66:69], v[172:175], v[40:43]
	v_mfma_f32_16x16x32_bf16 v[28:31], v[58:61], v[180:183], v[28:31]
	v_mfma_f32_16x16x32_bf16 v[24:27], v[66:69], v[180:183], v[24:27]
	v_mfma_f32_16x16x32_bf16 v[12:15], v[58:61], v[188:191], v[12:15]
	v_mfma_f32_16x16x32_bf16 v[8:11], v[66:69], v[188:191], v[8:11]
	v_mfma_f32_16x16x32_bf16 v[76:79], v[62:65], v[168:171], v[74:77]
	v_mfma_f32_16x16x32_bf16 v[72:75], v[80:83], v[168:171], v[70:73]
	v_mfma_f32_16x16x32_bf16 v[44:47], v[62:65], v[176:179], v[44:47]
	v_mfma_f32_16x16x32_bf16 v[40:43], v[80:83], v[176:179], v[40:43]
	v_mfma_f32_16x16x32_bf16 v[28:31], v[62:65], v[184:187], v[28:31]
	v_mfma_f32_16x16x32_bf16 v[24:27], v[80:83], v[184:187], v[24:27]
	v_mfma_f32_16x16x32_bf16 v[12:15], v[62:65], v[208:211], v[12:15]
	v_mfma_f32_16x16x32_bf16 v[8:11], v[80:83], v[208:211], v[8:11]
	v_mfma_f32_16x16x32_bf16 v[52:55], v[84:87], v[164:167], v[52:55]
	v_mfma_f32_16x16x32_bf16 v[48:51], v[92:95], v[164:167], v[48:51]
	v_mfma_f32_16x16x32_bf16 v[36:39], v[84:87], v[172:175], v[36:39]
	v_mfma_f32_16x16x32_bf16 v[32:35], v[92:95], v[172:175], v[32:35]
	v_mfma_f32_16x16x32_bf16 v[20:23], v[84:87], v[180:183], v[20:23]
	v_mfma_f32_16x16x32_bf16 v[16:19], v[92:95], v[180:183], v[16:19]
	v_mfma_f32_16x16x32_bf16 v[4:7], v[84:87], v[188:191], v[4:7]
	v_mfma_f32_16x16x32_bf16 v[0:3], v[92:95], v[188:191], v[0:3]
	v_mfma_f32_16x16x32_bf16 v[52:55], v[88:91], v[168:171], v[52:55]
	v_mfma_f32_16x16x32_bf16 v[48:51], v[152:155], v[168:171], v[48:51]
	v_mfma_f32_16x16x32_bf16 v[36:39], v[88:91], v[176:179], v[36:39]
	v_mfma_f32_16x16x32_bf16 v[32:35], v[152:155], v[176:179], v[32:35]
	v_mfma_f32_16x16x32_bf16 v[20:23], v[88:91], v[184:187], v[20:23]
	v_mfma_f32_16x16x32_bf16 v[16:19], v[152:155], v[184:187], v[16:19]
	v_mfma_f32_16x16x32_bf16 v[4:7], v[88:91], v[208:211], v[4:7]
	v_mfma_f32_16x16x32_bf16 v[0:3], v[152:155], v[208:211], v[0:3]
	s_barrier
	s_add_u32 vcc_lo, vcc_lo, 0x100
	s_addc_u32 vcc_hi, vcc_hi, 0
	s_add_u32 s61, s61, 0x100
	s_addc_u32 s67, s67, 0
	s_cmp_ge_u32 s80, s52
	s_mov_b32 s74, s80
	s_cbranch_scc0 .LBB0_567
	s_and_b64 vcc, exec, s[64:65]
	s_cbranch_vccz .LBB0_570
	s_barrier
